# MFMA order inside every 32-MFMA K-loop segment: activation fragment (srcB) held for 4 consecutive MFMAs (order k,m,half,n), the two weight halves interleaved; per-accumulator order unchanged
# baseline (speedup 1.0000x reference)
; #define PG8_STAGE(bufoff, gbase, voff) do { _Pragma("unroll") for (int _i = 0; _i < 2; ++_i) \
;         __builtin_amdgcn_global_load_lds((const unsigned*)((const char*)(gbase) + (voff)[_i]), (PG8_LAS unsigned*)(lds + (bufoff) + ldsw + _i * 8192), 16, 0, 0); } while (0)
; #define PG8_LDA(dst, b, h) do { _Pragma("unroll") for (int m = 0; m < 4; ++m) _Pragma("unroll") for (int k = 0; k < 2; ++k) dst[m][k] = *(const PG8_LAS bf16x8*)(lds + PG8_SA(b, h) + aoff + m * 2048 + k * 1024); } while (0)
; #define PG8_LDB(dst, b, h) do { _Pragma("unroll") for (int n = 0; n < 2; ++n) _Pragma("unroll") for (int k = 0; k < 2; ++k) dst[n][k] = *(const PG8_LAS bf16x8*)(lds + PG8_SB(b, h) + boff + n * 2048 + k * 1024); } while (0)
; #define PG8_MMA(ai, bj, At, Bt) do { __builtin_amdgcn_s_setprio(1); _Pragma("unroll") for (int m = 0; m < 4; ++m) _Pragma("unroll") for (int n = 0; n < 2; ++n) _Pragma("unroll") for (int k = 0; k < 2; ++k) \
;         acc[ai][bj][m][n] = __builtin_amdgcn_mfma_f32_16x16x32_bf16(Bt[n][k], At[m][k], acc[ai][bj][m][n], 0, 0, 0); __builtin_amdgcn_s_setprio(0); } while (0)
; #define PG8_WAIT_V(n) asm volatile("s_waitcnt vmcnt(" #n ")" ::: "memory")
; #define PG8_WAIT_L(n) asm volatile("s_waitcnt lgkmcnt(" #n ")" ::: "memory")
; template <class Epi, class Sched, bool ALIGN_EPI = false, bool SP2 = false>
; __device__ __forceinline__ void gemm_phase(PG8_LAS unsigned char* lds, const Gemm g, const Sched& S, const Epi& E) {
;     ...
;             const bool last = (t == nt - 2);
;             const char* a1 = cA + (size_t)(t + 1) * kstep;
;             const char* a2 = last ? nA : cA + (size_t)(t + 2) * kstep; const char* b2 = last ? nB : cB + (size_t)(t + 2) * kstep;
;             const char* a3 = a2 + kstep; const char* b3 = b2 + kstep;
;             if (last && has_next) S.a_ready(nxt);
;             if constexpr (SP2) {
;             PG8_LDB(B0, 0, 0); PG8_LDB(B1, 0, 1); PG8_SCHED; PG8_LDA(At, 0, 0); PG8_STAGE(PG8_SA(1, 1), a1 + hstep, voffA);
;             PG8_WAIT_V(8); PG8_WAIT_L(0); PG8_BAR; PG8_MMA(0, 0, At, B0); PG8_MMA(0, 1, At, B1); PG8_BAR; PG8_SCHED;
;             PG8_LDA(At, 0, 1); PG8_STAGE(PG8_SB(0, 0), b2, voffB); PG8_STAGE(PG8_SB(0, 1), b2 + hstep, voffB); PG8_STAGE(PG8_SA(0, 0), a2, voffA);
;             PG8_WAIT_V(8); PG8_WAIT_L(0); PG8_BAR; PG8_MMA(1, 0, At, B0); PG8_MMA(1, 1, At, B1); PG8_BAR; PG8_SCHED;
.Labo_peel:
	ds_read_b128 v[68:71], v254
	ds_read_b128 v[72:75], v254 offset:1024
	ds_read_b128 v[76:79], v254 offset:2048
	ds_read_b128 v[80:83], v254 offset:3072
	ds_read_b128 v[174:177], v254 offset:16384
	ds_read_b128 v[182:185], v254 offset:17408
	ds_read_b128 v[186:189], v254 offset:18432
	ds_read_b128 v[210:213], v254 offset:19456
	s_add_u32 s2, s0, 0xfffc0080
	s_addc_u32 s3, s1, -1
	s_cmp_eq_u32 s56, 12
	s_cselect_b32 s5, s27, s3
	s_cselect_b32 s4, s52, s2
	s_cselect_b32 s3, s25, s55
	s_cselect_b32 s2, s53, s54
	s_add_i32 m0, s29, 0xc000
	ds_read_b128 v[214:217], v179
	ds_read_b128 v[218:221], v179 offset:1024
	ds_read_b128 v[222:225], v179 offset:2048
	ds_read_b128 v[226:229], v179 offset:3072
	ds_read_b128 v[230:233], v179 offset:4096
	ds_read_b128 v[234:237], v179 offset:5120
	ds_read_b128 v[238:241], v179 offset:6144
	ds_read_b128 v[242:245], v179 offset:7168
	global_load_lds_dwordx4 v170, s[0:1]
	s_add_i32 m0, s29, 0xe000
	s_nop 0
	global_load_lds_dwordx4 v172, s[0:1]
	s_waitcnt vmcnt(8)
	s_waitcnt lgkmcnt(0)
	s_barrier
	s_setprio 1
	v_mfma_f32_16x16x32_bf16 v[140:143], v[68:71], v[214:217], 0
	v_mfma_f32_16x16x32_bf16 v[136:139], v[76:79], v[214:217], 0
	v_mfma_f32_16x16x32_bf16 v[132:135], v[174:177], v[214:217], 0
	v_mfma_f32_16x16x32_bf16 v[128:131], v[186:189], v[214:217], 0
	v_mfma_f32_16x16x32_bf16 v[124:127], v[68:71], v[222:225], 0
	v_mfma_f32_16x16x32_bf16 v[120:123], v[76:79], v[222:225], 0
	v_mfma_f32_16x16x32_bf16 v[116:119], v[174:177], v[222:225], 0
	v_mfma_f32_16x16x32_bf16 v[112:115], v[186:189], v[222:225], 0
	v_mfma_f32_16x16x32_bf16 v[108:111], v[68:71], v[230:233], 0
	v_mfma_f32_16x16x32_bf16 v[104:107], v[76:79], v[230:233], 0
	v_mfma_f32_16x16x32_bf16 v[100:103], v[174:177], v[230:233], 0
	v_mfma_f32_16x16x32_bf16 v[96:99], v[186:189], v[230:233], 0
	v_mfma_f32_16x16x32_bf16 v[92:95], v[68:71], v[238:241], 0
	v_mfma_f32_16x16x32_bf16 v[88:91], v[76:79], v[238:241], 0
	v_mfma_f32_16x16x32_bf16 v[84:87], v[174:177], v[238:241], 0
	v_mfma_f32_16x16x32_bf16 v[64:67], v[186:189], v[238:241], 0
	v_mfma_f32_16x16x32_bf16 v[140:143], v[72:75], v[218:221], v[140:143]
	v_mfma_f32_16x16x32_bf16 v[136:139], v[80:83], v[218:221], v[136:139]
	v_mfma_f32_16x16x32_bf16 v[132:135], v[182:185], v[218:221], v[132:135]
	v_mfma_f32_16x16x32_bf16 v[128:131], v[210:213], v[218:221], v[128:131]
	v_mfma_f32_16x16x32_bf16 v[124:127], v[72:75], v[226:229], v[124:127]
	v_mfma_f32_16x16x32_bf16 v[120:123], v[80:83], v[226:229], v[120:123]
	v_mfma_f32_16x16x32_bf16 v[116:119], v[182:185], v[226:229], v[116:119]
	v_mfma_f32_16x16x32_bf16 v[112:115], v[210:213], v[226:229], v[112:115]
	v_mfma_f32_16x16x32_bf16 v[108:111], v[72:75], v[234:237], v[108:111]
	v_mfma_f32_16x16x32_bf16 v[104:107], v[80:83], v[234:237], v[104:107]
	v_mfma_f32_16x16x32_bf16 v[100:103], v[182:185], v[234:237], v[100:103]
	v_mfma_f32_16x16x32_bf16 v[96:99], v[210:213], v[234:237], v[96:99]
	v_mfma_f32_16x16x32_bf16 v[92:95], v[72:75], v[242:245], v[92:95]
	v_mfma_f32_16x16x32_bf16 v[88:91], v[80:83], v[242:245], v[88:91]
	v_mfma_f32_16x16x32_bf16 v[84:87], v[182:185], v[242:245], v[84:87]
	v_mfma_f32_16x16x32_bf16 v[64:67], v[210:213], v[242:245], v[64:67]
	s_setprio 0
	s_barrier
	s_mov_b32 m0, s30
	s_add_u32 s58, s2, 0x40000
	s_addc_u32 s59, s3, 0
	ds_read_b128 v[214:217], v179 offset:16384
	ds_read_b128 v[218:221], v179 offset:17408
	ds_read_b128 v[222:225], v179 offset:18432
	ds_read_b128 v[226:229], v179 offset:19456
	ds_read_b128 v[230:233], v179 offset:20480
	ds_read_b128 v[234:237], v179 offset:21504
	ds_read_b128 v[238:241], v179 offset:22528
	ds_read_b128 v[242:245], v179 offset:23552
	global_load_lds_dwordx4 v166, s[2:3]
	s_mov_b32 m0, s31
	s_nop 0
	global_load_lds_dwordx4 v162, s[2:3]
	s_mov_b32 m0, s33
	s_nop 0
	global_load_lds_dwordx4 v166, s[58:59]
	s_mov_b32 m0, s34
	s_nop 0
	global_load_lds_dwordx4 v162, s[58:59]
	s_mov_b32 m0, s29
	s_nop 0
	global_load_lds_dwordx4 v168, s[4:5]
	s_mov_b32 m0, s35
	s_nop 0
	global_load_lds_dwordx4 v164, s[4:5]
	s_waitcnt vmcnt(8)
	s_waitcnt lgkmcnt(0)
	s_barrier
	s_setprio 1
	v_mfma_f32_16x16x32_bf16 v[60:63], v[68:71], v[214:217], 0
	v_mfma_f32_16x16x32_bf16 v[56:59], v[76:79], v[214:217], 0
	v_mfma_f32_16x16x32_bf16 v[52:55], v[174:177], v[214:217], 0
	v_mfma_f32_16x16x32_bf16 v[48:51], v[186:189], v[214:217], 0
	v_mfma_f32_16x16x32_bf16 v[44:47], v[68:71], v[222:225], 0
	v_mfma_f32_16x16x32_bf16 v[40:43], v[76:79], v[222:225], 0
	v_mfma_f32_16x16x32_bf16 v[36:39], v[174:177], v[222:225], 0
	v_mfma_f32_16x16x32_bf16 v[32:35], v[186:189], v[222:225], 0
	v_mfma_f32_16x16x32_bf16 v[28:31], v[68:71], v[230:233], 0
	v_mfma_f32_16x16x32_bf16 v[24:27], v[76:79], v[230:233], 0
	v_mfma_f32_16x16x32_bf16 v[20:23], v[174:177], v[230:233], 0
	v_mfma_f32_16x16x32_bf16 v[16:19], v[186:189], v[230:233], 0
	v_mfma_f32_16x16x32_bf16 v[12:15], v[68:71], v[238:241], 0
	v_mfma_f32_16x16x32_bf16 v[8:11], v[76:79], v[238:241], 0
	v_mfma_f32_16x16x32_bf16 v[4:7], v[174:177], v[238:241], 0
	v_mfma_f32_16x16x32_bf16 v[0:3], v[186:189], v[238:241], 0
	v_mfma_f32_16x16x32_bf16 v[60:63], v[72:75], v[218:221], v[60:63]
	v_mfma_f32_16x16x32_bf16 v[56:59], v[80:83], v[218:221], v[56:59]
	v_mfma_f32_16x16x32_bf16 v[52:55], v[182:185], v[218:221], v[52:55]
	v_mfma_f32_16x16x32_bf16 v[48:51], v[210:213], v[218:221], v[48:51]
	v_mfma_f32_16x16x32_bf16 v[44:47], v[72:75], v[226:229], v[44:47]
	v_mfma_f32_16x16x32_bf16 v[40:43], v[80:83], v[226:229], v[40:43]
	v_mfma_f32_16x16x32_bf16 v[36:39], v[182:185], v[226:229], v[36:39]
	v_mfma_f32_16x16x32_bf16 v[32:35], v[210:213], v[226:229], v[32:35]
	v_mfma_f32_16x16x32_bf16 v[28:31], v[72:75], v[234:237], v[28:31]
	v_mfma_f32_16x16x32_bf16 v[24:27], v[80:83], v[234:237], v[24:27]
	v_mfma_f32_16x16x32_bf16 v[20:23], v[182:185], v[234:237], v[20:23]
	v_mfma_f32_16x16x32_bf16 v[16:19], v[210:213], v[234:237], v[16:19]
	v_mfma_f32_16x16x32_bf16 v[12:15], v[72:75], v[242:245], v[12:15]
	v_mfma_f32_16x16x32_bf16 v[8:11], v[80:83], v[242:245], v[8:11]
	v_mfma_f32_16x16x32_bf16 v[4:7], v[182:185], v[242:245], v[4:7]
	v_mfma_f32_16x16x32_bf16 v[0:3], v[210:213], v[242:245], v[0:3]
	s_setprio 0
	s_barrier
; #define PG8_STAGE(bufoff, gbase, voff) do { _Pragma("unroll") for (int _i = 0; _i < 2; ++_i) \
;         __builtin_amdgcn_global_load_lds((const unsigned*)((const char*)(gbase) + (voff)[_i]), (PG8_LAS unsigned*)(lds + (bufoff) + ldsw + _i * 8192), 16, 0, 0); } while (0)
; #define PG8_LDA(dst, b, h) do { _Pragma("unroll") for (int m = 0; m < 4; ++m) _Pragma("unroll") for (int k = 0; k < 2; ++k) dst[m][k] = *(const PG8_LAS bf16x8*)(lds + PG8_SA(b, h) + aoff + m * 2048 + k * 1024); } while (0)
; #define PG8_LDB(dst, b, h) do { _Pragma("unroll") for (int n = 0; n < 2; ++n) _Pragma("unroll") for (int k = 0; k < 2; ++k) dst[n][k] = *(const PG8_LAS bf16x8*)(lds + PG8_SB(b, h) + boff + n * 2048 + k * 1024); } while (0)
; #define PG8_MMA(ai, bj, At, Bt) do { __builtin_amdgcn_s_setprio(1); _Pragma("unroll") for (int m = 0; m < 4; ++m) _Pragma("unroll") for (int n = 0; n < 2; ++n) _Pragma("unroll") for (int k = 0; k < 2; ++k) \
;         acc[ai][bj][m][n] = __builtin_amdgcn_mfma_f32_16x16x32_bf16(Bt[n][k], At[m][k], acc[ai][bj][m][n], 0, 0, 0); __builtin_amdgcn_s_setprio(0); } while (0)
; #define PG8_WAIT_V(n) asm volatile("s_waitcnt vmcnt(" #n ")" ::: "memory")
; #define PG8_WAIT_L(n) asm volatile("s_waitcnt lgkmcnt(" #n ")" ::: "memory")
; #define PG8_BAR __builtin_amdgcn_s_barrier()
; #define PG8_SCHED __builtin_amdgcn_sched_barrier(0)
; template <class Epi, class Sched, bool ALIGN_EPI = false, bool SP2 = false>
; __device__ __forceinline__ void gemm_phase(PG8_LAS unsigned char* lds, const Gemm g, const Sched& S, const Epi& E) {
;     ...
;             PG8_LDB(B0, 1, 0); PG8_LDB(B1, 1, 1); PG8_SCHED; PG8_LDA(At, 1, 0); PG8_STAGE(PG8_SA(0, 1), a2 + hstep, voffA);
;             PG8_WAIT_V(8); PG8_WAIT_L(0); PG8_BAR; PG8_MMA(0, 0, At, B0); PG8_MMA(0, 1, At, B1); PG8_BAR; PG8_SCHED;
;             PG8_LDA(At, 1, 1); PG8_STAGE(PG8_SB(1, 0), b3, voffB); PG8_STAGE(PG8_SB(1, 1), b3 + hstep, voffB); PG8_STAGE(PG8_SA(1, 0), a3, voffA);
;             PG8_WAIT_V(8); PG8_WAIT_L(0); PG8_BAR; PG8_MMA(1, 0, At, B0); PG8_MMA(1, 1, At, B1); PG8_BAR; PG8_SCHED;
	ds_read_b128 v[68:71], v254 offset:32768
	ds_read_b128 v[72:75], v254 offset:33792
	ds_read_b128 v[76:79], v254 offset:34816
	ds_read_b128 v[80:83], v254 offset:35840
	ds_read_b128 v[174:177], v254 offset:49152
	ds_read_b128 v[182:185], v254 offset:50176
	ds_read_b128 v[186:189], v254 offset:51200
	ds_read_b128 v[210:213], v254 offset:52224
	s_add_u32 s4, s4, 0x40000
	s_addc_u32 s5, s5, 0
	s_mov_b32 m0, s40
	ds_read_b128 v[214:217], v179 offset:32768
	ds_read_b128 v[218:221], v179 offset:33792
	ds_read_b128 v[222:225], v179 offset:34816
	ds_read_b128 v[226:229], v179 offset:35840
	ds_read_b128 v[230:233], v179 offset:36864
	ds_read_b128 v[234:237], v179 offset:37888
	ds_read_b128 v[238:241], v179 offset:38912
	ds_read_b128 v[242:245], v179 offset:39936
	global_load_lds_dwordx4 v168, s[4:5]
	s_mov_b32 m0, s41
	s_nop 0
	global_load_lds_dwordx4 v164, s[4:5]
	s_waitcnt vmcnt(8)
	s_waitcnt lgkmcnt(0)
	s_barrier
	s_setprio 1
	v_mfma_f32_16x16x32_bf16 v[140:143], v[68:71], v[214:217], v[140:143]
	v_mfma_f32_16x16x32_bf16 v[136:139], v[76:79], v[214:217], v[136:139]
	v_mfma_f32_16x16x32_bf16 v[132:135], v[174:177], v[214:217], v[132:135]
	v_mfma_f32_16x16x32_bf16 v[128:131], v[186:189], v[214:217], v[128:131]
	v_mfma_f32_16x16x32_bf16 v[124:127], v[68:71], v[222:225], v[124:127]
	v_mfma_f32_16x16x32_bf16 v[120:123], v[76:79], v[222:225], v[120:123]
	v_mfma_f32_16x16x32_bf16 v[116:119], v[174:177], v[222:225], v[116:119]
	v_mfma_f32_16x16x32_bf16 v[112:115], v[186:189], v[222:225], v[112:115]
	v_mfma_f32_16x16x32_bf16 v[108:111], v[68:71], v[230:233], v[108:111]
	v_mfma_f32_16x16x32_bf16 v[104:107], v[76:79], v[230:233], v[104:107]
	v_mfma_f32_16x16x32_bf16 v[100:103], v[174:177], v[230:233], v[100:103]
	v_mfma_f32_16x16x32_bf16 v[96:99], v[186:189], v[230:233], v[96:99]
	v_mfma_f32_16x16x32_bf16 v[92:95], v[68:71], v[238:241], v[92:95]
	v_mfma_f32_16x16x32_bf16 v[88:91], v[76:79], v[238:241], v[88:91]
	v_mfma_f32_16x16x32_bf16 v[84:87], v[174:177], v[238:241], v[84:87]
	v_mfma_f32_16x16x32_bf16 v[64:67], v[186:189], v[238:241], v[64:67]
	v_mfma_f32_16x16x32_bf16 v[140:143], v[72:75], v[218:221], v[140:143]
	v_mfma_f32_16x16x32_bf16 v[136:139], v[80:83], v[218:221], v[136:139]
	v_mfma_f32_16x16x32_bf16 v[132:135], v[182:185], v[218:221], v[132:135]
	v_mfma_f32_16x16x32_bf16 v[128:131], v[210:213], v[218:221], v[128:131]
	v_mfma_f32_16x16x32_bf16 v[124:127], v[72:75], v[226:229], v[124:127]
	v_mfma_f32_16x16x32_bf16 v[120:123], v[80:83], v[226:229], v[120:123]
	v_mfma_f32_16x16x32_bf16 v[116:119], v[182:185], v[226:229], v[116:119]
	v_mfma_f32_16x16x32_bf16 v[112:115], v[210:213], v[226:229], v[112:115]
	v_mfma_f32_16x16x32_bf16 v[108:111], v[72:75], v[234:237], v[108:111]
	v_mfma_f32_16x16x32_bf16 v[104:107], v[80:83], v[234:237], v[104:107]
	v_mfma_f32_16x16x32_bf16 v[100:103], v[182:185], v[234:237], v[100:103]
	v_mfma_f32_16x16x32_bf16 v[96:99], v[210:213], v[234:237], v[96:99]
	v_mfma_f32_16x16x32_bf16 v[92:95], v[72:75], v[242:245], v[92:95]
	v_mfma_f32_16x16x32_bf16 v[88:91], v[80:83], v[242:245], v[88:91]
	v_mfma_f32_16x16x32_bf16 v[84:87], v[182:185], v[242:245], v[84:87]
	v_mfma_f32_16x16x32_bf16 v[64:67], v[210:213], v[242:245], v[64:67]
	s_setprio 0
	s_barrier
	s_mov_b32 m0, s45
	s_add_u32 s2, s2, 0x40080
	s_addc_u32 s3, s3, 0
	ds_read_b128 v[214:217], v179 offset:49152
	ds_read_b128 v[218:221], v179 offset:50176
	ds_read_b128 v[222:225], v179 offset:51200
	ds_read_b128 v[226:229], v179 offset:52224
	ds_read_b128 v[230:233], v179 offset:53248
	ds_read_b128 v[234:237], v179 offset:54272
	ds_read_b128 v[238:241], v179 offset:55296
	ds_read_b128 v[242:245], v179 offset:56320
	s_add_u32 s98, s2, 0xfffc0000
	s_addc_u32 s99, s3, -1
	global_load_lds_dwordx4 v166, s[98:99]
	s_mov_b32 m0, s46
	s_nop 0
	global_load_lds_dwordx4 v162, s[98:99]
	s_mov_b32 m0, s49
	s_nop 0
	global_load_lds_dwordx4 v166, s[2:3]
	s_mov_b32 m0, s50
	s_nop 0
	global_load_lds_dwordx4 v162, s[2:3]
	s_mov_b32 m0, s47
	s_nop 0
	s_add_u32 s100, s4, 0xfffc0080
	s_addc_u32 s101, s5, -1
	global_load_lds_dwordx4 v168, s[100:101]
	s_mov_b32 m0, s48
	s_nop 0
	global_load_lds_dwordx4 v164, s[100:101]
	s_waitcnt vmcnt(8)
	s_waitcnt lgkmcnt(0)
	s_barrier
	s_setprio 1
	v_mfma_f32_16x16x32_bf16 v[60:63], v[68:71], v[214:217], v[60:63]
	v_mfma_f32_16x16x32_bf16 v[56:59], v[76:79], v[214:217], v[56:59]
	v_mfma_f32_16x16x32_bf16 v[52:55], v[174:177], v[214:217], v[52:55]
	v_mfma_f32_16x16x32_bf16 v[48:51], v[186:189], v[214:217], v[48:51]
	v_mfma_f32_16x16x32_bf16 v[44:47], v[68:71], v[222:225], v[44:47]
	v_mfma_f32_16x16x32_bf16 v[40:43], v[76:79], v[222:225], v[40:43]
	v_mfma_f32_16x16x32_bf16 v[36:39], v[174:177], v[222:225], v[36:39]
	v_mfma_f32_16x16x32_bf16 v[32:35], v[186:189], v[222:225], v[32:35]
	v_mfma_f32_16x16x32_bf16 v[28:31], v[68:71], v[230:233], v[28:31]
	v_mfma_f32_16x16x32_bf16 v[24:27], v[76:79], v[230:233], v[24:27]
	v_mfma_f32_16x16x32_bf16 v[20:23], v[174:177], v[230:233], v[20:23]
	v_mfma_f32_16x16x32_bf16 v[16:19], v[186:189], v[230:233], v[16:19]
	v_mfma_f32_16x16x32_bf16 v[12:15], v[68:71], v[238:241], v[12:15]
	v_mfma_f32_16x16x32_bf16 v[8:11], v[76:79], v[238:241], v[8:11]
	v_mfma_f32_16x16x32_bf16 v[4:7], v[174:177], v[238:241], v[4:7]
	v_mfma_f32_16x16x32_bf16 v[0:3], v[186:189], v[238:241], v[0:3]
	v_mfma_f32_16x16x32_bf16 v[60:63], v[72:75], v[218:221], v[60:63]
	v_mfma_f32_16x16x32_bf16 v[56:59], v[80:83], v[218:221], v[56:59]
	v_mfma_f32_16x16x32_bf16 v[52:55], v[182:185], v[218:221], v[52:55]
	v_mfma_f32_16x16x32_bf16 v[48:51], v[210:213], v[218:221], v[48:51]
	v_mfma_f32_16x16x32_bf16 v[44:47], v[72:75], v[226:229], v[44:47]
	v_mfma_f32_16x16x32_bf16 v[40:43], v[80:83], v[226:229], v[40:43]
	v_mfma_f32_16x16x32_bf16 v[36:39], v[182:185], v[226:229], v[36:39]
	v_mfma_f32_16x16x32_bf16 v[32:35], v[210:213], v[226:229], v[32:35]
	v_mfma_f32_16x16x32_bf16 v[28:31], v[72:75], v[234:237], v[28:31]
	v_mfma_f32_16x16x32_bf16 v[24:27], v[80:83], v[234:237], v[24:27]
	v_mfma_f32_16x16x32_bf16 v[20:23], v[182:185], v[234:237], v[20:23]
	v_mfma_f32_16x16x32_bf16 v[16:19], v[210:213], v[234:237], v[16:19]
	v_mfma_f32_16x16x32_bf16 v[12:15], v[72:75], v[242:245], v[12:15]
	v_mfma_f32_16x16x32_bf16 v[8:11], v[80:83], v[242:245], v[8:11]
	v_mfma_f32_16x16x32_bf16 v[4:7], v[182:185], v[242:245], v[4:7]
	v_mfma_f32_16x16x32_bf16 v[0:3], v[210:213], v[242:245], v[0:3]
	s_setprio 0
	s_barrier
	s_add_i32 s56, s56, 2
	s_add_u32 s0, s0, 0x100
	s_addc_u32 s1, s1, 0
	s_add_u32 s54, s54, 0x100
	s_addc_u32 s55, s55, 0
	s_cmp_gt_u32 s56, 13
; #define PG8_STAGE(bufoff, gbase, voff) do { _Pragma("unroll") for (int _i = 0; _i < 2; ++_i) \
;         __builtin_amdgcn_global_load_lds((const unsigned*)((const char*)(gbase) + (voff)[_i]), (PG8_LAS unsigned*)(lds + (bufoff) + ldsw + _i * 8192), 16, 0, 0); } while (0)
; #define PG8_LDA(dst, b, h) do { _Pragma("unroll") for (int m = 0; m < 4; ++m) _Pragma("unroll") for (int k = 0; k < 2; ++k) dst[m][k] = *(const PG8_LAS bf16x8*)(lds + PG8_SA(b, h) + aoff + m * 2048 + k * 1024); } while (0)
; #define PG8_LDB(dst, b, h) do { _Pragma("unroll") for (int n = 0; n < 2; ++n) _Pragma("unroll") for (int k = 0; k < 2; ++k) dst[n][k] = *(const PG8_LAS bf16x8*)(lds + PG8_SB(b, h) + boff + n * 2048 + k * 1024); } while (0)
; #define PG8_MMA(ai, bj, At, Bt) do { __builtin_amdgcn_s_setprio(1); _Pragma("unroll") for (int m = 0; m < 4; ++m) _Pragma("unroll") for (int n = 0; n < 2; ++n) _Pragma("unroll") for (int k = 0; k < 2; ++k) \
;         acc[ai][bj][m][n] = __builtin_amdgcn_mfma_f32_16x16x32_bf16(Bt[n][k], At[m][k], acc[ai][bj][m][n], 0, 0, 0); __builtin_amdgcn_s_setprio(0); } while (0)
; #define PG8_WAIT_V(n) asm volatile("s_waitcnt vmcnt(" #n ")" ::: "memory")
; #define PG8_BAR __builtin_amdgcn_s_barrier()
; template <class Epi, class Sched, bool ALIGN_EPI = false, bool SP2 = false>
; __device__ __forceinline__ void gemm_phase(PG8_LAS unsigned char* lds, const Gemm g, const Sched& S, const Epi& E) {
;     ...
;         for (int t = 0; t < nt; t += 2) {
;             const bool last = (t == nt - 2);
;             const char* a1 = cA + (size_t)(t + 1) * kstep;
;             const char* a2 = last ? nA : cA + (size_t)(t + 2) * kstep; const char* b2 = last ? nB : cB + (size_t)(t + 2) * kstep;
;             const char* a3 = a2 + kstep; const char* b3 = b2 + kstep;
;             if (last && has_next) S.a_ready(nxt);
;             if constexpr (SP2) {
;             PG8_LDB(B0, 0, 0); PG8_LDB(B1, 0, 1); PG8_SCHED; PG8_LDA(At, 0, 0); PG8_STAGE(PG8_SA(1, 1), a1 + hstep, voffA);
;             PG8_WAIT_V(8); PG8_WAIT_L(0); PG8_BAR; PG8_MMA(0, 0, At, B0); PG8_MMA(0, 1, At, B1); PG8_BAR; PG8_SCHED;
;             PG8_LDA(At, 0, 1); PG8_STAGE(PG8_SB(0, 0), b2, voffB); PG8_STAGE(PG8_SB(0, 1), b2 + hstep, voffB); PG8_STAGE(PG8_SA(0, 0), a2, voffA);
;             PG8_WAIT_V(8); PG8_WAIT_L(0); PG8_BAR; PG8_MMA(1, 0, At, B0); PG8_MMA(1, 1, At, B1); PG8_BAR; PG8_SCHED;
.LBB0_327:
	ds_read_b128 v[68:71], v254
	ds_read_b128 v[72:75], v254 offset:1024
	ds_read_b128 v[76:79], v254 offset:2048
	ds_read_b128 v[80:83], v254 offset:3072
	ds_read_b128 v[174:177], v254 offset:16384
	ds_read_b128 v[182:185], v254 offset:17408
	ds_read_b128 v[186:189], v254 offset:18432
	ds_read_b128 v[210:213], v254 offset:19456
	s_add_u32 s2, s0, 0xfffc0080
	s_addc_u32 s3, s1, -1
	s_cmp_eq_u32 s56, 12
	s_cselect_b32 s5, s27, s3
	s_cselect_b32 s4, s52, s2
	s_cselect_b32 s3, s25, s55
	s_cselect_b32 s2, s53, s54
	s_add_i32 m0, s29, 0xc000
	ds_read_b128 v[214:217], v179
	ds_read_b128 v[218:221], v179 offset:1024
	ds_read_b128 v[222:225], v179 offset:2048
	ds_read_b128 v[226:229], v179 offset:3072
	ds_read_b128 v[230:233], v179 offset:4096
	ds_read_b128 v[234:237], v179 offset:5120
	ds_read_b128 v[238:241], v179 offset:6144
	ds_read_b128 v[242:245], v179 offset:7168
	global_load_lds_dwordx4 v170, s[0:1]
	s_add_i32 m0, s29, 0xe000
	s_nop 0
	global_load_lds_dwordx4 v172, s[0:1]
	s_waitcnt vmcnt(8)
	s_waitcnt lgkmcnt(0)
	s_barrier
	s_setprio 1
	v_mfma_f32_16x16x32_bf16 v[140:143], v[68:71], v[214:217], v[140:143]
	v_mfma_f32_16x16x32_bf16 v[136:139], v[76:79], v[214:217], v[136:139]
	v_mfma_f32_16x16x32_bf16 v[132:135], v[174:177], v[214:217], v[132:135]
	v_mfma_f32_16x16x32_bf16 v[128:131], v[186:189], v[214:217], v[128:131]
	v_mfma_f32_16x16x32_bf16 v[124:127], v[68:71], v[222:225], v[124:127]
	v_mfma_f32_16x16x32_bf16 v[120:123], v[76:79], v[222:225], v[120:123]
	v_mfma_f32_16x16x32_bf16 v[116:119], v[174:177], v[222:225], v[116:119]
	v_mfma_f32_16x16x32_bf16 v[112:115], v[186:189], v[222:225], v[112:115]
	v_mfma_f32_16x16x32_bf16 v[108:111], v[68:71], v[230:233], v[108:111]
	v_mfma_f32_16x16x32_bf16 v[104:107], v[76:79], v[230:233], v[104:107]
	v_mfma_f32_16x16x32_bf16 v[100:103], v[174:177], v[230:233], v[100:103]
	v_mfma_f32_16x16x32_bf16 v[96:99], v[186:189], v[230:233], v[96:99]
	v_mfma_f32_16x16x32_bf16 v[92:95], v[68:71], v[238:241], v[92:95]
	v_mfma_f32_16x16x32_bf16 v[88:91], v[76:79], v[238:241], v[88:91]
	v_mfma_f32_16x16x32_bf16 v[84:87], v[174:177], v[238:241], v[84:87]
	v_mfma_f32_16x16x32_bf16 v[64:67], v[186:189], v[238:241], v[64:67]
	v_mfma_f32_16x16x32_bf16 v[140:143], v[72:75], v[218:221], v[140:143]
	v_mfma_f32_16x16x32_bf16 v[136:139], v[80:83], v[218:221], v[136:139]
	v_mfma_f32_16x16x32_bf16 v[132:135], v[182:185], v[218:221], v[132:135]
	v_mfma_f32_16x16x32_bf16 v[128:131], v[210:213], v[218:221], v[128:131]
	v_mfma_f32_16x16x32_bf16 v[124:127], v[72:75], v[226:229], v[124:127]
	v_mfma_f32_16x16x32_bf16 v[120:123], v[80:83], v[226:229], v[120:123]
	v_mfma_f32_16x16x32_bf16 v[116:119], v[182:185], v[226:229], v[116:119]
	v_mfma_f32_16x16x32_bf16 v[112:115], v[210:213], v[226:229], v[112:115]
	v_mfma_f32_16x16x32_bf16 v[108:111], v[72:75], v[234:237], v[108:111]
	v_mfma_f32_16x16x32_bf16 v[104:107], v[80:83], v[234:237], v[104:107]
	v_mfma_f32_16x16x32_bf16 v[100:103], v[182:185], v[234:237], v[100:103]
	v_mfma_f32_16x16x32_bf16 v[96:99], v[210:213], v[234:237], v[96:99]
	v_mfma_f32_16x16x32_bf16 v[92:95], v[72:75], v[242:245], v[92:95]
	v_mfma_f32_16x16x32_bf16 v[88:91], v[80:83], v[242:245], v[88:91]
	v_mfma_f32_16x16x32_bf16 v[84:87], v[182:185], v[242:245], v[84:87]
	v_mfma_f32_16x16x32_bf16 v[64:67], v[210:213], v[242:245], v[64:67]
	s_setprio 0
	s_barrier
	s_mov_b32 m0, s30
	s_add_u32 s58, s2, 0x40000
	s_addc_u32 s59, s3, 0
	ds_read_b128 v[214:217], v179 offset:16384
	ds_read_b128 v[218:221], v179 offset:17408
	ds_read_b128 v[222:225], v179 offset:18432
	ds_read_b128 v[226:229], v179 offset:19456
	ds_read_b128 v[230:233], v179 offset:20480
	ds_read_b128 v[234:237], v179 offset:21504
	ds_read_b128 v[238:241], v179 offset:22528
	ds_read_b128 v[242:245], v179 offset:23552
	global_load_lds_dwordx4 v166, s[2:3]
	s_mov_b32 m0, s31
	s_nop 0
	global_load_lds_dwordx4 v162, s[2:3]
	s_mov_b32 m0, s33
	s_nop 0
	global_load_lds_dwordx4 v166, s[58:59]
	s_mov_b32 m0, s34
	s_nop 0
	global_load_lds_dwordx4 v162, s[58:59]
	s_mov_b32 m0, s29
	s_nop 0
	global_load_lds_dwordx4 v168, s[4:5]
	s_mov_b32 m0, s35
	s_nop 0
	global_load_lds_dwordx4 v164, s[4:5]
	s_waitcnt vmcnt(8)
	s_waitcnt lgkmcnt(0)
	s_barrier
	s_setprio 1
	v_mfma_f32_16x16x32_bf16 v[60:63], v[68:71], v[214:217], v[60:63]
	v_mfma_f32_16x16x32_bf16 v[56:59], v[76:79], v[214:217], v[56:59]
	v_mfma_f32_16x16x32_bf16 v[52:55], v[174:177], v[214:217], v[52:55]
	v_mfma_f32_16x16x32_bf16 v[48:51], v[186:189], v[214:217], v[48:51]
	v_mfma_f32_16x16x32_bf16 v[44:47], v[68:71], v[222:225], v[44:47]
	v_mfma_f32_16x16x32_bf16 v[40:43], v[76:79], v[222:225], v[40:43]
	v_mfma_f32_16x16x32_bf16 v[36:39], v[174:177], v[222:225], v[36:39]
	v_mfma_f32_16x16x32_bf16 v[32:35], v[186:189], v[222:225], v[32:35]
	v_mfma_f32_16x16x32_bf16 v[28:31], v[68:71], v[230:233], v[28:31]
	v_mfma_f32_16x16x32_bf16 v[24:27], v[76:79], v[230:233], v[24:27]
	v_mfma_f32_16x16x32_bf16 v[20:23], v[174:177], v[230:233], v[20:23]
	v_mfma_f32_16x16x32_bf16 v[16:19], v[186:189], v[230:233], v[16:19]
	v_mfma_f32_16x16x32_bf16 v[12:15], v[68:71], v[238:241], v[12:15]
	v_mfma_f32_16x16x32_bf16 v[8:11], v[76:79], v[238:241], v[8:11]
	v_mfma_f32_16x16x32_bf16 v[4:7], v[174:177], v[238:241], v[4:7]
	v_mfma_f32_16x16x32_bf16 v[0:3], v[186:189], v[238:241], v[0:3]
	v_mfma_f32_16x16x32_bf16 v[60:63], v[72:75], v[218:221], v[60:63]
	v_mfma_f32_16x16x32_bf16 v[56:59], v[80:83], v[218:221], v[56:59]
	v_mfma_f32_16x16x32_bf16 v[52:55], v[182:185], v[218:221], v[52:55]
	v_mfma_f32_16x16x32_bf16 v[48:51], v[210:213], v[218:221], v[48:51]
	v_mfma_f32_16x16x32_bf16 v[44:47], v[72:75], v[226:229], v[44:47]
	v_mfma_f32_16x16x32_bf16 v[40:43], v[80:83], v[226:229], v[40:43]
	v_mfma_f32_16x16x32_bf16 v[36:39], v[182:185], v[226:229], v[36:39]
	v_mfma_f32_16x16x32_bf16 v[32:35], v[210:213], v[226:229], v[32:35]
	v_mfma_f32_16x16x32_bf16 v[28:31], v[72:75], v[234:237], v[28:31]
	v_mfma_f32_16x16x32_bf16 v[24:27], v[80:83], v[234:237], v[24:27]
	v_mfma_f32_16x16x32_bf16 v[20:23], v[182:185], v[234:237], v[20:23]
	v_mfma_f32_16x16x32_bf16 v[16:19], v[210:213], v[234:237], v[16:19]
	v_mfma_f32_16x16x32_bf16 v[12:15], v[72:75], v[242:245], v[12:15]
	v_mfma_f32_16x16x32_bf16 v[8:11], v[80:83], v[242:245], v[8:11]
	v_mfma_f32_16x16x32_bf16 v[4:7], v[182:185], v[242:245], v[4:7]
	v_mfma_f32_16x16x32_bf16 v[0:3], v[210:213], v[242:245], v[0:3]
	s_setprio 0
	s_barrier
; #define PG8_STAGE(bufoff, gbase, voff) do { _Pragma("unroll") for (int _i = 0; _i < 2; ++_i) \
;         __builtin_amdgcn_global_load_lds((const unsigned*)((const char*)(gbase) + (voff)[_i]), (PG8_LAS unsigned*)(lds + (bufoff) + ldsw + _i * 8192), 16, 0, 0); } while (0)
; #define PG8_LDA(dst, b, h) do { _Pragma("unroll") for (int m = 0; m < 4; ++m) _Pragma("unroll") for (int k = 0; k < 2; ++k) dst[m][k] = *(const PG8_LAS bf16x8*)(lds + PG8_SA(b, h) + aoff + m * 2048 + k * 1024); } while (0)
; #define PG8_LDB(dst, b, h) do { _Pragma("unroll") for (int n = 0; n < 2; ++n) _Pragma("unroll") for (int k = 0; k < 2; ++k) dst[n][k] = *(const PG8_LAS bf16x8*)(lds + PG8_SB(b, h) + boff + n * 2048 + k * 1024); } while (0)
; #define PG8_MMA(ai, bj, At, Bt) do { __builtin_amdgcn_s_setprio(1); _Pragma("unroll") for (int m = 0; m < 4; ++m) _Pragma("unroll") for (int n = 0; n < 2; ++n) _Pragma("unroll") for (int k = 0; k < 2; ++k) \
;         acc[ai][bj][m][n] = __builtin_amdgcn_mfma_f32_16x16x32_bf16(Bt[n][k], At[m][k], acc[ai][bj][m][n], 0, 0, 0); __builtin_amdgcn_s_setprio(0); } while (0)
; #define PG8_WAIT_V(n) asm volatile("s_waitcnt vmcnt(" #n ")" ::: "memory")
; #define PG8_WAIT_L(n) asm volatile("s_waitcnt lgkmcnt(" #n ")" ::: "memory")
; #define PG8_BAR __builtin_amdgcn_s_barrier()
; template <class Epi, class Sched, bool ALIGN_EPI = false, bool SP2 = false>
; __device__ __forceinline__ void gemm_phase(PG8_LAS unsigned char* lds, const Gemm g, const Sched& S, const Epi& E) {
;     ...
;         for (int t = 0; t < nt; t += 2) {
;             const bool last = (t == nt - 2);
;             const char* a1 = cA + (size_t)(t + 1) * kstep;
;             const char* a2 = last ? nA : cA + (size_t)(t + 2) * kstep; const char* b2 = last ? nB : cB + (size_t)(t + 2) * kstep;
;             const char* a3 = a2 + kstep; const char* b3 = b2 + kstep;
;     ...
;             PG8_LDB(B0, 1, 0); PG8_LDB(B1, 1, 1); PG8_SCHED; PG8_LDA(At, 1, 0); PG8_STAGE(PG8_SA(0, 1), a2 + hstep, voffA);
;             PG8_WAIT_V(8); PG8_WAIT_L(0); PG8_BAR; PG8_MMA(0, 0, At, B0); PG8_MMA(0, 1, At, B1); PG8_BAR; PG8_SCHED;
;             PG8_LDA(At, 1, 1); PG8_STAGE(PG8_SB(1, 0), b3, voffB); PG8_STAGE(PG8_SB(1, 1), b3 + hstep, voffB); PG8_STAGE(PG8_SA(1, 0), a3, voffA);
;             PG8_WAIT_V(8); PG8_WAIT_L(0); PG8_BAR; PG8_MMA(1, 0, At, B0); PG8_MMA(1, 1, At, B1); PG8_BAR; PG8_SCHED;
	ds_read_b128 v[68:71], v254 offset:32768
	ds_read_b128 v[72:75], v254 offset:33792
	ds_read_b128 v[76:79], v254 offset:34816
	ds_read_b128 v[80:83], v254 offset:35840
	ds_read_b128 v[174:177], v254 offset:49152
	ds_read_b128 v[182:185], v254 offset:50176
	ds_read_b128 v[186:189], v254 offset:51200
	ds_read_b128 v[210:213], v254 offset:52224
	s_add_u32 s4, s4, 0x40000
	s_addc_u32 s5, s5, 0
	s_mov_b32 m0, s40
	ds_read_b128 v[214:217], v179 offset:32768
	ds_read_b128 v[218:221], v179 offset:33792
	ds_read_b128 v[222:225], v179 offset:34816
	ds_read_b128 v[226:229], v179 offset:35840
	ds_read_b128 v[230:233], v179 offset:36864
	ds_read_b128 v[234:237], v179 offset:37888
	ds_read_b128 v[238:241], v179 offset:38912
	ds_read_b128 v[242:245], v179 offset:39936
	global_load_lds_dwordx4 v168, s[4:5]
	s_mov_b32 m0, s41
	s_nop 0
	global_load_lds_dwordx4 v164, s[4:5]
	s_waitcnt vmcnt(8)
	s_waitcnt lgkmcnt(0)
	s_barrier
	s_setprio 1
	v_mfma_f32_16x16x32_bf16 v[140:143], v[68:71], v[214:217], v[140:143]
	v_mfma_f32_16x16x32_bf16 v[136:139], v[76:79], v[214:217], v[136:139]
	v_mfma_f32_16x16x32_bf16 v[132:135], v[174:177], v[214:217], v[132:135]
	v_mfma_f32_16x16x32_bf16 v[128:131], v[186:189], v[214:217], v[128:131]
	v_mfma_f32_16x16x32_bf16 v[124:127], v[68:71], v[222:225], v[124:127]
	v_mfma_f32_16x16x32_bf16 v[120:123], v[76:79], v[222:225], v[120:123]
	v_mfma_f32_16x16x32_bf16 v[116:119], v[174:177], v[222:225], v[116:119]
	v_mfma_f32_16x16x32_bf16 v[112:115], v[186:189], v[222:225], v[112:115]
	v_mfma_f32_16x16x32_bf16 v[108:111], v[68:71], v[230:233], v[108:111]
	v_mfma_f32_16x16x32_bf16 v[104:107], v[76:79], v[230:233], v[104:107]
	v_mfma_f32_16x16x32_bf16 v[100:103], v[174:177], v[230:233], v[100:103]
	v_mfma_f32_16x16x32_bf16 v[96:99], v[186:189], v[230:233], v[96:99]
	v_mfma_f32_16x16x32_bf16 v[92:95], v[68:71], v[238:241], v[92:95]
	v_mfma_f32_16x16x32_bf16 v[88:91], v[76:79], v[238:241], v[88:91]
	v_mfma_f32_16x16x32_bf16 v[84:87], v[174:177], v[238:241], v[84:87]
	v_mfma_f32_16x16x32_bf16 v[64:67], v[186:189], v[238:241], v[64:67]
	v_mfma_f32_16x16x32_bf16 v[140:143], v[72:75], v[218:221], v[140:143]
	v_mfma_f32_16x16x32_bf16 v[136:139], v[80:83], v[218:221], v[136:139]
	v_mfma_f32_16x16x32_bf16 v[132:135], v[182:185], v[218:221], v[132:135]
	v_mfma_f32_16x16x32_bf16 v[128:131], v[210:213], v[218:221], v[128:131]
	v_mfma_f32_16x16x32_bf16 v[124:127], v[72:75], v[226:229], v[124:127]
	v_mfma_f32_16x16x32_bf16 v[120:123], v[80:83], v[226:229], v[120:123]
	v_mfma_f32_16x16x32_bf16 v[116:119], v[182:185], v[226:229], v[116:119]
	v_mfma_f32_16x16x32_bf16 v[112:115], v[210:213], v[226:229], v[112:115]
	v_mfma_f32_16x16x32_bf16 v[108:111], v[72:75], v[234:237], v[108:111]
	v_mfma_f32_16x16x32_bf16 v[104:107], v[80:83], v[234:237], v[104:107]
	v_mfma_f32_16x16x32_bf16 v[100:103], v[182:185], v[234:237], v[100:103]
	v_mfma_f32_16x16x32_bf16 v[96:99], v[210:213], v[234:237], v[96:99]
	v_mfma_f32_16x16x32_bf16 v[92:95], v[72:75], v[242:245], v[92:95]
	v_mfma_f32_16x16x32_bf16 v[88:91], v[80:83], v[242:245], v[88:91]
	v_mfma_f32_16x16x32_bf16 v[84:87], v[182:185], v[242:245], v[84:87]
	v_mfma_f32_16x16x32_bf16 v[64:67], v[210:213], v[242:245], v[64:67]
	s_setprio 0
	s_barrier
	s_mov_b32 m0, s45
	s_add_u32 s2, s2, 0x40080
	s_addc_u32 s3, s3, 0
	ds_read_b128 v[214:217], v179 offset:49152
	ds_read_b128 v[218:221], v179 offset:50176
	ds_read_b128 v[222:225], v179 offset:51200
	ds_read_b128 v[226:229], v179 offset:52224
	ds_read_b128 v[230:233], v179 offset:53248
	ds_read_b128 v[234:237], v179 offset:54272
	ds_read_b128 v[238:241], v179 offset:55296
	ds_read_b128 v[242:245], v179 offset:56320
	s_add_u32 s98, s2, 0xfffc0000
	s_addc_u32 s99, s3, -1
	global_load_lds_dwordx4 v166, s[98:99]
	s_mov_b32 m0, s46
	s_nop 0
	global_load_lds_dwordx4 v162, s[98:99]
	s_mov_b32 m0, s49
	s_nop 0
	global_load_lds_dwordx4 v166, s[2:3]
	s_mov_b32 m0, s50
	s_nop 0
	global_load_lds_dwordx4 v162, s[2:3]
	s_mov_b32 m0, s47
	s_nop 0
	s_add_u32 s100, s4, 0xfffc0080
	s_addc_u32 s101, s5, -1
	global_load_lds_dwordx4 v168, s[100:101]
	s_mov_b32 m0, s48
	s_nop 0
	global_load_lds_dwordx4 v164, s[100:101]
	s_waitcnt vmcnt(8)
	s_waitcnt lgkmcnt(0)
	s_barrier
	s_setprio 1
	v_mfma_f32_16x16x32_bf16 v[60:63], v[68:71], v[214:217], v[60:63]
	v_mfma_f32_16x16x32_bf16 v[56:59], v[76:79], v[214:217], v[56:59]
	v_mfma_f32_16x16x32_bf16 v[52:55], v[174:177], v[214:217], v[52:55]
	v_mfma_f32_16x16x32_bf16 v[48:51], v[186:189], v[214:217], v[48:51]
	v_mfma_f32_16x16x32_bf16 v[44:47], v[68:71], v[222:225], v[44:47]
	v_mfma_f32_16x16x32_bf16 v[40:43], v[76:79], v[222:225], v[40:43]
	v_mfma_f32_16x16x32_bf16 v[36:39], v[174:177], v[222:225], v[36:39]
	v_mfma_f32_16x16x32_bf16 v[32:35], v[186:189], v[222:225], v[32:35]
	v_mfma_f32_16x16x32_bf16 v[28:31], v[68:71], v[230:233], v[28:31]
	v_mfma_f32_16x16x32_bf16 v[24:27], v[76:79], v[230:233], v[24:27]
	v_mfma_f32_16x16x32_bf16 v[20:23], v[174:177], v[230:233], v[20:23]
	v_mfma_f32_16x16x32_bf16 v[16:19], v[186:189], v[230:233], v[16:19]
	v_mfma_f32_16x16x32_bf16 v[12:15], v[68:71], v[238:241], v[12:15]
	v_mfma_f32_16x16x32_bf16 v[8:11], v[76:79], v[238:241], v[8:11]
	v_mfma_f32_16x16x32_bf16 v[4:7], v[174:177], v[238:241], v[4:7]
	v_mfma_f32_16x16x32_bf16 v[0:3], v[186:189], v[238:241], v[0:3]
	v_mfma_f32_16x16x32_bf16 v[60:63], v[72:75], v[218:221], v[60:63]
	v_mfma_f32_16x16x32_bf16 v[56:59], v[80:83], v[218:221], v[56:59]
	v_mfma_f32_16x16x32_bf16 v[52:55], v[182:185], v[218:221], v[52:55]
	v_mfma_f32_16x16x32_bf16 v[48:51], v[210:213], v[218:221], v[48:51]
	v_mfma_f32_16x16x32_bf16 v[44:47], v[72:75], v[226:229], v[44:47]
	v_mfma_f32_16x16x32_bf16 v[40:43], v[80:83], v[226:229], v[40:43]
	v_mfma_f32_16x16x32_bf16 v[36:39], v[182:185], v[226:229], v[36:39]
	v_mfma_f32_16x16x32_bf16 v[32:35], v[210:213], v[226:229], v[32:35]
	v_mfma_f32_16x16x32_bf16 v[28:31], v[72:75], v[234:237], v[28:31]
	v_mfma_f32_16x16x32_bf16 v[24:27], v[80:83], v[234:237], v[24:27]
	v_mfma_f32_16x16x32_bf16 v[20:23], v[182:185], v[234:237], v[20:23]
	v_mfma_f32_16x16x32_bf16 v[16:19], v[210:213], v[234:237], v[16:19]
	v_mfma_f32_16x16x32_bf16 v[12:15], v[72:75], v[242:245], v[12:15]
	v_mfma_f32_16x16x32_bf16 v[8:11], v[80:83], v[242:245], v[8:11]
	v_mfma_f32_16x16x32_bf16 v[4:7], v[182:185], v[242:245], v[4:7]
	v_mfma_f32_16x16x32_bf16 v[0:3], v[210:213], v[242:245], v[0:3]
	s_setprio 0
	s_barrier
	s_add_i32 s56, s56, 2
	s_add_u32 s0, s0, 0x100
	s_addc_u32 s1, s1, 0
	s_add_u32 s54, s54, 0x100
	s_addc_u32 s55, s55, 0
	s_cmp_gt_u32 s56, 13
	s_cbranch_scc0 .LBB0_327
	s_and_b64 vcc, exec, s[22:23]
	s_cbranch_vccz .LBB0_330
	s_barrier

; #define PG8_STAGE(bufoff, gbase, voff) do { _Pragma("unroll") for (int _i = 0; _i < 2; ++_i) \
;         __builtin_amdgcn_global_load_lds((const unsigned*)((const char*)(gbase) + (voff)[_i]), (PG8_LAS unsigned*)(lds + (bufoff) + ldsw + _i * 8192), 16, 0, 0); } while (0)
; #define PG8_LDA(dst, b, h) do { _Pragma("unroll") for (int m = 0; m < 4; ++m) _Pragma("unroll") for (int k = 0; k < 2; ++k) dst[m][k] = *(const PG8_LAS bf16x8*)(lds + PG8_SA(b, h) + aoff + m * 2048 + k * 1024); } while (0)
; #define PG8_LDB(dst, b, h) do { _Pragma("unroll") for (int n = 0; n < 2; ++n) _Pragma("unroll") for (int k = 0; k < 2; ++k) dst[n][k] = *(const PG8_LAS bf16x8*)(lds + PG8_SB(b, h) + boff + n * 2048 + k * 1024); } while (0)
; #define PG8_WAIT_V(n) asm volatile("s_waitcnt vmcnt(" #n ")" ::: "memory")
; #define PG8_WAIT_L(n) asm volatile("s_waitcnt lgkmcnt(" #n ")" ::: "memory")
; #define PG8_BAR __builtin_amdgcn_s_barrier()
; #define PG8_SCHED __builtin_amdgcn_sched_barrier(0)
; template <class Epi, class Sched, bool ALIGN_EPI = false, bool SP2 = false>
; __device__ __forceinline__ void gemm_phase(PG8_LAS unsigned char* lds, const Gemm g, const Sched& S, const Epi& E) {
;     ...
;     for (;;) {
;         const bool has_next = S.next(ui + 1, nxt);
;         const char* nA = has_next ? (const char*)g.A + (size_t)nxt.pm * tstep : cA; const char* nB = has_next ? (const char*)g.Bt + (size_t)nxt.pn * tstep : cB;
;         for (int t = 0; t < nt; t += 2) {
;             const bool last = (t == nt - 2);
;             const char* a1 = cA + (size_t)(t + 1) * kstep;
;             const char* a2 = last ? nA : cA + (size_t)(t + 2) * kstep; const char* b2 = last ? nB : cB + (size_t)(t + 2) * kstep;
;             const char* a3 = a2 + kstep; const char* b3 = b2 + kstep;
;             if (last && has_next) S.a_ready(nxt);
;             if constexpr (SP2) {
;             PG8_LDB(B0, 0, 0); PG8_LDB(B1, 0, 1); PG8_SCHED; PG8_LDA(At, 0, 0); PG8_STAGE(PG8_SA(1, 1), a1 + hstep, voffA);
;             PG8_WAIT_V(8); PG8_WAIT_L(0); PG8_BAR; PG8_MMA(0, 0, At, B0); PG8_MMA(0, 1, At, B1); PG8_BAR; PG8_SCHED;
;             PG8_LDA(At, 0, 1); PG8_STAGE(PG8_SB(0, 0), b2, voffB); PG8_STAGE(PG8_SB(0, 1), b2 + hstep, voffB); PG8_STAGE(PG8_SA(0, 0), a2, voffA);
;             PG8_WAIT_V(8); PG8_WAIT_L(0); PG8_BAR; PG8_MMA(1, 0, At, B0); PG8_MMA(1, 1, At, B1); PG8_BAR; PG8_SCHED;
.Lup_peel:
	ds_read_b128 v[140:143], v254
	ds_read_b128 v[168:171], v254 offset:1024
	ds_read_b128 v[172:175], v254 offset:2048
	ds_read_b128 v[176:179], v254 offset:3072
	ds_read_b128 v[180:183], v254 offset:16384
	ds_read_b128 v[184:187], v254 offset:17408
	ds_read_b128 v[188:191], v254 offset:18432
	ds_read_b128 v[210:213], v254 offset:19456
	s_add_u32 s16, s14, 0xfffc0080
	s_addc_u32 s17, s15, -1
	s_cmp_eq_u32 s53, 12
	s_cselect_b32 s19, s7, s17
	s_cselect_b32 s18, s49, s16
	s_cselect_b32 s17, s5, s52
	s_cselect_b32 s16, s50, s51
	s_mov_b32 m0, s43
	ds_read_b128 v[214:217], v165
	ds_read_b128 v[218:221], v165 offset:1024
	ds_read_b128 v[222:225], v165 offset:2048
	ds_read_b128 v[226:229], v165 offset:3072
	ds_read_b128 v[230:233], v165 offset:4096
	ds_read_b128 v[234:237], v165 offset:5120
	ds_read_b128 v[238:241], v165 offset:6144
	ds_read_b128 v[242:245], v165 offset:7168
	global_load_lds_dwordx4 v136, s[14:15]
	s_mov_b32 m0, s44
	s_nop 0
	global_load_lds_dwordx4 v138, s[14:15]
	s_waitcnt vmcnt(8)
	s_waitcnt lgkmcnt(0)
	s_barrier
	s_setprio 1
	v_mfma_f32_16x16x32_bf16 v[124:127], v[140:143], v[214:217], 0
	v_mfma_f32_16x16x32_bf16 v[116:119], v[172:175], v[214:217], 0
	v_mfma_f32_16x16x32_bf16 v[120:123], v[180:183], v[214:217], 0
	v_mfma_f32_16x16x32_bf16 v[112:115], v[188:191], v[214:217], 0
	v_mfma_f32_16x16x32_bf16 v[108:111], v[140:143], v[222:225], 0
	v_mfma_f32_16x16x32_bf16 v[100:103], v[172:175], v[222:225], 0
	v_mfma_f32_16x16x32_bf16 v[104:107], v[180:183], v[222:225], 0
	v_mfma_f32_16x16x32_bf16 v[96:99], v[188:191], v[222:225], 0
	v_mfma_f32_16x16x32_bf16 v[92:95], v[140:143], v[230:233], 0
	v_mfma_f32_16x16x32_bf16 v[84:87], v[172:175], v[230:233], 0
	v_mfma_f32_16x16x32_bf16 v[88:91], v[180:183], v[230:233], 0
	v_mfma_f32_16x16x32_bf16 v[80:83], v[188:191], v[230:233], 0
	v_mfma_f32_16x16x32_bf16 v[76:79], v[140:143], v[238:241], 0
	v_mfma_f32_16x16x32_bf16 v[68:71], v[172:175], v[238:241], 0
	v_mfma_f32_16x16x32_bf16 v[72:75], v[180:183], v[238:241], 0
	v_mfma_f32_16x16x32_bf16 v[64:67], v[188:191], v[238:241], 0
	v_mfma_f32_16x16x32_bf16 v[124:127], v[168:171], v[218:221], v[124:127]
	v_mfma_f32_16x16x32_bf16 v[116:119], v[176:179], v[218:221], v[116:119]
	v_mfma_f32_16x16x32_bf16 v[120:123], v[184:187], v[218:221], v[120:123]
	v_mfma_f32_16x16x32_bf16 v[112:115], v[210:213], v[218:221], v[112:115]
	v_mfma_f32_16x16x32_bf16 v[108:111], v[168:171], v[226:229], v[108:111]
	v_mfma_f32_16x16x32_bf16 v[100:103], v[176:179], v[226:229], v[100:103]
	v_mfma_f32_16x16x32_bf16 v[104:107], v[184:187], v[226:229], v[104:107]
	v_mfma_f32_16x16x32_bf16 v[96:99], v[210:213], v[226:229], v[96:99]
	v_mfma_f32_16x16x32_bf16 v[92:95], v[168:171], v[234:237], v[92:95]
	v_mfma_f32_16x16x32_bf16 v[84:87], v[176:179], v[234:237], v[84:87]
	v_mfma_f32_16x16x32_bf16 v[88:91], v[184:187], v[234:237], v[88:91]
	v_mfma_f32_16x16x32_bf16 v[80:83], v[210:213], v[234:237], v[80:83]
	v_mfma_f32_16x16x32_bf16 v[76:79], v[168:171], v[242:245], v[76:79]
	v_mfma_f32_16x16x32_bf16 v[68:71], v[176:179], v[242:245], v[68:71]
	v_mfma_f32_16x16x32_bf16 v[72:75], v[184:187], v[242:245], v[72:75]
	v_mfma_f32_16x16x32_bf16 v[64:67], v[210:213], v[242:245], v[64:67]
	s_setprio 0
	s_barrier
	s_mov_b32 m0, s27
	s_add_u32 s54, s16, 0x40000
	s_addc_u32 s55, s17, 0
	ds_read_b128 v[214:217], v165 offset:16384
	ds_read_b128 v[218:221], v165 offset:17408
	ds_read_b128 v[222:225], v165 offset:18432
	ds_read_b128 v[226:229], v165 offset:19456
	ds_read_b128 v[230:233], v165 offset:20480
	ds_read_b128 v[234:237], v165 offset:21504
	ds_read_b128 v[238:241], v165 offset:22528
	ds_read_b128 v[242:245], v165 offset:23552
	global_load_lds_dwordx4 v132, s[16:17]
	s_mov_b32 m0, s28
	s_nop 0
	global_load_lds_dwordx4 v128, s[16:17]
	s_mov_b32 m0, s29
	s_nop 0
	global_load_lds_dwordx4 v132, s[54:55]
	s_mov_b32 m0, s30
	s_nop 0
	global_load_lds_dwordx4 v128, s[54:55]
	s_mov_b32 m0, s22
	s_nop 0
	global_load_lds_dwordx4 v134, s[18:19]
	s_mov_b32 m0, s31
	s_nop 0
	global_load_lds_dwordx4 v130, s[18:19]
	s_waitcnt vmcnt(8)
	s_waitcnt lgkmcnt(0)
	s_barrier
	s_setprio 1
	v_mfma_f32_16x16x32_bf16 v[60:63], v[140:143], v[214:217], 0
	v_mfma_f32_16x16x32_bf16 v[52:55], v[172:175], v[214:217], 0
	v_mfma_f32_16x16x32_bf16 v[56:59], v[180:183], v[214:217], 0
	v_mfma_f32_16x16x32_bf16 v[48:51], v[188:191], v[214:217], 0
	v_mfma_f32_16x16x32_bf16 v[44:47], v[140:143], v[222:225], 0
	v_mfma_f32_16x16x32_bf16 v[36:39], v[172:175], v[222:225], 0
	v_mfma_f32_16x16x32_bf16 v[40:43], v[180:183], v[222:225], 0
	v_mfma_f32_16x16x32_bf16 v[32:35], v[188:191], v[222:225], 0
	v_mfma_f32_16x16x32_bf16 v[28:31], v[140:143], v[230:233], 0
	v_mfma_f32_16x16x32_bf16 v[20:23], v[172:175], v[230:233], 0
	v_mfma_f32_16x16x32_bf16 v[24:27], v[180:183], v[230:233], 0
	v_mfma_f32_16x16x32_bf16 v[16:19], v[188:191], v[230:233], 0
	v_mfma_f32_16x16x32_bf16 v[12:15], v[140:143], v[238:241], 0
	v_mfma_f32_16x16x32_bf16 v[4:7], v[172:175], v[238:241], 0
	v_mfma_f32_16x16x32_bf16 v[8:11], v[180:183], v[238:241], 0
	v_mfma_f32_16x16x32_bf16 v[0:3], v[188:191], v[238:241], 0
	v_mfma_f32_16x16x32_bf16 v[60:63], v[168:171], v[218:221], v[60:63]
	v_mfma_f32_16x16x32_bf16 v[52:55], v[176:179], v[218:221], v[52:55]
	v_mfma_f32_16x16x32_bf16 v[56:59], v[184:187], v[218:221], v[56:59]
	v_mfma_f32_16x16x32_bf16 v[48:51], v[210:213], v[218:221], v[48:51]
	v_mfma_f32_16x16x32_bf16 v[44:47], v[168:171], v[226:229], v[44:47]
	v_mfma_f32_16x16x32_bf16 v[36:39], v[176:179], v[226:229], v[36:39]
	v_mfma_f32_16x16x32_bf16 v[40:43], v[184:187], v[226:229], v[40:43]
	v_mfma_f32_16x16x32_bf16 v[32:35], v[210:213], v[226:229], v[32:35]
	v_mfma_f32_16x16x32_bf16 v[28:31], v[168:171], v[234:237], v[28:31]
	v_mfma_f32_16x16x32_bf16 v[20:23], v[176:179], v[234:237], v[20:23]
	v_mfma_f32_16x16x32_bf16 v[24:27], v[184:187], v[234:237], v[24:27]
	v_mfma_f32_16x16x32_bf16 v[16:19], v[210:213], v[234:237], v[16:19]
	v_mfma_f32_16x16x32_bf16 v[12:15], v[168:171], v[242:245], v[12:15]
	v_mfma_f32_16x16x32_bf16 v[4:7], v[176:179], v[242:245], v[4:7]
	v_mfma_f32_16x16x32_bf16 v[8:11], v[184:187], v[242:245], v[8:11]
	v_mfma_f32_16x16x32_bf16 v[0:3], v[210:213], v[242:245], v[0:3]
	s_setprio 0
	s_barrier
; #define PG8_STAGE(bufoff, gbase, voff) do { _Pragma("unroll") for (int _i = 0; _i < 2; ++_i) \
;         __builtin_amdgcn_global_load_lds((const unsigned*)((const char*)(gbase) + (voff)[_i]), (PG8_LAS unsigned*)(lds + (bufoff) + ldsw + _i * 8192), 16, 0, 0); } while (0)
; #define PG8_LDA(dst, b, h) do { _Pragma("unroll") for (int m = 0; m < 4; ++m) _Pragma("unroll") for (int k = 0; k < 2; ++k) dst[m][k] = *(const PG8_LAS bf16x8*)(lds + PG8_SA(b, h) + aoff + m * 2048 + k * 1024); } while (0)
; #define PG8_LDB(dst, b, h) do { _Pragma("unroll") for (int n = 0; n < 2; ++n) _Pragma("unroll") for (int k = 0; k < 2; ++k) dst[n][k] = *(const PG8_LAS bf16x8*)(lds + PG8_SB(b, h) + boff + n * 2048 + k * 1024); } while (0)
; #define PG8_MMA(ai, bj, At, Bt) do { __builtin_amdgcn_s_setprio(1); _Pragma("unroll") for (int m = 0; m < 4; ++m) _Pragma("unroll") for (int n = 0; n < 2; ++n) _Pragma("unroll") for (int k = 0; k < 2; ++k) \
;         acc[ai][bj][m][n] = __builtin_amdgcn_mfma_f32_16x16x32_bf16(Bt[n][k], At[m][k], acc[ai][bj][m][n], 0, 0, 0); __builtin_amdgcn_s_setprio(0); } while (0)
; #define PG8_WAIT_V(n) asm volatile("s_waitcnt vmcnt(" #n ")" ::: "memory")
; #define PG8_WAIT_L(n) asm volatile("s_waitcnt lgkmcnt(" #n ")" ::: "memory")
; #define PG8_BAR __builtin_amdgcn_s_barrier()
; template <class Epi, class Sched, bool ALIGN_EPI = false, bool SP2 = false>
; __device__ __forceinline__ void gemm_phase(PG8_LAS unsigned char* lds, const Gemm g, const Sched& S, const Epi& E) {
;     ...
;         for (int t = 0; t < nt; t += 2) {
;             const bool last = (t == nt - 2);
;             const char* a1 = cA + (size_t)(t + 1) * kstep;
;             const char* a2 = last ? nA : cA + (size_t)(t + 2) * kstep; const char* b2 = last ? nB : cB + (size_t)(t + 2) * kstep;
;             const char* a3 = a2 + kstep; const char* b3 = b2 + kstep;
;     ...
;             PG8_LDB(B0, 1, 0); PG8_LDB(B1, 1, 1); PG8_SCHED; PG8_LDA(At, 1, 0); PG8_STAGE(PG8_SA(0, 1), a2 + hstep, voffA);
;             PG8_WAIT_V(8); PG8_WAIT_L(0); PG8_BAR; PG8_MMA(0, 0, At, B0); PG8_MMA(0, 1, At, B1); PG8_BAR; PG8_SCHED;
;             PG8_LDA(At, 1, 1); PG8_STAGE(PG8_SB(1, 0), b3, voffB); PG8_STAGE(PG8_SB(1, 1), b3 + hstep, voffB); PG8_STAGE(PG8_SA(1, 0), a3, voffA);
;             PG8_WAIT_V(8); PG8_WAIT_L(0); PG8_BAR; PG8_MMA(1, 0, At, B0); PG8_MMA(1, 1, At, B1); PG8_BAR; PG8_SCHED;
	ds_read_b128 v[140:143], v254 offset:32768
	ds_read_b128 v[168:171], v254 offset:33792
	ds_read_b128 v[172:175], v254 offset:34816
	ds_read_b128 v[176:179], v254 offset:35840
	ds_read_b128 v[180:183], v254 offset:49152
	ds_read_b128 v[184:187], v254 offset:50176
	ds_read_b128 v[188:191], v254 offset:51200
	ds_read_b128 v[210:213], v254 offset:52224
	s_add_u32 s18, s18, 0x40000
	s_addc_u32 s19, s19, 0
	s_mov_b32 m0, s33
	ds_read_b128 v[214:217], v165 offset:32768
	ds_read_b128 v[218:221], v165 offset:33792
	ds_read_b128 v[222:225], v165 offset:34816
	ds_read_b128 v[226:229], v165 offset:35840
	ds_read_b128 v[230:233], v165 offset:36864
	ds_read_b128 v[234:237], v165 offset:37888
	ds_read_b128 v[238:241], v165 offset:38912
	ds_read_b128 v[242:245], v165 offset:39936
	global_load_lds_dwordx4 v134, s[18:19]
	s_mov_b32 m0, s34
	s_nop 0
	global_load_lds_dwordx4 v130, s[18:19]
	s_waitcnt vmcnt(8)
	s_waitcnt lgkmcnt(0)
	s_barrier
	s_setprio 1
	v_mfma_f32_16x16x32_bf16 v[124:127], v[140:143], v[214:217], v[124:127]
	v_mfma_f32_16x16x32_bf16 v[116:119], v[172:175], v[214:217], v[116:119]
	v_mfma_f32_16x16x32_bf16 v[120:123], v[180:183], v[214:217], v[120:123]
	v_mfma_f32_16x16x32_bf16 v[112:115], v[188:191], v[214:217], v[112:115]
	v_mfma_f32_16x16x32_bf16 v[108:111], v[140:143], v[222:225], v[108:111]
	v_mfma_f32_16x16x32_bf16 v[100:103], v[172:175], v[222:225], v[100:103]
	v_mfma_f32_16x16x32_bf16 v[104:107], v[180:183], v[222:225], v[104:107]
	v_mfma_f32_16x16x32_bf16 v[96:99], v[188:191], v[222:225], v[96:99]
	v_mfma_f32_16x16x32_bf16 v[92:95], v[140:143], v[230:233], v[92:95]
	v_mfma_f32_16x16x32_bf16 v[84:87], v[172:175], v[230:233], v[84:87]
	v_mfma_f32_16x16x32_bf16 v[88:91], v[180:183], v[230:233], v[88:91]
	v_mfma_f32_16x16x32_bf16 v[80:83], v[188:191], v[230:233], v[80:83]
	v_mfma_f32_16x16x32_bf16 v[76:79], v[140:143], v[238:241], v[76:79]
	v_mfma_f32_16x16x32_bf16 v[68:71], v[172:175], v[238:241], v[68:71]
	v_mfma_f32_16x16x32_bf16 v[72:75], v[180:183], v[238:241], v[72:75]
	v_mfma_f32_16x16x32_bf16 v[64:67], v[188:191], v[238:241], v[64:67]
	v_mfma_f32_16x16x32_bf16 v[124:127], v[168:171], v[218:221], v[124:127]
	v_mfma_f32_16x16x32_bf16 v[116:119], v[176:179], v[218:221], v[116:119]
	v_mfma_f32_16x16x32_bf16 v[120:123], v[184:187], v[218:221], v[120:123]
	v_mfma_f32_16x16x32_bf16 v[112:115], v[210:213], v[218:221], v[112:115]
	v_mfma_f32_16x16x32_bf16 v[108:111], v[168:171], v[226:229], v[108:111]
	v_mfma_f32_16x16x32_bf16 v[100:103], v[176:179], v[226:229], v[100:103]
	v_mfma_f32_16x16x32_bf16 v[104:107], v[184:187], v[226:229], v[104:107]
	v_mfma_f32_16x16x32_bf16 v[96:99], v[210:213], v[226:229], v[96:99]
	v_mfma_f32_16x16x32_bf16 v[92:95], v[168:171], v[234:237], v[92:95]
	v_mfma_f32_16x16x32_bf16 v[84:87], v[176:179], v[234:237], v[84:87]
	v_mfma_f32_16x16x32_bf16 v[88:91], v[184:187], v[234:237], v[88:91]
	v_mfma_f32_16x16x32_bf16 v[80:83], v[210:213], v[234:237], v[80:83]
	v_mfma_f32_16x16x32_bf16 v[76:79], v[168:171], v[242:245], v[76:79]
	v_mfma_f32_16x16x32_bf16 v[68:71], v[176:179], v[242:245], v[68:71]
	v_mfma_f32_16x16x32_bf16 v[72:75], v[184:187], v[242:245], v[72:75]
	v_mfma_f32_16x16x32_bf16 v[64:67], v[210:213], v[242:245], v[64:67]
	s_setprio 0
	s_barrier
	s_mov_b32 m0, s37
	s_add_u32 s16, s16, 0x40080
	s_addc_u32 s17, s17, 0
	ds_read_b128 v[214:217], v165 offset:49152
	ds_read_b128 v[218:221], v165 offset:50176
	ds_read_b128 v[222:225], v165 offset:51200
	ds_read_b128 v[226:229], v165 offset:52224
	ds_read_b128 v[230:233], v165 offset:53248
	ds_read_b128 v[234:237], v165 offset:54272
	ds_read_b128 v[238:241], v165 offset:55296
	ds_read_b128 v[242:245], v165 offset:56320
	s_add_u32 s98, s16, 0xfffc0000
	s_addc_u32 s99, s17, -1
	global_load_lds_dwordx4 v132, s[98:99]
	s_mov_b32 m0, s38
	s_nop 0
	global_load_lds_dwordx4 v128, s[98:99]
	s_mov_b32 m0, s41
	s_nop 0
	global_load_lds_dwordx4 v132, s[16:17]
	s_mov_b32 m0, s42
	s_nop 0
	global_load_lds_dwordx4 v128, s[16:17]
	s_mov_b32 m0, s39
	s_nop 0
	s_add_u32 s100, s18, 0xfffc0080
	s_addc_u32 s101, s19, -1
	global_load_lds_dwordx4 v134, s[100:101]
	s_mov_b32 m0, s40
	s_nop 0
	global_load_lds_dwordx4 v130, s[100:101]
	s_waitcnt vmcnt(8)
	s_waitcnt lgkmcnt(0)
	s_barrier
	s_setprio 1
	v_mfma_f32_16x16x32_bf16 v[60:63], v[140:143], v[214:217], v[60:63]
	v_mfma_f32_16x16x32_bf16 v[52:55], v[172:175], v[214:217], v[52:55]
	v_mfma_f32_16x16x32_bf16 v[56:59], v[180:183], v[214:217], v[56:59]
	v_mfma_f32_16x16x32_bf16 v[48:51], v[188:191], v[214:217], v[48:51]
	v_mfma_f32_16x16x32_bf16 v[44:47], v[140:143], v[222:225], v[44:47]
	v_mfma_f32_16x16x32_bf16 v[36:39], v[172:175], v[222:225], v[36:39]
	v_mfma_f32_16x16x32_bf16 v[40:43], v[180:183], v[222:225], v[40:43]
	v_mfma_f32_16x16x32_bf16 v[32:35], v[188:191], v[222:225], v[32:35]
	v_mfma_f32_16x16x32_bf16 v[28:31], v[140:143], v[230:233], v[28:31]
	v_mfma_f32_16x16x32_bf16 v[20:23], v[172:175], v[230:233], v[20:23]
	v_mfma_f32_16x16x32_bf16 v[24:27], v[180:183], v[230:233], v[24:27]
	v_mfma_f32_16x16x32_bf16 v[16:19], v[188:191], v[230:233], v[16:19]
	v_mfma_f32_16x16x32_bf16 v[12:15], v[140:143], v[238:241], v[12:15]
	v_mfma_f32_16x16x32_bf16 v[4:7], v[172:175], v[238:241], v[4:7]
	v_mfma_f32_16x16x32_bf16 v[8:11], v[180:183], v[238:241], v[8:11]
	v_mfma_f32_16x16x32_bf16 v[0:3], v[188:191], v[238:241], v[0:3]
	v_mfma_f32_16x16x32_bf16 v[60:63], v[168:171], v[218:221], v[60:63]
	v_mfma_f32_16x16x32_bf16 v[52:55], v[176:179], v[218:221], v[52:55]
	v_mfma_f32_16x16x32_bf16 v[56:59], v[184:187], v[218:221], v[56:59]
	v_mfma_f32_16x16x32_bf16 v[48:51], v[210:213], v[218:221], v[48:51]
	v_mfma_f32_16x16x32_bf16 v[44:47], v[168:171], v[226:229], v[44:47]
	v_mfma_f32_16x16x32_bf16 v[36:39], v[176:179], v[226:229], v[36:39]
	v_mfma_f32_16x16x32_bf16 v[40:43], v[184:187], v[226:229], v[40:43]
	v_mfma_f32_16x16x32_bf16 v[32:35], v[210:213], v[226:229], v[32:35]
	v_mfma_f32_16x16x32_bf16 v[28:31], v[168:171], v[234:237], v[28:31]
	v_mfma_f32_16x16x32_bf16 v[20:23], v[176:179], v[234:237], v[20:23]
	v_mfma_f32_16x16x32_bf16 v[24:27], v[184:187], v[234:237], v[24:27]
	v_mfma_f32_16x16x32_bf16 v[16:19], v[210:213], v[234:237], v[16:19]
	v_mfma_f32_16x16x32_bf16 v[12:15], v[168:171], v[242:245], v[12:15]
	v_mfma_f32_16x16x32_bf16 v[4:7], v[176:179], v[242:245], v[4:7]
	v_mfma_f32_16x16x32_bf16 v[8:11], v[184:187], v[242:245], v[8:11]
	v_mfma_f32_16x16x32_bf16 v[0:3], v[210:213], v[242:245], v[0:3]
	s_setprio 0
	s_barrier
	s_add_i32 s53, s53, 2
	s_add_u32 s14, s14, 0x100
	s_addc_u32 s15, s15, 0
	s_add_u32 s51, s51, 0x100
	s_addc_u32 s52, s52, 0
	s_cmp_gt_u32 s53, 13
; #define PG8_STAGE(bufoff, gbase, voff) do { _Pragma("unroll") for (int _i = 0; _i < 2; ++_i) \
;         __builtin_amdgcn_global_load_lds((const unsigned*)((const char*)(gbase) + (voff)[_i]), (PG8_LAS unsigned*)(lds + (bufoff) + ldsw + _i * 8192), 16, 0, 0); } while (0)
; #define PG8_LDA(dst, b, h) do { _Pragma("unroll") for (int m = 0; m < 4; ++m) _Pragma("unroll") for (int k = 0; k < 2; ++k) dst[m][k] = *(const PG8_LAS bf16x8*)(lds + PG8_SA(b, h) + aoff + m * 2048 + k * 1024); } while (0)
; #define PG8_LDB(dst, b, h) do { _Pragma("unroll") for (int n = 0; n < 2; ++n) _Pragma("unroll") for (int k = 0; k < 2; ++k) dst[n][k] = *(const PG8_LAS bf16x8*)(lds + PG8_SB(b, h) + boff + n * 2048 + k * 1024); } while (0)
; #define PG8_MMA(ai, bj, At, Bt) do { __builtin_amdgcn_s_setprio(1); _Pragma("unroll") for (int m = 0; m < 4; ++m) _Pragma("unroll") for (int n = 0; n < 2; ++n) _Pragma("unroll") for (int k = 0; k < 2; ++k) \
;         acc[ai][bj][m][n] = __builtin_amdgcn_mfma_f32_16x16x32_bf16(Bt[n][k], At[m][k], acc[ai][bj][m][n], 0, 0, 0); __builtin_amdgcn_s_setprio(0); } while (0)
; #define PG8_WAIT_V(n) asm volatile("s_waitcnt vmcnt(" #n ")" ::: "memory")
; #define PG8_BAR __builtin_amdgcn_s_barrier()
; template <class Epi, class Sched, bool ALIGN_EPI = false, bool SP2 = false>
; __device__ __forceinline__ void gemm_phase(PG8_LAS unsigned char* lds, const Gemm g, const Sched& S, const Epi& E) {
;     ...
;         for (int t = 0; t < nt; t += 2) {
;             const bool last = (t == nt - 2);
;             const char* a1 = cA + (size_t)(t + 1) * kstep;
;             const char* a2 = last ? nA : cA + (size_t)(t + 2) * kstep; const char* b2 = last ? nB : cB + (size_t)(t + 2) * kstep;
;             const char* a3 = a2 + kstep; const char* b3 = b2 + kstep;
;             if (last && has_next) S.a_ready(nxt);
;             if constexpr (SP2) {
;             PG8_LDB(B0, 0, 0); PG8_LDB(B1, 0, 1); PG8_SCHED; PG8_LDA(At, 0, 0); PG8_STAGE(PG8_SA(1, 1), a1 + hstep, voffA);
;             PG8_WAIT_V(8); PG8_WAIT_L(0); PG8_BAR; PG8_MMA(0, 0, At, B0); PG8_MMA(0, 1, At, B1); PG8_BAR; PG8_SCHED;
;             PG8_LDA(At, 0, 1); PG8_STAGE(PG8_SB(0, 0), b2, voffB); PG8_STAGE(PG8_SB(0, 1), b2 + hstep, voffB); PG8_STAGE(PG8_SA(0, 0), a2, voffA);
;             PG8_WAIT_V(8); PG8_WAIT_L(0); PG8_BAR; PG8_MMA(1, 0, At, B0); PG8_MMA(1, 1, At, B1); PG8_BAR; PG8_SCHED;
.LBB0_446:
	ds_read_b128 v[140:143], v254
	ds_read_b128 v[168:171], v254 offset:1024
	ds_read_b128 v[172:175], v254 offset:2048
	ds_read_b128 v[176:179], v254 offset:3072
	ds_read_b128 v[180:183], v254 offset:16384
	ds_read_b128 v[184:187], v254 offset:17408
	ds_read_b128 v[188:191], v254 offset:18432
	ds_read_b128 v[210:213], v254 offset:19456
	s_add_u32 s16, s14, 0xfffc0080
	s_addc_u32 s17, s15, -1
	s_cmp_eq_u32 s53, 12
	s_cselect_b32 s19, s7, s17
	s_cselect_b32 s18, s49, s16
	s_cselect_b32 s17, s5, s52
	s_cselect_b32 s16, s50, s51
	s_mov_b32 m0, s43
	ds_read_b128 v[214:217], v165
	ds_read_b128 v[218:221], v165 offset:1024
	ds_read_b128 v[222:225], v165 offset:2048
	ds_read_b128 v[226:229], v165 offset:3072
	ds_read_b128 v[230:233], v165 offset:4096
	ds_read_b128 v[234:237], v165 offset:5120
	ds_read_b128 v[238:241], v165 offset:6144
	ds_read_b128 v[242:245], v165 offset:7168
	global_load_lds_dwordx4 v136, s[14:15]
	s_mov_b32 m0, s44
	s_nop 0
	global_load_lds_dwordx4 v138, s[14:15]
	s_waitcnt vmcnt(8)
	s_waitcnt lgkmcnt(0)
	s_barrier
	s_setprio 1
	v_mfma_f32_16x16x32_bf16 v[124:127], v[140:143], v[214:217], v[124:127]
	v_mfma_f32_16x16x32_bf16 v[116:119], v[172:175], v[214:217], v[116:119]
	v_mfma_f32_16x16x32_bf16 v[120:123], v[180:183], v[214:217], v[120:123]
	v_mfma_f32_16x16x32_bf16 v[112:115], v[188:191], v[214:217], v[112:115]
	v_mfma_f32_16x16x32_bf16 v[108:111], v[140:143], v[222:225], v[108:111]
	v_mfma_f32_16x16x32_bf16 v[100:103], v[172:175], v[222:225], v[100:103]
	v_mfma_f32_16x16x32_bf16 v[104:107], v[180:183], v[222:225], v[104:107]
	v_mfma_f32_16x16x32_bf16 v[96:99], v[188:191], v[222:225], v[96:99]
	v_mfma_f32_16x16x32_bf16 v[92:95], v[140:143], v[230:233], v[92:95]
	v_mfma_f32_16x16x32_bf16 v[84:87], v[172:175], v[230:233], v[84:87]
	v_mfma_f32_16x16x32_bf16 v[88:91], v[180:183], v[230:233], v[88:91]
	v_mfma_f32_16x16x32_bf16 v[80:83], v[188:191], v[230:233], v[80:83]
	v_mfma_f32_16x16x32_bf16 v[76:79], v[140:143], v[238:241], v[76:79]
	v_mfma_f32_16x16x32_bf16 v[68:71], v[172:175], v[238:241], v[68:71]
	v_mfma_f32_16x16x32_bf16 v[72:75], v[180:183], v[238:241], v[72:75]
	v_mfma_f32_16x16x32_bf16 v[64:67], v[188:191], v[238:241], v[64:67]
	v_mfma_f32_16x16x32_bf16 v[124:127], v[168:171], v[218:221], v[124:127]
	v_mfma_f32_16x16x32_bf16 v[116:119], v[176:179], v[218:221], v[116:119]
	v_mfma_f32_16x16x32_bf16 v[120:123], v[184:187], v[218:221], v[120:123]
	v_mfma_f32_16x16x32_bf16 v[112:115], v[210:213], v[218:221], v[112:115]
	v_mfma_f32_16x16x32_bf16 v[108:111], v[168:171], v[226:229], v[108:111]
	v_mfma_f32_16x16x32_bf16 v[100:103], v[176:179], v[226:229], v[100:103]
	v_mfma_f32_16x16x32_bf16 v[104:107], v[184:187], v[226:229], v[104:107]
	v_mfma_f32_16x16x32_bf16 v[96:99], v[210:213], v[226:229], v[96:99]
	v_mfma_f32_16x16x32_bf16 v[92:95], v[168:171], v[234:237], v[92:95]
	v_mfma_f32_16x16x32_bf16 v[84:87], v[176:179], v[234:237], v[84:87]
	v_mfma_f32_16x16x32_bf16 v[88:91], v[184:187], v[234:237], v[88:91]
	v_mfma_f32_16x16x32_bf16 v[80:83], v[210:213], v[234:237], v[80:83]
	v_mfma_f32_16x16x32_bf16 v[76:79], v[168:171], v[242:245], v[76:79]
	v_mfma_f32_16x16x32_bf16 v[68:71], v[176:179], v[242:245], v[68:71]
	v_mfma_f32_16x16x32_bf16 v[72:75], v[184:187], v[242:245], v[72:75]
	v_mfma_f32_16x16x32_bf16 v[64:67], v[210:213], v[242:245], v[64:67]
	s_setprio 0
	s_barrier
	s_mov_b32 m0, s27
	s_add_u32 s54, s16, 0x40000
	s_addc_u32 s55, s17, 0
	ds_read_b128 v[214:217], v165 offset:16384
	ds_read_b128 v[218:221], v165 offset:17408
	ds_read_b128 v[222:225], v165 offset:18432
	ds_read_b128 v[226:229], v165 offset:19456
	ds_read_b128 v[230:233], v165 offset:20480
	ds_read_b128 v[234:237], v165 offset:21504
	ds_read_b128 v[238:241], v165 offset:22528
	ds_read_b128 v[242:245], v165 offset:23552
	global_load_lds_dwordx4 v132, s[16:17]
	s_mov_b32 m0, s28
	s_nop 0
	global_load_lds_dwordx4 v128, s[16:17]
	s_mov_b32 m0, s29
	s_nop 0
	global_load_lds_dwordx4 v132, s[54:55]
	s_mov_b32 m0, s30
	s_nop 0
	global_load_lds_dwordx4 v128, s[54:55]
	s_mov_b32 m0, s22
	s_nop 0
	global_load_lds_dwordx4 v134, s[18:19]
	s_mov_b32 m0, s31
	s_nop 0
	global_load_lds_dwordx4 v130, s[18:19]
	s_waitcnt vmcnt(8)
	s_waitcnt lgkmcnt(0)
	s_barrier
	s_setprio 1
	v_mfma_f32_16x16x32_bf16 v[60:63], v[140:143], v[214:217], v[60:63]
	v_mfma_f32_16x16x32_bf16 v[52:55], v[172:175], v[214:217], v[52:55]
	v_mfma_f32_16x16x32_bf16 v[56:59], v[180:183], v[214:217], v[56:59]
	v_mfma_f32_16x16x32_bf16 v[48:51], v[188:191], v[214:217], v[48:51]
	v_mfma_f32_16x16x32_bf16 v[44:47], v[140:143], v[222:225], v[44:47]
	v_mfma_f32_16x16x32_bf16 v[36:39], v[172:175], v[222:225], v[36:39]
	v_mfma_f32_16x16x32_bf16 v[40:43], v[180:183], v[222:225], v[40:43]
	v_mfma_f32_16x16x32_bf16 v[32:35], v[188:191], v[222:225], v[32:35]
	v_mfma_f32_16x16x32_bf16 v[28:31], v[140:143], v[230:233], v[28:31]
	v_mfma_f32_16x16x32_bf16 v[20:23], v[172:175], v[230:233], v[20:23]
	v_mfma_f32_16x16x32_bf16 v[24:27], v[180:183], v[230:233], v[24:27]
	v_mfma_f32_16x16x32_bf16 v[16:19], v[188:191], v[230:233], v[16:19]
	v_mfma_f32_16x16x32_bf16 v[12:15], v[140:143], v[238:241], v[12:15]
	v_mfma_f32_16x16x32_bf16 v[4:7], v[172:175], v[238:241], v[4:7]
	v_mfma_f32_16x16x32_bf16 v[8:11], v[180:183], v[238:241], v[8:11]
	v_mfma_f32_16x16x32_bf16 v[0:3], v[188:191], v[238:241], v[0:3]
	v_mfma_f32_16x16x32_bf16 v[60:63], v[168:171], v[218:221], v[60:63]
	v_mfma_f32_16x16x32_bf16 v[52:55], v[176:179], v[218:221], v[52:55]
	v_mfma_f32_16x16x32_bf16 v[56:59], v[184:187], v[218:221], v[56:59]
	v_mfma_f32_16x16x32_bf16 v[48:51], v[210:213], v[218:221], v[48:51]
	v_mfma_f32_16x16x32_bf16 v[44:47], v[168:171], v[226:229], v[44:47]
	v_mfma_f32_16x16x32_bf16 v[36:39], v[176:179], v[226:229], v[36:39]
	v_mfma_f32_16x16x32_bf16 v[40:43], v[184:187], v[226:229], v[40:43]
	v_mfma_f32_16x16x32_bf16 v[32:35], v[210:213], v[226:229], v[32:35]
	v_mfma_f32_16x16x32_bf16 v[28:31], v[168:171], v[234:237], v[28:31]
	v_mfma_f32_16x16x32_bf16 v[20:23], v[176:179], v[234:237], v[20:23]
	v_mfma_f32_16x16x32_bf16 v[24:27], v[184:187], v[234:237], v[24:27]
	v_mfma_f32_16x16x32_bf16 v[16:19], v[210:213], v[234:237], v[16:19]
	v_mfma_f32_16x16x32_bf16 v[12:15], v[168:171], v[242:245], v[12:15]
	v_mfma_f32_16x16x32_bf16 v[4:7], v[176:179], v[242:245], v[4:7]
	v_mfma_f32_16x16x32_bf16 v[8:11], v[184:187], v[242:245], v[8:11]
	v_mfma_f32_16x16x32_bf16 v[0:3], v[210:213], v[242:245], v[0:3]
	s_setprio 0
	s_barrier
; #define PG8_STAGE(bufoff, gbase, voff) do { _Pragma("unroll") for (int _i = 0; _i < 2; ++_i) \
;         __builtin_amdgcn_global_load_lds((const unsigned*)((const char*)(gbase) + (voff)[_i]), (PG8_LAS unsigned*)(lds + (bufoff) + ldsw + _i * 8192), 16, 0, 0); } while (0)
; #define PG8_LDA(dst, b, h) do { _Pragma("unroll") for (int m = 0; m < 4; ++m) _Pragma("unroll") for (int k = 0; k < 2; ++k) dst[m][k] = *(const PG8_LAS bf16x8*)(lds + PG8_SA(b, h) + aoff + m * 2048 + k * 1024); } while (0)
; #define PG8_LDB(dst, b, h) do { _Pragma("unroll") for (int n = 0; n < 2; ++n) _Pragma("unroll") for (int k = 0; k < 2; ++k) dst[n][k] = *(const PG8_LAS bf16x8*)(lds + PG8_SB(b, h) + boff + n * 2048 + k * 1024); } while (0)
; #define PG8_MMA(ai, bj, At, Bt) do { __builtin_amdgcn_s_setprio(1); _Pragma("unroll") for (int m = 0; m < 4; ++m) _Pragma("unroll") for (int n = 0; n < 2; ++n) _Pragma("unroll") for (int k = 0; k < 2; ++k) \
;         acc[ai][bj][m][n] = __builtin_amdgcn_mfma_f32_16x16x32_bf16(Bt[n][k], At[m][k], acc[ai][bj][m][n], 0, 0, 0); __builtin_amdgcn_s_setprio(0); } while (0)
; #define PG8_WAIT_V(n) asm volatile("s_waitcnt vmcnt(" #n ")" ::: "memory")
; #define PG8_WAIT_L(n) asm volatile("s_waitcnt lgkmcnt(" #n ")" ::: "memory")
; #define PG8_BAR __builtin_amdgcn_s_barrier()
; template <class Epi, class Sched, bool ALIGN_EPI = false, bool SP2 = false>
; __device__ __forceinline__ void gemm_phase(PG8_LAS unsigned char* lds, const Gemm g, const Sched& S, const Epi& E) {
;     ...
;         for (int t = 0; t < nt; t += 2) {
;             const bool last = (t == nt - 2);
;             const char* a1 = cA + (size_t)(t + 1) * kstep;
;             const char* a2 = last ? nA : cA + (size_t)(t + 2) * kstep; const char* b2 = last ? nB : cB + (size_t)(t + 2) * kstep;
;             const char* a3 = a2 + kstep; const char* b3 = b2 + kstep;
;     ...
;             PG8_LDB(B0, 1, 0); PG8_LDB(B1, 1, 1); PG8_SCHED; PG8_LDA(At, 1, 0); PG8_STAGE(PG8_SA(0, 1), a2 + hstep, voffA);
;             PG8_WAIT_V(8); PG8_WAIT_L(0); PG8_BAR; PG8_MMA(0, 0, At, B0); PG8_MMA(0, 1, At, B1); PG8_BAR; PG8_SCHED;
;             PG8_LDA(At, 1, 1); PG8_STAGE(PG8_SB(1, 0), b3, voffB); PG8_STAGE(PG8_SB(1, 1), b3 + hstep, voffB); PG8_STAGE(PG8_SA(1, 0), a3, voffA);
;             PG8_WAIT_V(8); PG8_WAIT_L(0); PG8_BAR; PG8_MMA(1, 0, At, B0); PG8_MMA(1, 1, At, B1); PG8_BAR; PG8_SCHED;
	ds_read_b128 v[140:143], v254 offset:32768
	ds_read_b128 v[168:171], v254 offset:33792
	ds_read_b128 v[172:175], v254 offset:34816
	ds_read_b128 v[176:179], v254 offset:35840
	ds_read_b128 v[180:183], v254 offset:49152
	ds_read_b128 v[184:187], v254 offset:50176
	ds_read_b128 v[188:191], v254 offset:51200
	ds_read_b128 v[210:213], v254 offset:52224
	s_add_u32 s18, s18, 0x40000
	s_addc_u32 s19, s19, 0
	s_mov_b32 m0, s33
	ds_read_b128 v[214:217], v165 offset:32768
	ds_read_b128 v[218:221], v165 offset:33792
	ds_read_b128 v[222:225], v165 offset:34816
	ds_read_b128 v[226:229], v165 offset:35840
	ds_read_b128 v[230:233], v165 offset:36864
	ds_read_b128 v[234:237], v165 offset:37888
	ds_read_b128 v[238:241], v165 offset:38912
	ds_read_b128 v[242:245], v165 offset:39936
	global_load_lds_dwordx4 v134, s[18:19]
	s_mov_b32 m0, s34
	s_nop 0
	global_load_lds_dwordx4 v130, s[18:19]
	s_waitcnt vmcnt(8)
	s_waitcnt lgkmcnt(0)
	s_barrier
	s_setprio 1
	v_mfma_f32_16x16x32_bf16 v[124:127], v[140:143], v[214:217], v[124:127]
	v_mfma_f32_16x16x32_bf16 v[116:119], v[172:175], v[214:217], v[116:119]
	v_mfma_f32_16x16x32_bf16 v[120:123], v[180:183], v[214:217], v[120:123]
	v_mfma_f32_16x16x32_bf16 v[112:115], v[188:191], v[214:217], v[112:115]
	v_mfma_f32_16x16x32_bf16 v[108:111], v[140:143], v[222:225], v[108:111]
	v_mfma_f32_16x16x32_bf16 v[100:103], v[172:175], v[222:225], v[100:103]
	v_mfma_f32_16x16x32_bf16 v[104:107], v[180:183], v[222:225], v[104:107]
	v_mfma_f32_16x16x32_bf16 v[96:99], v[188:191], v[222:225], v[96:99]
	v_mfma_f32_16x16x32_bf16 v[92:95], v[140:143], v[230:233], v[92:95]
	v_mfma_f32_16x16x32_bf16 v[84:87], v[172:175], v[230:233], v[84:87]
	v_mfma_f32_16x16x32_bf16 v[88:91], v[180:183], v[230:233], v[88:91]
	v_mfma_f32_16x16x32_bf16 v[80:83], v[188:191], v[230:233], v[80:83]
	v_mfma_f32_16x16x32_bf16 v[76:79], v[140:143], v[238:241], v[76:79]
	v_mfma_f32_16x16x32_bf16 v[68:71], v[172:175], v[238:241], v[68:71]
	v_mfma_f32_16x16x32_bf16 v[72:75], v[180:183], v[238:241], v[72:75]
	v_mfma_f32_16x16x32_bf16 v[64:67], v[188:191], v[238:241], v[64:67]
	v_mfma_f32_16x16x32_bf16 v[124:127], v[168:171], v[218:221], v[124:127]
	v_mfma_f32_16x16x32_bf16 v[116:119], v[176:179], v[218:221], v[116:119]
	v_mfma_f32_16x16x32_bf16 v[120:123], v[184:187], v[218:221], v[120:123]
	v_mfma_f32_16x16x32_bf16 v[112:115], v[210:213], v[218:221], v[112:115]
	v_mfma_f32_16x16x32_bf16 v[108:111], v[168:171], v[226:229], v[108:111]
	v_mfma_f32_16x16x32_bf16 v[100:103], v[176:179], v[226:229], v[100:103]
	v_mfma_f32_16x16x32_bf16 v[104:107], v[184:187], v[226:229], v[104:107]
	v_mfma_f32_16x16x32_bf16 v[96:99], v[210:213], v[226:229], v[96:99]
	v_mfma_f32_16x16x32_bf16 v[92:95], v[168:171], v[234:237], v[92:95]
	v_mfma_f32_16x16x32_bf16 v[84:87], v[176:179], v[234:237], v[84:87]
	v_mfma_f32_16x16x32_bf16 v[88:91], v[184:187], v[234:237], v[88:91]
	v_mfma_f32_16x16x32_bf16 v[80:83], v[210:213], v[234:237], v[80:83]
	v_mfma_f32_16x16x32_bf16 v[76:79], v[168:171], v[242:245], v[76:79]
	v_mfma_f32_16x16x32_bf16 v[68:71], v[176:179], v[242:245], v[68:71]
	v_mfma_f32_16x16x32_bf16 v[72:75], v[184:187], v[242:245], v[72:75]
	v_mfma_f32_16x16x32_bf16 v[64:67], v[210:213], v[242:245], v[64:67]
	s_setprio 0
	s_barrier
	s_mov_b32 m0, s37
	s_add_u32 s16, s16, 0x40080
	s_addc_u32 s17, s17, 0
	ds_read_b128 v[214:217], v165 offset:49152
	ds_read_b128 v[218:221], v165 offset:50176
	ds_read_b128 v[222:225], v165 offset:51200
	ds_read_b128 v[226:229], v165 offset:52224
	ds_read_b128 v[230:233], v165 offset:53248
	ds_read_b128 v[234:237], v165 offset:54272
	ds_read_b128 v[238:241], v165 offset:55296
	ds_read_b128 v[242:245], v165 offset:56320
	s_add_u32 s98, s16, 0xfffc0000
	s_addc_u32 s99, s17, -1
	global_load_lds_dwordx4 v132, s[98:99]
	s_mov_b32 m0, s38
	s_nop 0
	global_load_lds_dwordx4 v128, s[98:99]
	s_mov_b32 m0, s41
	s_nop 0
	global_load_lds_dwordx4 v132, s[16:17]
	s_mov_b32 m0, s42
	s_nop 0
	global_load_lds_dwordx4 v128, s[16:17]
	s_mov_b32 m0, s39
	s_nop 0
	s_add_u32 s100, s18, 0xfffc0080
	s_addc_u32 s101, s19, -1
	global_load_lds_dwordx4 v134, s[100:101]
	s_mov_b32 m0, s40
	s_nop 0
	global_load_lds_dwordx4 v130, s[100:101]
	s_waitcnt vmcnt(8)
	s_waitcnt lgkmcnt(0)
	s_barrier
	s_setprio 1
	v_mfma_f32_16x16x32_bf16 v[60:63], v[140:143], v[214:217], v[60:63]
	v_mfma_f32_16x16x32_bf16 v[52:55], v[172:175], v[214:217], v[52:55]
	v_mfma_f32_16x16x32_bf16 v[56:59], v[180:183], v[214:217], v[56:59]
	v_mfma_f32_16x16x32_bf16 v[48:51], v[188:191], v[214:217], v[48:51]
	v_mfma_f32_16x16x32_bf16 v[44:47], v[140:143], v[222:225], v[44:47]
	v_mfma_f32_16x16x32_bf16 v[36:39], v[172:175], v[222:225], v[36:39]
	v_mfma_f32_16x16x32_bf16 v[40:43], v[180:183], v[222:225], v[40:43]
	v_mfma_f32_16x16x32_bf16 v[32:35], v[188:191], v[222:225], v[32:35]
	v_mfma_f32_16x16x32_bf16 v[28:31], v[140:143], v[230:233], v[28:31]
	v_mfma_f32_16x16x32_bf16 v[20:23], v[172:175], v[230:233], v[20:23]
	v_mfma_f32_16x16x32_bf16 v[24:27], v[180:183], v[230:233], v[24:27]
	v_mfma_f32_16x16x32_bf16 v[16:19], v[188:191], v[230:233], v[16:19]
	v_mfma_f32_16x16x32_bf16 v[12:15], v[140:143], v[238:241], v[12:15]
	v_mfma_f32_16x16x32_bf16 v[4:7], v[172:175], v[238:241], v[4:7]
	v_mfma_f32_16x16x32_bf16 v[8:11], v[180:183], v[238:241], v[8:11]
	v_mfma_f32_16x16x32_bf16 v[0:3], v[188:191], v[238:241], v[0:3]
	v_mfma_f32_16x16x32_bf16 v[60:63], v[168:171], v[218:221], v[60:63]
	v_mfma_f32_16x16x32_bf16 v[52:55], v[176:179], v[218:221], v[52:55]
	v_mfma_f32_16x16x32_bf16 v[56:59], v[184:187], v[218:221], v[56:59]
	v_mfma_f32_16x16x32_bf16 v[48:51], v[210:213], v[218:221], v[48:51]
	v_mfma_f32_16x16x32_bf16 v[44:47], v[168:171], v[226:229], v[44:47]
	v_mfma_f32_16x16x32_bf16 v[36:39], v[176:179], v[226:229], v[36:39]
	v_mfma_f32_16x16x32_bf16 v[40:43], v[184:187], v[226:229], v[40:43]
	v_mfma_f32_16x16x32_bf16 v[32:35], v[210:213], v[226:229], v[32:35]
	v_mfma_f32_16x16x32_bf16 v[28:31], v[168:171], v[234:237], v[28:31]
	v_mfma_f32_16x16x32_bf16 v[20:23], v[176:179], v[234:237], v[20:23]
	v_mfma_f32_16x16x32_bf16 v[24:27], v[184:187], v[234:237], v[24:27]
	v_mfma_f32_16x16x32_bf16 v[16:19], v[210:213], v[234:237], v[16:19]
	v_mfma_f32_16x16x32_bf16 v[12:15], v[168:171], v[242:245], v[12:15]
	v_mfma_f32_16x16x32_bf16 v[4:7], v[176:179], v[242:245], v[4:7]
	v_mfma_f32_16x16x32_bf16 v[8:11], v[184:187], v[242:245], v[8:11]
	v_mfma_f32_16x16x32_bf16 v[0:3], v[210:213], v[242:245], v[0:3]
	s_setprio 0
	s_barrier
	s_add_i32 s53, s53, 2
	s_add_u32 s14, s14, 0x100
	s_addc_u32 s15, s15, 0
	s_add_u32 s51, s51, 0x100
	s_addc_u32 s52, s52, 0
	s_cmp_gt_u32 s53, 13
	s_cbranch_scc0 .LBB0_446
	s_and_b64 vcc, exec, s[2:3]
	s_cbranch_vccz .LBB0_449
	s_barrier

; #define PG8_STAGE(bufoff, gbase, voff) do { _Pragma("unroll") for (int _i = 0; _i < 2; ++_i) \
;         __builtin_amdgcn_global_load_lds((const unsigned*)((const char*)(gbase) + (voff)[_i]), (PG8_LAS unsigned*)(lds + (bufoff) + ldsw + _i * 8192), 16, 0, 0); } while (0)
; #define PG8_LDA(dst, b, h) do { _Pragma("unroll") for (int m = 0; m < 4; ++m) _Pragma("unroll") for (int k = 0; k < 2; ++k) dst[m][k] = *(const PG8_LAS bf16x8*)(lds + PG8_SA(b, h) + aoff + m * 2048 + k * 1024); } while (0)
; #define PG8_LDB(dst, b, h) do { _Pragma("unroll") for (int n = 0; n < 2; ++n) _Pragma("unroll") for (int k = 0; k < 2; ++k) dst[n][k] = *(const PG8_LAS bf16x8*)(lds + PG8_SB(b, h) + boff + n * 2048 + k * 1024); } while (0)
; #define PG8_WAIT_V(n) asm volatile("s_waitcnt vmcnt(" #n ")" ::: "memory")
; #define PG8_WAIT_L(n) asm volatile("s_waitcnt lgkmcnt(" #n ")" ::: "memory")
; #define PG8_BAR __builtin_amdgcn_s_barrier()
; #define PG8_SCHED __builtin_amdgcn_sched_barrier(0)
; template <class Epi, class Sched, bool ALIGN_EPI = false, bool SP2 = false>
; __device__ __forceinline__ void gemm_phase(PG8_LAS unsigned char* lds, const Gemm g, const Sched& S, const Epi& E) {
;     ...
;     for (;;) {
;         const bool has_next = S.next(ui + 1, nxt);
;         const char* nA = has_next ? (const char*)g.A + (size_t)nxt.pm * tstep : cA; const char* nB = has_next ? (const char*)g.Bt + (size_t)nxt.pn * tstep : cB;
;         for (int t = 0; t < nt; t += 2) {
;             const bool last = (t == nt - 2);
;             const char* a1 = cA + (size_t)(t + 1) * kstep;
;             const char* a2 = last ? nA : cA + (size_t)(t + 2) * kstep; const char* b2 = last ? nB : cB + (size_t)(t + 2) * kstep;
;             const char* a3 = a2 + kstep; const char* b3 = b2 + kstep;
;             if (last && has_next) S.a_ready(nxt);
;             if constexpr (SP2) {
;             PG8_LDB(B0, 0, 0); PG8_LDB(B1, 0, 1); PG8_SCHED; PG8_LDA(At, 0, 0); PG8_STAGE(PG8_SA(1, 1), a1 + hstep, voffA);
;             PG8_WAIT_V(8); PG8_WAIT_L(0); PG8_BAR; PG8_MMA(0, 0, At, B0); PG8_MMA(0, 1, At, B1); PG8_BAR; PG8_SCHED;
;             PG8_LDA(At, 0, 1); PG8_STAGE(PG8_SB(0, 0), b2, voffB); PG8_STAGE(PG8_SB(0, 1), b2 + hstep, voffB); PG8_STAGE(PG8_SA(0, 0), a2, voffA);
;             PG8_WAIT_V(8); PG8_WAIT_L(0); PG8_BAR; PG8_MMA(1, 0, At, B0); PG8_MMA(1, 1, At, B1); PG8_BAR; PG8_SCHED;
.Ldn_peel:
	ds_read_b128 v[128:131], v254
	ds_read_b128 v[132:135], v254 offset:1024
	ds_read_b128 v[136:139], v254 offset:2048
	ds_read_b128 v[140:143], v254 offset:3072
	ds_read_b128 v[174:177], v254 offset:16384
	ds_read_b128 v[184:187], v254 offset:17408
	ds_read_b128 v[188:191], v254 offset:18432
	ds_read_b128 v[210:213], v254 offset:19456
	s_add_u32 s2, s0, 0x100
	s_addc_u32 s3, s1, 0
	s_cmp_eq_u32 s13, 40
	s_cselect_b32 s7, s27, s3
	s_cselect_b32 s6, s26, s2
	s_cselect_b32 s5, s37, s11
	s_cselect_b32 s4, s36, s10
	s_add_i32 m0, s29, 0xc000
	ds_read_b128 v[214:217], v181
	ds_read_b128 v[218:221], v181 offset:1024
	ds_read_b128 v[222:225], v181 offset:2048
	ds_read_b128 v[226:229], v181 offset:3072
	ds_read_b128 v[230:233], v181 offset:4096
	ds_read_b128 v[234:237], v181 offset:5120
	ds_read_b128 v[238:241], v181 offset:6144
	ds_read_b128 v[242:245], v181 offset:7168
	global_load_lds_dwordx4 v170, s[0:1]
	s_add_i32 m0, s29, 0xe000
	s_nop 0
	global_load_lds_dwordx4 v172, s[0:1]
	s_waitcnt vmcnt(8)
	s_waitcnt lgkmcnt(0)
	s_barrier
	s_setprio 1
	v_mfma_f32_16x16x32_bf16 v[124:127], v[128:131], v[214:217], 0
	v_mfma_f32_16x16x32_bf16 v[120:123], v[136:139], v[214:217], 0
	v_mfma_f32_16x16x32_bf16 v[116:119], v[174:177], v[214:217], 0
	v_mfma_f32_16x16x32_bf16 v[112:115], v[188:191], v[214:217], 0
	v_mfma_f32_16x16x32_bf16 v[108:111], v[128:131], v[222:225], 0
	v_mfma_f32_16x16x32_bf16 v[104:107], v[136:139], v[222:225], 0
	v_mfma_f32_16x16x32_bf16 v[100:103], v[174:177], v[222:225], 0
	v_mfma_f32_16x16x32_bf16 v[96:99], v[188:191], v[222:225], 0
	v_mfma_f32_16x16x32_bf16 v[92:95], v[128:131], v[230:233], 0
	v_mfma_f32_16x16x32_bf16 v[88:91], v[136:139], v[230:233], 0
	v_mfma_f32_16x16x32_bf16 v[84:87], v[174:177], v[230:233], 0
	v_mfma_f32_16x16x32_bf16 v[80:83], v[188:191], v[230:233], 0
	v_mfma_f32_16x16x32_bf16 v[76:79], v[128:131], v[238:241], 0
	v_mfma_f32_16x16x32_bf16 v[72:75], v[136:139], v[238:241], 0
	v_mfma_f32_16x16x32_bf16 v[68:71], v[174:177], v[238:241], 0
	v_mfma_f32_16x16x32_bf16 v[64:67], v[188:191], v[238:241], 0
	v_mfma_f32_16x16x32_bf16 v[124:127], v[132:135], v[218:221], v[124:127]
	v_mfma_f32_16x16x32_bf16 v[120:123], v[140:143], v[218:221], v[120:123]
	v_mfma_f32_16x16x32_bf16 v[116:119], v[184:187], v[218:221], v[116:119]
	v_mfma_f32_16x16x32_bf16 v[112:115], v[210:213], v[218:221], v[112:115]
	v_mfma_f32_16x16x32_bf16 v[108:111], v[132:135], v[226:229], v[108:111]
	v_mfma_f32_16x16x32_bf16 v[104:107], v[140:143], v[226:229], v[104:107]
	v_mfma_f32_16x16x32_bf16 v[100:103], v[184:187], v[226:229], v[100:103]
	v_mfma_f32_16x16x32_bf16 v[96:99], v[210:213], v[226:229], v[96:99]
	v_mfma_f32_16x16x32_bf16 v[92:95], v[132:135], v[234:237], v[92:95]
	v_mfma_f32_16x16x32_bf16 v[88:91], v[140:143], v[234:237], v[88:91]
	v_mfma_f32_16x16x32_bf16 v[84:87], v[184:187], v[234:237], v[84:87]
	v_mfma_f32_16x16x32_bf16 v[80:83], v[210:213], v[234:237], v[80:83]
	v_mfma_f32_16x16x32_bf16 v[76:79], v[132:135], v[242:245], v[76:79]
	v_mfma_f32_16x16x32_bf16 v[72:75], v[140:143], v[242:245], v[72:75]
	v_mfma_f32_16x16x32_bf16 v[68:71], v[184:187], v[242:245], v[68:71]
	v_mfma_f32_16x16x32_bf16 v[64:67], v[210:213], v[242:245], v[64:67]
	s_setprio 0
	s_barrier
	s_mov_b32 m0, s35
	s_add_u32 s0, s4, 0xb0000
	s_addc_u32 s1, s5, 0
	ds_read_b128 v[214:217], v181 offset:16384
	ds_read_b128 v[218:221], v181 offset:17408
	ds_read_b128 v[222:225], v181 offset:18432
	ds_read_b128 v[226:229], v181 offset:19456
	ds_read_b128 v[230:233], v181 offset:20480
	ds_read_b128 v[234:237], v181 offset:21504
	ds_read_b128 v[238:241], v181 offset:22528
	ds_read_b128 v[242:245], v181 offset:23552
	global_load_lds_dwordx4 v166, s[4:5]
	s_mov_b32 m0, s38
	s_nop 0
	global_load_lds_dwordx4 v162, s[4:5]
	s_mov_b32 m0, s39
	s_nop 0
	global_load_lds_dwordx4 v166, s[0:1]
	s_mov_b32 m0, s40
	s_nop 0
	global_load_lds_dwordx4 v162, s[0:1]
	s_mov_b32 m0, s29
	s_nop 0
	global_load_lds_dwordx4 v168, s[6:7]
	s_mov_b32 m0, s41
	s_nop 0
	global_load_lds_dwordx4 v164, s[6:7]
	s_waitcnt vmcnt(8)
	s_waitcnt lgkmcnt(0)
	s_barrier
	s_setprio 1
	v_mfma_f32_16x16x32_bf16 v[60:63], v[128:131], v[214:217], 0
	v_mfma_f32_16x16x32_bf16 v[56:59], v[136:139], v[214:217], 0
	v_mfma_f32_16x16x32_bf16 v[52:55], v[174:177], v[214:217], 0
	v_mfma_f32_16x16x32_bf16 v[48:51], v[188:191], v[214:217], 0
	v_mfma_f32_16x16x32_bf16 v[44:47], v[128:131], v[222:225], 0
	v_mfma_f32_16x16x32_bf16 v[40:43], v[136:139], v[222:225], 0
	v_mfma_f32_16x16x32_bf16 v[36:39], v[174:177], v[222:225], 0
	v_mfma_f32_16x16x32_bf16 v[32:35], v[188:191], v[222:225], 0
	v_mfma_f32_16x16x32_bf16 v[28:31], v[128:131], v[230:233], 0
	v_mfma_f32_16x16x32_bf16 v[24:27], v[136:139], v[230:233], 0
	v_mfma_f32_16x16x32_bf16 v[20:23], v[174:177], v[230:233], 0
	v_mfma_f32_16x16x32_bf16 v[16:19], v[188:191], v[230:233], 0
	v_mfma_f32_16x16x32_bf16 v[12:15], v[128:131], v[238:241], 0
	v_mfma_f32_16x16x32_bf16 v[8:11], v[136:139], v[238:241], 0
	v_mfma_f32_16x16x32_bf16 v[4:7], v[174:177], v[238:241], 0
	v_mfma_f32_16x16x32_bf16 v[0:3], v[188:191], v[238:241], 0
	v_mfma_f32_16x16x32_bf16 v[60:63], v[132:135], v[218:221], v[60:63]
	v_mfma_f32_16x16x32_bf16 v[56:59], v[140:143], v[218:221], v[56:59]
	v_mfma_f32_16x16x32_bf16 v[52:55], v[184:187], v[218:221], v[52:55]
	v_mfma_f32_16x16x32_bf16 v[48:51], v[210:213], v[218:221], v[48:51]
	v_mfma_f32_16x16x32_bf16 v[44:47], v[132:135], v[226:229], v[44:47]
	v_mfma_f32_16x16x32_bf16 v[40:43], v[140:143], v[226:229], v[40:43]
	v_mfma_f32_16x16x32_bf16 v[36:39], v[184:187], v[226:229], v[36:39]
	v_mfma_f32_16x16x32_bf16 v[32:35], v[210:213], v[226:229], v[32:35]
	v_mfma_f32_16x16x32_bf16 v[28:31], v[132:135], v[234:237], v[28:31]
	v_mfma_f32_16x16x32_bf16 v[24:27], v[140:143], v[234:237], v[24:27]
	v_mfma_f32_16x16x32_bf16 v[20:23], v[184:187], v[234:237], v[20:23]
	v_mfma_f32_16x16x32_bf16 v[16:19], v[210:213], v[234:237], v[16:19]
	v_mfma_f32_16x16x32_bf16 v[12:15], v[132:135], v[242:245], v[12:15]
	v_mfma_f32_16x16x32_bf16 v[8:11], v[140:143], v[242:245], v[8:11]
	v_mfma_f32_16x16x32_bf16 v[4:7], v[184:187], v[242:245], v[4:7]
	v_mfma_f32_16x16x32_bf16 v[0:3], v[210:213], v[242:245], v[0:3]
	s_setprio 0
	s_barrier
; #define PG8_STAGE(bufoff, gbase, voff) do { _Pragma("unroll") for (int _i = 0; _i < 2; ++_i) \
;         __builtin_amdgcn_global_load_lds((const unsigned*)((const char*)(gbase) + (voff)[_i]), (PG8_LAS unsigned*)(lds + (bufoff) + ldsw + _i * 8192), 16, 0, 0); } while (0)
; #define PG8_LDA(dst, b, h) do { _Pragma("unroll") for (int m = 0; m < 4; ++m) _Pragma("unroll") for (int k = 0; k < 2; ++k) dst[m][k] = *(const PG8_LAS bf16x8*)(lds + PG8_SA(b, h) + aoff + m * 2048 + k * 1024); } while (0)
; #define PG8_LDB(dst, b, h) do { _Pragma("unroll") for (int n = 0; n < 2; ++n) _Pragma("unroll") for (int k = 0; k < 2; ++k) dst[n][k] = *(const PG8_LAS bf16x8*)(lds + PG8_SB(b, h) + boff + n * 2048 + k * 1024); } while (0)
; #define PG8_MMA(ai, bj, At, Bt) do { __builtin_amdgcn_s_setprio(1); _Pragma("unroll") for (int m = 0; m < 4; ++m) _Pragma("unroll") for (int n = 0; n < 2; ++n) _Pragma("unroll") for (int k = 0; k < 2; ++k) \
;         acc[ai][bj][m][n] = __builtin_amdgcn_mfma_f32_16x16x32_bf16(Bt[n][k], At[m][k], acc[ai][bj][m][n], 0, 0, 0); __builtin_amdgcn_s_setprio(0); } while (0)
; #define PG8_WAIT_V(n) asm volatile("s_waitcnt vmcnt(" #n ")" ::: "memory")
; #define PG8_WAIT_L(n) asm volatile("s_waitcnt lgkmcnt(" #n ")" ::: "memory")
; #define PG8_BAR __builtin_amdgcn_s_barrier()
; template <class Epi, class Sched, bool ALIGN_EPI = false, bool SP2 = false>
; __device__ __forceinline__ void gemm_phase(PG8_LAS unsigned char* lds, const Gemm g, const Sched& S, const Epi& E) {
;     ...
;         for (int t = 0; t < nt; t += 2) {
;             const bool last = (t == nt - 2);
;             const char* a1 = cA + (size_t)(t + 1) * kstep;
;             const char* a2 = last ? nA : cA + (size_t)(t + 2) * kstep; const char* b2 = last ? nB : cB + (size_t)(t + 2) * kstep;
;             const char* a3 = a2 + kstep; const char* b3 = b2 + kstep;
;     ...
;             PG8_LDB(B0, 1, 0); PG8_LDB(B1, 1, 1); PG8_SCHED; PG8_LDA(At, 1, 0); PG8_STAGE(PG8_SA(0, 1), a2 + hstep, voffA);
;             PG8_WAIT_V(8); PG8_WAIT_L(0); PG8_BAR; PG8_MMA(0, 0, At, B0); PG8_MMA(0, 1, At, B1); PG8_BAR; PG8_SCHED;
;             PG8_LDA(At, 1, 1); PG8_STAGE(PG8_SB(1, 0), b3, voffB); PG8_STAGE(PG8_SB(1, 1), b3 + hstep, voffB); PG8_STAGE(PG8_SA(1, 0), a3, voffA);
;             PG8_WAIT_V(8); PG8_WAIT_L(0); PG8_BAR; PG8_MMA(1, 0, At, B0); PG8_MMA(1, 1, At, B1); PG8_BAR; PG8_SCHED;
	ds_read_b128 v[128:131], v254 offset:32768
	ds_read_b128 v[132:135], v254 offset:33792
	ds_read_b128 v[136:139], v254 offset:34816
	ds_read_b128 v[140:143], v254 offset:35840
	ds_read_b128 v[174:177], v254 offset:49152
	ds_read_b128 v[184:187], v254 offset:50176
	ds_read_b128 v[188:191], v254 offset:51200
	ds_read_b128 v[210:213], v254 offset:52224
	s_add_u32 s0, s6, 0xb0000
	s_addc_u32 s1, s7, 0
	s_mov_b32 m0, s42
	ds_read_b128 v[214:217], v181 offset:32768
	ds_read_b128 v[218:221], v181 offset:33792
	ds_read_b128 v[222:225], v181 offset:34816
	ds_read_b128 v[226:229], v181 offset:35840
	ds_read_b128 v[230:233], v181 offset:36864
	ds_read_b128 v[234:237], v181 offset:37888
	ds_read_b128 v[238:241], v181 offset:38912
	ds_read_b128 v[242:245], v181 offset:39936
	global_load_lds_dwordx4 v168, s[0:1]
	s_mov_b32 m0, s43
	s_nop 0
	global_load_lds_dwordx4 v164, s[0:1]
	s_waitcnt vmcnt(8)
	s_waitcnt lgkmcnt(0)
	s_barrier
	s_setprio 1
	v_mfma_f32_16x16x32_bf16 v[124:127], v[128:131], v[214:217], v[124:127]
	v_mfma_f32_16x16x32_bf16 v[120:123], v[136:139], v[214:217], v[120:123]
	v_mfma_f32_16x16x32_bf16 v[116:119], v[174:177], v[214:217], v[116:119]
	v_mfma_f32_16x16x32_bf16 v[112:115], v[188:191], v[214:217], v[112:115]
	v_mfma_f32_16x16x32_bf16 v[108:111], v[128:131], v[222:225], v[108:111]
	v_mfma_f32_16x16x32_bf16 v[104:107], v[136:139], v[222:225], v[104:107]
	v_mfma_f32_16x16x32_bf16 v[100:103], v[174:177], v[222:225], v[100:103]
	v_mfma_f32_16x16x32_bf16 v[96:99], v[188:191], v[222:225], v[96:99]
	v_mfma_f32_16x16x32_bf16 v[92:95], v[128:131], v[230:233], v[92:95]
	v_mfma_f32_16x16x32_bf16 v[88:91], v[136:139], v[230:233], v[88:91]
	v_mfma_f32_16x16x32_bf16 v[84:87], v[174:177], v[230:233], v[84:87]
	v_mfma_f32_16x16x32_bf16 v[80:83], v[188:191], v[230:233], v[80:83]
	v_mfma_f32_16x16x32_bf16 v[76:79], v[128:131], v[238:241], v[76:79]
	v_mfma_f32_16x16x32_bf16 v[72:75], v[136:139], v[238:241], v[72:75]
	v_mfma_f32_16x16x32_bf16 v[68:71], v[174:177], v[238:241], v[68:71]
	v_mfma_f32_16x16x32_bf16 v[64:67], v[188:191], v[238:241], v[64:67]
	v_mfma_f32_16x16x32_bf16 v[124:127], v[132:135], v[218:221], v[124:127]
	v_mfma_f32_16x16x32_bf16 v[120:123], v[140:143], v[218:221], v[120:123]
	v_mfma_f32_16x16x32_bf16 v[116:119], v[184:187], v[218:221], v[116:119]
	v_mfma_f32_16x16x32_bf16 v[112:115], v[210:213], v[218:221], v[112:115]
	v_mfma_f32_16x16x32_bf16 v[108:111], v[132:135], v[226:229], v[108:111]
	v_mfma_f32_16x16x32_bf16 v[104:107], v[140:143], v[226:229], v[104:107]
	v_mfma_f32_16x16x32_bf16 v[100:103], v[184:187], v[226:229], v[100:103]
	v_mfma_f32_16x16x32_bf16 v[96:99], v[210:213], v[226:229], v[96:99]
	v_mfma_f32_16x16x32_bf16 v[92:95], v[132:135], v[234:237], v[92:95]
	v_mfma_f32_16x16x32_bf16 v[88:91], v[140:143], v[234:237], v[88:91]
	v_mfma_f32_16x16x32_bf16 v[84:87], v[184:187], v[234:237], v[84:87]
	v_mfma_f32_16x16x32_bf16 v[80:83], v[210:213], v[234:237], v[80:83]
	v_mfma_f32_16x16x32_bf16 v[76:79], v[132:135], v[242:245], v[76:79]
	v_mfma_f32_16x16x32_bf16 v[72:75], v[140:143], v[242:245], v[72:75]
	v_mfma_f32_16x16x32_bf16 v[68:71], v[184:187], v[242:245], v[68:71]
	v_mfma_f32_16x16x32_bf16 v[64:67], v[210:213], v[242:245], v[64:67]
	s_setprio 0
	s_barrier
	s_mov_b32 m0, s47
	s_add_u32 s0, s4, 0xb0080
	s_addc_u32 s1, s5, 0
	ds_read_b128 v[214:217], v181 offset:49152
	ds_read_b128 v[218:221], v181 offset:50176
	ds_read_b128 v[222:225], v181 offset:51200
	ds_read_b128 v[226:229], v181 offset:52224
	ds_read_b128 v[230:233], v181 offset:53248
	ds_read_b128 v[234:237], v181 offset:54272
	ds_read_b128 v[238:241], v181 offset:55296
	ds_read_b128 v[242:245], v181 offset:56320
	s_add_u32 s98, s4, 0x80
	s_addc_u32 s99, s5, 0
	global_load_lds_dwordx4 v166, s[98:99]
	s_mov_b32 m0, s48
	s_nop 0
	global_load_lds_dwordx4 v162, s[98:99]
	s_mov_b32 m0, s51
	s_nop 0
	global_load_lds_dwordx4 v166, s[0:1]
	s_mov_b32 m0, s52
	s_nop 0
	global_load_lds_dwordx4 v162, s[0:1]
	s_mov_b32 m0, s49
	s_nop 0
	s_add_u32 s100, s6, 0x80
	s_addc_u32 s101, s7, 0
	global_load_lds_dwordx4 v168, s[100:101]
	s_mov_b32 m0, s50
	s_nop 0
	global_load_lds_dwordx4 v164, s[100:101]
	s_waitcnt vmcnt(8)
	s_waitcnt lgkmcnt(0)
	s_barrier
	s_setprio 1
	v_mfma_f32_16x16x32_bf16 v[60:63], v[128:131], v[214:217], v[60:63]
	v_mfma_f32_16x16x32_bf16 v[56:59], v[136:139], v[214:217], v[56:59]
	v_mfma_f32_16x16x32_bf16 v[52:55], v[174:177], v[214:217], v[52:55]
	v_mfma_f32_16x16x32_bf16 v[48:51], v[188:191], v[214:217], v[48:51]
	v_mfma_f32_16x16x32_bf16 v[44:47], v[128:131], v[222:225], v[44:47]
	v_mfma_f32_16x16x32_bf16 v[40:43], v[136:139], v[222:225], v[40:43]
	v_mfma_f32_16x16x32_bf16 v[36:39], v[174:177], v[222:225], v[36:39]
	v_mfma_f32_16x16x32_bf16 v[32:35], v[188:191], v[222:225], v[32:35]
	v_mfma_f32_16x16x32_bf16 v[28:31], v[128:131], v[230:233], v[28:31]
	v_mfma_f32_16x16x32_bf16 v[24:27], v[136:139], v[230:233], v[24:27]
	v_mfma_f32_16x16x32_bf16 v[20:23], v[174:177], v[230:233], v[20:23]
	v_mfma_f32_16x16x32_bf16 v[16:19], v[188:191], v[230:233], v[16:19]
	v_mfma_f32_16x16x32_bf16 v[12:15], v[128:131], v[238:241], v[12:15]
	v_mfma_f32_16x16x32_bf16 v[8:11], v[136:139], v[238:241], v[8:11]
	v_mfma_f32_16x16x32_bf16 v[4:7], v[174:177], v[238:241], v[4:7]
	v_mfma_f32_16x16x32_bf16 v[0:3], v[188:191], v[238:241], v[0:3]
	v_mfma_f32_16x16x32_bf16 v[60:63], v[132:135], v[218:221], v[60:63]
	v_mfma_f32_16x16x32_bf16 v[56:59], v[140:143], v[218:221], v[56:59]
	v_mfma_f32_16x16x32_bf16 v[52:55], v[184:187], v[218:221], v[52:55]
	v_mfma_f32_16x16x32_bf16 v[48:51], v[210:213], v[218:221], v[48:51]
	v_mfma_f32_16x16x32_bf16 v[44:47], v[132:135], v[226:229], v[44:47]
	v_mfma_f32_16x16x32_bf16 v[40:43], v[140:143], v[226:229], v[40:43]
	v_mfma_f32_16x16x32_bf16 v[36:39], v[184:187], v[226:229], v[36:39]
	v_mfma_f32_16x16x32_bf16 v[32:35], v[210:213], v[226:229], v[32:35]
	v_mfma_f32_16x16x32_bf16 v[28:31], v[132:135], v[234:237], v[28:31]
	v_mfma_f32_16x16x32_bf16 v[24:27], v[140:143], v[234:237], v[24:27]
	v_mfma_f32_16x16x32_bf16 v[20:23], v[184:187], v[234:237], v[20:23]
	v_mfma_f32_16x16x32_bf16 v[16:19], v[210:213], v[234:237], v[16:19]
	v_mfma_f32_16x16x32_bf16 v[12:15], v[132:135], v[242:245], v[12:15]
	v_mfma_f32_16x16x32_bf16 v[8:11], v[140:143], v[242:245], v[8:11]
	v_mfma_f32_16x16x32_bf16 v[4:7], v[184:187], v[242:245], v[4:7]
	v_mfma_f32_16x16x32_bf16 v[0:3], v[210:213], v[242:245], v[0:3]
	s_setprio 0
	s_barrier
	s_add_i32 s13, s13, 2
	s_add_u32 s10, s10, 0x100
	s_addc_u32 s11, s11, 0
	s_cmp_gt_u32 s13, 41
	s_mov_b64 s[0:1], s[2:3]
; #define PG8_STAGE(bufoff, gbase, voff) do { _Pragma("unroll") for (int _i = 0; _i < 2; ++_i) \
;         __builtin_amdgcn_global_load_lds((const unsigned*)((const char*)(gbase) + (voff)[_i]), (PG8_LAS unsigned*)(lds + (bufoff) + ldsw + _i * 8192), 16, 0, 0); } while (0)
; #define PG8_LDA(dst, b, h) do { _Pragma("unroll") for (int m = 0; m < 4; ++m) _Pragma("unroll") for (int k = 0; k < 2; ++k) dst[m][k] = *(const PG8_LAS bf16x8*)(lds + PG8_SA(b, h) + aoff + m * 2048 + k * 1024); } while (0)
; #define PG8_LDB(dst, b, h) do { _Pragma("unroll") for (int n = 0; n < 2; ++n) _Pragma("unroll") for (int k = 0; k < 2; ++k) dst[n][k] = *(const PG8_LAS bf16x8*)(lds + PG8_SB(b, h) + boff + n * 2048 + k * 1024); } while (0)
; #define PG8_MMA(ai, bj, At, Bt) do { __builtin_amdgcn_s_setprio(1); _Pragma("unroll") for (int m = 0; m < 4; ++m) _Pragma("unroll") for (int n = 0; n < 2; ++n) _Pragma("unroll") for (int k = 0; k < 2; ++k) \
;         acc[ai][bj][m][n] = __builtin_amdgcn_mfma_f32_16x16x32_bf16(Bt[n][k], At[m][k], acc[ai][bj][m][n], 0, 0, 0); __builtin_amdgcn_s_setprio(0); } while (0)
; #define PG8_WAIT_V(n) asm volatile("s_waitcnt vmcnt(" #n ")" ::: "memory")
; #define PG8_BAR __builtin_amdgcn_s_barrier()
; template <class Epi, class Sched, bool ALIGN_EPI = false, bool SP2 = false>
; __device__ __forceinline__ void gemm_phase(PG8_LAS unsigned char* lds, const Gemm g, const Sched& S, const Epi& E) {
;     ...
;         for (int t = 0; t < nt; t += 2) {
;             const bool last = (t == nt - 2);
;             const char* a1 = cA + (size_t)(t + 1) * kstep;
;             const char* a2 = last ? nA : cA + (size_t)(t + 2) * kstep; const char* b2 = last ? nB : cB + (size_t)(t + 2) * kstep;
;             const char* a3 = a2 + kstep; const char* b3 = b2 + kstep;
;             if (last && has_next) S.a_ready(nxt);
;             if constexpr (SP2) {
;             PG8_LDB(B0, 0, 0); PG8_LDB(B1, 0, 1); PG8_SCHED; PG8_LDA(At, 0, 0); PG8_STAGE(PG8_SA(1, 1), a1 + hstep, voffA);
;             PG8_WAIT_V(8); PG8_WAIT_L(0); PG8_BAR; PG8_MMA(0, 0, At, B0); PG8_MMA(0, 1, At, B1); PG8_BAR; PG8_SCHED;
;             PG8_LDA(At, 0, 1); PG8_STAGE(PG8_SB(0, 0), b2, voffB); PG8_STAGE(PG8_SB(0, 1), b2 + hstep, voffB); PG8_STAGE(PG8_SA(0, 0), a2, voffA);
;             PG8_WAIT_V(8); PG8_WAIT_L(0); PG8_BAR; PG8_MMA(1, 0, At, B0); PG8_MMA(1, 1, At, B1); PG8_BAR; PG8_SCHED;
.LBB0_545:
	ds_read_b128 v[128:131], v254
	ds_read_b128 v[132:135], v254 offset:1024
	ds_read_b128 v[136:139], v254 offset:2048
	ds_read_b128 v[140:143], v254 offset:3072
	ds_read_b128 v[174:177], v254 offset:16384
	ds_read_b128 v[184:187], v254 offset:17408
	ds_read_b128 v[188:191], v254 offset:18432
	ds_read_b128 v[210:213], v254 offset:19456
	s_add_u32 s2, s0, 0x100
	s_addc_u32 s3, s1, 0
	s_cmp_eq_u32 s13, 40
	s_cselect_b32 s7, s27, s3
	s_cselect_b32 s6, s26, s2
	s_cselect_b32 s5, s37, s11
	s_cselect_b32 s4, s36, s10
	s_add_i32 m0, s29, 0xc000
	ds_read_b128 v[214:217], v181
	ds_read_b128 v[218:221], v181 offset:1024
	ds_read_b128 v[222:225], v181 offset:2048
	ds_read_b128 v[226:229], v181 offset:3072
	ds_read_b128 v[230:233], v181 offset:4096
	ds_read_b128 v[234:237], v181 offset:5120
	ds_read_b128 v[238:241], v181 offset:6144
	ds_read_b128 v[242:245], v181 offset:7168
	global_load_lds_dwordx4 v170, s[0:1]
	s_add_i32 m0, s29, 0xe000
	s_nop 0
	global_load_lds_dwordx4 v172, s[0:1]
	s_waitcnt vmcnt(8)
	s_waitcnt lgkmcnt(0)
	s_barrier
	s_setprio 1
	v_mfma_f32_16x16x32_bf16 v[124:127], v[128:131], v[214:217], v[124:127]
	v_mfma_f32_16x16x32_bf16 v[120:123], v[136:139], v[214:217], v[120:123]
	v_mfma_f32_16x16x32_bf16 v[116:119], v[174:177], v[214:217], v[116:119]
	v_mfma_f32_16x16x32_bf16 v[112:115], v[188:191], v[214:217], v[112:115]
	v_mfma_f32_16x16x32_bf16 v[108:111], v[128:131], v[222:225], v[108:111]
	v_mfma_f32_16x16x32_bf16 v[104:107], v[136:139], v[222:225], v[104:107]
	v_mfma_f32_16x16x32_bf16 v[100:103], v[174:177], v[222:225], v[100:103]
	v_mfma_f32_16x16x32_bf16 v[96:99], v[188:191], v[222:225], v[96:99]
	v_mfma_f32_16x16x32_bf16 v[92:95], v[128:131], v[230:233], v[92:95]
	v_mfma_f32_16x16x32_bf16 v[88:91], v[136:139], v[230:233], v[88:91]
	v_mfma_f32_16x16x32_bf16 v[84:87], v[174:177], v[230:233], v[84:87]
	v_mfma_f32_16x16x32_bf16 v[80:83], v[188:191], v[230:233], v[80:83]
	v_mfma_f32_16x16x32_bf16 v[76:79], v[128:131], v[238:241], v[76:79]
	v_mfma_f32_16x16x32_bf16 v[72:75], v[136:139], v[238:241], v[72:75]
	v_mfma_f32_16x16x32_bf16 v[68:71], v[174:177], v[238:241], v[68:71]
	v_mfma_f32_16x16x32_bf16 v[64:67], v[188:191], v[238:241], v[64:67]
	v_mfma_f32_16x16x32_bf16 v[124:127], v[132:135], v[218:221], v[124:127]
	v_mfma_f32_16x16x32_bf16 v[120:123], v[140:143], v[218:221], v[120:123]
	v_mfma_f32_16x16x32_bf16 v[116:119], v[184:187], v[218:221], v[116:119]
	v_mfma_f32_16x16x32_bf16 v[112:115], v[210:213], v[218:221], v[112:115]
	v_mfma_f32_16x16x32_bf16 v[108:111], v[132:135], v[226:229], v[108:111]
	v_mfma_f32_16x16x32_bf16 v[104:107], v[140:143], v[226:229], v[104:107]
	v_mfma_f32_16x16x32_bf16 v[100:103], v[184:187], v[226:229], v[100:103]
	v_mfma_f32_16x16x32_bf16 v[96:99], v[210:213], v[226:229], v[96:99]
	v_mfma_f32_16x16x32_bf16 v[92:95], v[132:135], v[234:237], v[92:95]
	v_mfma_f32_16x16x32_bf16 v[88:91], v[140:143], v[234:237], v[88:91]
	v_mfma_f32_16x16x32_bf16 v[84:87], v[184:187], v[234:237], v[84:87]
	v_mfma_f32_16x16x32_bf16 v[80:83], v[210:213], v[234:237], v[80:83]
	v_mfma_f32_16x16x32_bf16 v[76:79], v[132:135], v[242:245], v[76:79]
	v_mfma_f32_16x16x32_bf16 v[72:75], v[140:143], v[242:245], v[72:75]
	v_mfma_f32_16x16x32_bf16 v[68:71], v[184:187], v[242:245], v[68:71]
	v_mfma_f32_16x16x32_bf16 v[64:67], v[210:213], v[242:245], v[64:67]
	s_setprio 0
	s_barrier
	s_mov_b32 m0, s35
	s_add_u32 s0, s4, 0xb0000
	s_addc_u32 s1, s5, 0
	ds_read_b128 v[214:217], v181 offset:16384
	ds_read_b128 v[218:221], v181 offset:17408
	ds_read_b128 v[222:225], v181 offset:18432
	ds_read_b128 v[226:229], v181 offset:19456
	ds_read_b128 v[230:233], v181 offset:20480
	ds_read_b128 v[234:237], v181 offset:21504
	ds_read_b128 v[238:241], v181 offset:22528
	ds_read_b128 v[242:245], v181 offset:23552
	global_load_lds_dwordx4 v166, s[4:5]
	s_mov_b32 m0, s38
	s_nop 0
	global_load_lds_dwordx4 v162, s[4:5]
	s_mov_b32 m0, s39
	s_nop 0
	global_load_lds_dwordx4 v166, s[0:1]
	s_mov_b32 m0, s40
	s_nop 0
	global_load_lds_dwordx4 v162, s[0:1]
	s_mov_b32 m0, s29
	s_nop 0
	global_load_lds_dwordx4 v168, s[6:7]
	s_mov_b32 m0, s41
	s_nop 0
	global_load_lds_dwordx4 v164, s[6:7]
	s_waitcnt vmcnt(8)
	s_waitcnt lgkmcnt(0)
	s_barrier
	s_setprio 1
	v_mfma_f32_16x16x32_bf16 v[60:63], v[128:131], v[214:217], v[60:63]
	v_mfma_f32_16x16x32_bf16 v[56:59], v[136:139], v[214:217], v[56:59]
	v_mfma_f32_16x16x32_bf16 v[52:55], v[174:177], v[214:217], v[52:55]
	v_mfma_f32_16x16x32_bf16 v[48:51], v[188:191], v[214:217], v[48:51]
	v_mfma_f32_16x16x32_bf16 v[44:47], v[128:131], v[222:225], v[44:47]
	v_mfma_f32_16x16x32_bf16 v[40:43], v[136:139], v[222:225], v[40:43]
	v_mfma_f32_16x16x32_bf16 v[36:39], v[174:177], v[222:225], v[36:39]
	v_mfma_f32_16x16x32_bf16 v[32:35], v[188:191], v[222:225], v[32:35]
	v_mfma_f32_16x16x32_bf16 v[28:31], v[128:131], v[230:233], v[28:31]
	v_mfma_f32_16x16x32_bf16 v[24:27], v[136:139], v[230:233], v[24:27]
	v_mfma_f32_16x16x32_bf16 v[20:23], v[174:177], v[230:233], v[20:23]
	v_mfma_f32_16x16x32_bf16 v[16:19], v[188:191], v[230:233], v[16:19]
	v_mfma_f32_16x16x32_bf16 v[12:15], v[128:131], v[238:241], v[12:15]
	v_mfma_f32_16x16x32_bf16 v[8:11], v[136:139], v[238:241], v[8:11]
	v_mfma_f32_16x16x32_bf16 v[4:7], v[174:177], v[238:241], v[4:7]
	v_mfma_f32_16x16x32_bf16 v[0:3], v[188:191], v[238:241], v[0:3]
	v_mfma_f32_16x16x32_bf16 v[60:63], v[132:135], v[218:221], v[60:63]
	v_mfma_f32_16x16x32_bf16 v[56:59], v[140:143], v[218:221], v[56:59]
	v_mfma_f32_16x16x32_bf16 v[52:55], v[184:187], v[218:221], v[52:55]
	v_mfma_f32_16x16x32_bf16 v[48:51], v[210:213], v[218:221], v[48:51]
	v_mfma_f32_16x16x32_bf16 v[44:47], v[132:135], v[226:229], v[44:47]
	v_mfma_f32_16x16x32_bf16 v[40:43], v[140:143], v[226:229], v[40:43]
	v_mfma_f32_16x16x32_bf16 v[36:39], v[184:187], v[226:229], v[36:39]
	v_mfma_f32_16x16x32_bf16 v[32:35], v[210:213], v[226:229], v[32:35]
	v_mfma_f32_16x16x32_bf16 v[28:31], v[132:135], v[234:237], v[28:31]
	v_mfma_f32_16x16x32_bf16 v[24:27], v[140:143], v[234:237], v[24:27]
	v_mfma_f32_16x16x32_bf16 v[20:23], v[184:187], v[234:237], v[20:23]
	v_mfma_f32_16x16x32_bf16 v[16:19], v[210:213], v[234:237], v[16:19]
	v_mfma_f32_16x16x32_bf16 v[12:15], v[132:135], v[242:245], v[12:15]
	v_mfma_f32_16x16x32_bf16 v[8:11], v[140:143], v[242:245], v[8:11]
	v_mfma_f32_16x16x32_bf16 v[4:7], v[184:187], v[242:245], v[4:7]
	v_mfma_f32_16x16x32_bf16 v[0:3], v[210:213], v[242:245], v[0:3]
	s_setprio 0
	s_barrier
; #define PG8_STAGE(bufoff, gbase, voff) do { _Pragma("unroll") for (int _i = 0; _i < 2; ++_i) \
;         __builtin_amdgcn_global_load_lds((const unsigned*)((const char*)(gbase) + (voff)[_i]), (PG8_LAS unsigned*)(lds + (bufoff) + ldsw + _i * 8192), 16, 0, 0); } while (0)
; #define PG8_LDA(dst, b, h) do { _Pragma("unroll") for (int m = 0; m < 4; ++m) _Pragma("unroll") for (int k = 0; k < 2; ++k) dst[m][k] = *(const PG8_LAS bf16x8*)(lds + PG8_SA(b, h) + aoff + m * 2048 + k * 1024); } while (0)
; #define PG8_LDB(dst, b, h) do { _Pragma("unroll") for (int n = 0; n < 2; ++n) _Pragma("unroll") for (int k = 0; k < 2; ++k) dst[n][k] = *(const PG8_LAS bf16x8*)(lds + PG8_SB(b, h) + boff + n * 2048 + k * 1024); } while (0)
; #define PG8_MMA(ai, bj, At, Bt) do { __builtin_amdgcn_s_setprio(1); _Pragma("unroll") for (int m = 0; m < 4; ++m) _Pragma("unroll") for (int n = 0; n < 2; ++n) _Pragma("unroll") for (int k = 0; k < 2; ++k) \
;         acc[ai][bj][m][n] = __builtin_amdgcn_mfma_f32_16x16x32_bf16(Bt[n][k], At[m][k], acc[ai][bj][m][n], 0, 0, 0); __builtin_amdgcn_s_setprio(0); } while (0)
; #define PG8_WAIT_V(n) asm volatile("s_waitcnt vmcnt(" #n ")" ::: "memory")
; #define PG8_WAIT_L(n) asm volatile("s_waitcnt lgkmcnt(" #n ")" ::: "memory")
; #define PG8_BAR __builtin_amdgcn_s_barrier()
; template <class Epi, class Sched, bool ALIGN_EPI = false, bool SP2 = false>
; __device__ __forceinline__ void gemm_phase(PG8_LAS unsigned char* lds, const Gemm g, const Sched& S, const Epi& E) {
;     ...
;         for (int t = 0; t < nt; t += 2) {
;             const bool last = (t == nt - 2);
;             const char* a1 = cA + (size_t)(t + 1) * kstep;
;             const char* a2 = last ? nA : cA + (size_t)(t + 2) * kstep; const char* b2 = last ? nB : cB + (size_t)(t + 2) * kstep;
;             const char* a3 = a2 + kstep; const char* b3 = b2 + kstep;
;     ...
;             PG8_LDB(B0, 1, 0); PG8_LDB(B1, 1, 1); PG8_SCHED; PG8_LDA(At, 1, 0); PG8_STAGE(PG8_SA(0, 1), a2 + hstep, voffA);
;             PG8_WAIT_V(8); PG8_WAIT_L(0); PG8_BAR; PG8_MMA(0, 0, At, B0); PG8_MMA(0, 1, At, B1); PG8_BAR; PG8_SCHED;
;             PG8_LDA(At, 1, 1); PG8_STAGE(PG8_SB(1, 0), b3, voffB); PG8_STAGE(PG8_SB(1, 1), b3 + hstep, voffB); PG8_STAGE(PG8_SA(1, 0), a3, voffA);
;             PG8_WAIT_V(8); PG8_WAIT_L(0); PG8_BAR; PG8_MMA(1, 0, At, B0); PG8_MMA(1, 1, At, B1); PG8_BAR; PG8_SCHED;
	ds_read_b128 v[128:131], v254 offset:32768
	ds_read_b128 v[132:135], v254 offset:33792
	ds_read_b128 v[136:139], v254 offset:34816
	ds_read_b128 v[140:143], v254 offset:35840
	ds_read_b128 v[174:177], v254 offset:49152
	ds_read_b128 v[184:187], v254 offset:50176
	ds_read_b128 v[188:191], v254 offset:51200
	ds_read_b128 v[210:213], v254 offset:52224
	s_add_u32 s0, s6, 0xb0000
	s_addc_u32 s1, s7, 0
	s_mov_b32 m0, s42
	ds_read_b128 v[214:217], v181 offset:32768
	ds_read_b128 v[218:221], v181 offset:33792
	ds_read_b128 v[222:225], v181 offset:34816
	ds_read_b128 v[226:229], v181 offset:35840
	ds_read_b128 v[230:233], v181 offset:36864
	ds_read_b128 v[234:237], v181 offset:37888
	ds_read_b128 v[238:241], v181 offset:38912
	ds_read_b128 v[242:245], v181 offset:39936
	global_load_lds_dwordx4 v168, s[0:1]
	s_mov_b32 m0, s43
	s_nop 0
	global_load_lds_dwordx4 v164, s[0:1]
	s_waitcnt vmcnt(8)
	s_waitcnt lgkmcnt(0)
	s_barrier
	s_setprio 1
	v_mfma_f32_16x16x32_bf16 v[124:127], v[128:131], v[214:217], v[124:127]
	v_mfma_f32_16x16x32_bf16 v[120:123], v[136:139], v[214:217], v[120:123]
	v_mfma_f32_16x16x32_bf16 v[116:119], v[174:177], v[214:217], v[116:119]
	v_mfma_f32_16x16x32_bf16 v[112:115], v[188:191], v[214:217], v[112:115]
	v_mfma_f32_16x16x32_bf16 v[108:111], v[128:131], v[222:225], v[108:111]
	v_mfma_f32_16x16x32_bf16 v[104:107], v[136:139], v[222:225], v[104:107]
	v_mfma_f32_16x16x32_bf16 v[100:103], v[174:177], v[222:225], v[100:103]
	v_mfma_f32_16x16x32_bf16 v[96:99], v[188:191], v[222:225], v[96:99]
	v_mfma_f32_16x16x32_bf16 v[92:95], v[128:131], v[230:233], v[92:95]
	v_mfma_f32_16x16x32_bf16 v[88:91], v[136:139], v[230:233], v[88:91]
	v_mfma_f32_16x16x32_bf16 v[84:87], v[174:177], v[230:233], v[84:87]
	v_mfma_f32_16x16x32_bf16 v[80:83], v[188:191], v[230:233], v[80:83]
	v_mfma_f32_16x16x32_bf16 v[76:79], v[128:131], v[238:241], v[76:79]
	v_mfma_f32_16x16x32_bf16 v[72:75], v[136:139], v[238:241], v[72:75]
	v_mfma_f32_16x16x32_bf16 v[68:71], v[174:177], v[238:241], v[68:71]
	v_mfma_f32_16x16x32_bf16 v[64:67], v[188:191], v[238:241], v[64:67]
	v_mfma_f32_16x16x32_bf16 v[124:127], v[132:135], v[218:221], v[124:127]
	v_mfma_f32_16x16x32_bf16 v[120:123], v[140:143], v[218:221], v[120:123]
	v_mfma_f32_16x16x32_bf16 v[116:119], v[184:187], v[218:221], v[116:119]
	v_mfma_f32_16x16x32_bf16 v[112:115], v[210:213], v[218:221], v[112:115]
	v_mfma_f32_16x16x32_bf16 v[108:111], v[132:135], v[226:229], v[108:111]
	v_mfma_f32_16x16x32_bf16 v[104:107], v[140:143], v[226:229], v[104:107]
	v_mfma_f32_16x16x32_bf16 v[100:103], v[184:187], v[226:229], v[100:103]
	v_mfma_f32_16x16x32_bf16 v[96:99], v[210:213], v[226:229], v[96:99]
	v_mfma_f32_16x16x32_bf16 v[92:95], v[132:135], v[234:237], v[92:95]
	v_mfma_f32_16x16x32_bf16 v[88:91], v[140:143], v[234:237], v[88:91]
	v_mfma_f32_16x16x32_bf16 v[84:87], v[184:187], v[234:237], v[84:87]
	v_mfma_f32_16x16x32_bf16 v[80:83], v[210:213], v[234:237], v[80:83]
	v_mfma_f32_16x16x32_bf16 v[76:79], v[132:135], v[242:245], v[76:79]
	v_mfma_f32_16x16x32_bf16 v[72:75], v[140:143], v[242:245], v[72:75]
	v_mfma_f32_16x16x32_bf16 v[68:71], v[184:187], v[242:245], v[68:71]
	v_mfma_f32_16x16x32_bf16 v[64:67], v[210:213], v[242:245], v[64:67]
	s_setprio 0
	s_barrier
	s_mov_b32 m0, s47
	s_add_u32 s0, s4, 0xb0080
	s_addc_u32 s1, s5, 0
	ds_read_b128 v[214:217], v181 offset:49152
	ds_read_b128 v[218:221], v181 offset:50176
	ds_read_b128 v[222:225], v181 offset:51200
	ds_read_b128 v[226:229], v181 offset:52224
	ds_read_b128 v[230:233], v181 offset:53248
	ds_read_b128 v[234:237], v181 offset:54272
	ds_read_b128 v[238:241], v181 offset:55296
	ds_read_b128 v[242:245], v181 offset:56320
	s_add_u32 s98, s4, 0x80
	s_addc_u32 s99, s5, 0
	global_load_lds_dwordx4 v166, s[98:99]
	s_mov_b32 m0, s48
	s_nop 0
	global_load_lds_dwordx4 v162, s[98:99]
	s_mov_b32 m0, s51
	s_nop 0
	global_load_lds_dwordx4 v166, s[0:1]
	s_mov_b32 m0, s52
	s_nop 0
	global_load_lds_dwordx4 v162, s[0:1]
	s_mov_b32 m0, s49
	s_nop 0
	s_add_u32 s100, s6, 0x80
	s_addc_u32 s101, s7, 0
	global_load_lds_dwordx4 v168, s[100:101]
	s_mov_b32 m0, s50
	s_nop 0
	global_load_lds_dwordx4 v164, s[100:101]
	s_waitcnt vmcnt(8)
	s_waitcnt lgkmcnt(0)
	s_barrier
	s_setprio 1
	v_mfma_f32_16x16x32_bf16 v[60:63], v[128:131], v[214:217], v[60:63]
	v_mfma_f32_16x16x32_bf16 v[56:59], v[136:139], v[214:217], v[56:59]
	v_mfma_f32_16x16x32_bf16 v[52:55], v[174:177], v[214:217], v[52:55]
	v_mfma_f32_16x16x32_bf16 v[48:51], v[188:191], v[214:217], v[48:51]
	v_mfma_f32_16x16x32_bf16 v[44:47], v[128:131], v[222:225], v[44:47]
	v_mfma_f32_16x16x32_bf16 v[40:43], v[136:139], v[222:225], v[40:43]
	v_mfma_f32_16x16x32_bf16 v[36:39], v[174:177], v[222:225], v[36:39]
	v_mfma_f32_16x16x32_bf16 v[32:35], v[188:191], v[222:225], v[32:35]
	v_mfma_f32_16x16x32_bf16 v[28:31], v[128:131], v[230:233], v[28:31]
	v_mfma_f32_16x16x32_bf16 v[24:27], v[136:139], v[230:233], v[24:27]
	v_mfma_f32_16x16x32_bf16 v[20:23], v[174:177], v[230:233], v[20:23]
	v_mfma_f32_16x16x32_bf16 v[16:19], v[188:191], v[230:233], v[16:19]
	v_mfma_f32_16x16x32_bf16 v[12:15], v[128:131], v[238:241], v[12:15]
	v_mfma_f32_16x16x32_bf16 v[8:11], v[136:139], v[238:241], v[8:11]
	v_mfma_f32_16x16x32_bf16 v[4:7], v[174:177], v[238:241], v[4:7]
	v_mfma_f32_16x16x32_bf16 v[0:3], v[188:191], v[238:241], v[0:3]
	v_mfma_f32_16x16x32_bf16 v[60:63], v[132:135], v[218:221], v[60:63]
	v_mfma_f32_16x16x32_bf16 v[56:59], v[140:143], v[218:221], v[56:59]
	v_mfma_f32_16x16x32_bf16 v[52:55], v[184:187], v[218:221], v[52:55]
	v_mfma_f32_16x16x32_bf16 v[48:51], v[210:213], v[218:221], v[48:51]
	v_mfma_f32_16x16x32_bf16 v[44:47], v[132:135], v[226:229], v[44:47]
	v_mfma_f32_16x16x32_bf16 v[40:43], v[140:143], v[226:229], v[40:43]
	v_mfma_f32_16x16x32_bf16 v[36:39], v[184:187], v[226:229], v[36:39]
	v_mfma_f32_16x16x32_bf16 v[32:35], v[210:213], v[226:229], v[32:35]
	v_mfma_f32_16x16x32_bf16 v[28:31], v[132:135], v[234:237], v[28:31]
	v_mfma_f32_16x16x32_bf16 v[24:27], v[140:143], v[234:237], v[24:27]
	v_mfma_f32_16x16x32_bf16 v[20:23], v[184:187], v[234:237], v[20:23]
	v_mfma_f32_16x16x32_bf16 v[16:19], v[210:213], v[234:237], v[16:19]
	v_mfma_f32_16x16x32_bf16 v[12:15], v[132:135], v[242:245], v[12:15]
	v_mfma_f32_16x16x32_bf16 v[8:11], v[140:143], v[242:245], v[8:11]
	v_mfma_f32_16x16x32_bf16 v[4:7], v[184:187], v[242:245], v[4:7]
	v_mfma_f32_16x16x32_bf16 v[0:3], v[210:213], v[242:245], v[0:3]
	s_setprio 0
	s_barrier
	s_add_i32 s13, s13, 2
	s_add_u32 s10, s10, 0x100
	s_addc_u32 s11, s11, 0
	s_cmp_gt_u32 s13, 41
	s_mov_b64 s[0:1], s[2:3]
	s_cbranch_scc0 .LBB0_545
	s_and_b64 vcc, exec, s[22:23]
	s_cbranch_vccz .LBB0_548
	s_barrier

; #define PG8_STAGE(bufoff, gbase, voff) do { _Pragma("unroll") for (int _i = 0; _i < 2; ++_i) \
;         __builtin_amdgcn_global_load_lds((const unsigned*)((const char*)(gbase) + (voff)[_i]), (PG8_LAS unsigned*)(lds + (bufoff) + ldsw + _i * 8192), 16, 0, 0); } while (0)
; #define PG8_LDA(dst, b, h) do { _Pragma("unroll") for (int m = 0; m < 4; ++m) _Pragma("unroll") for (int k = 0; k < 2; ++k) dst[m][k] = *(const PG8_LAS bf16x8*)(lds + PG8_SA(b, h) + aoff + m * 2048 + k * 1024); } while (0)
; #define PG8_LDB(dst, b, h) do { _Pragma("unroll") for (int n = 0; n < 2; ++n) _Pragma("unroll") for (int k = 0; k < 2; ++k) dst[n][k] = *(const PG8_LAS bf16x8*)(lds + PG8_SB(b, h) + boff + n * 2048 + k * 1024); } while (0)
; #define PG8_WAIT_V(n) asm volatile("s_waitcnt vmcnt(" #n ")" ::: "memory")
; #define PG8_WAIT_L(n) asm volatile("s_waitcnt lgkmcnt(" #n ")" ::: "memory")
; #define PG8_BAR __builtin_amdgcn_s_barrier()
; #define PG8_SCHED __builtin_amdgcn_sched_barrier(0)
; template <class Epi, class Sched, bool ALIGN_EPI = false, bool SP2 = false>
; __device__ __forceinline__ void gemm_phase(PG8_LAS unsigned char* lds, const Gemm g, const Sched& S, const Epi& E) {
;     ...
;     for (;;) {
;         const bool has_next = S.next(ui + 1, nxt);
;         const char* nA = has_next ? (const char*)g.A + (size_t)nxt.pm * tstep : cA; const char* nB = has_next ? (const char*)g.Bt + (size_t)nxt.pn * tstep : cB;
;         for (int t = 0; t < nt; t += 2) {
;             const bool last = (t == nt - 2);
;             const char* a1 = cA + (size_t)(t + 1) * kstep;
;             const char* a2 = last ? nA : cA + (size_t)(t + 2) * kstep; const char* b2 = last ? nB : cB + (size_t)(t + 2) * kstep;
;             const char* a3 = a2 + kstep; const char* b3 = b2 + kstep;
;             if (last && has_next) S.a_ready(nxt);
;             if constexpr (SP2) {
;             PG8_LDB(B0, 0, 0); PG8_LDB(B1, 0, 1); PG8_SCHED; PG8_LDA(At, 0, 0); PG8_STAGE(PG8_SA(1, 1), a1 + hstep, voffA);
;             PG8_WAIT_V(8); PG8_WAIT_L(0); PG8_BAR; PG8_MMA(0, 0, At, B0); PG8_MMA(0, 1, At, B1); PG8_BAR; PG8_SCHED;
;             PG8_LDA(At, 0, 1); PG8_STAGE(PG8_SB(0, 0), b2, voffB); PG8_STAGE(PG8_SB(0, 1), b2 + hstep, voffB); PG8_STAGE(PG8_SA(0, 0), a2, voffA);
;             PG8_WAIT_V(8); PG8_WAIT_L(0); PG8_BAR; PG8_MMA(1, 0, At, B0); PG8_MMA(1, 1, At, B1); PG8_BAR; PG8_SCHED;
.Lsgi_peel:
	ds_read_b128 v[140:143], v254
	ds_read_b128 v[162:165], v254 offset:1024
	ds_read_b128 v[166:169], v254 offset:2048
	ds_read_b128 v[170:173], v254 offset:3072
	ds_read_b128 v[180:183], v254 offset:16384
	ds_read_b128 v[184:187], v254 offset:17408
	ds_read_b128 v[188:191], v254 offset:18432
	ds_read_b128 v[210:213], v254 offset:19456
	s_add_u32 s2, s0, 0xfffc0080
	s_addc_u32 s3, s1, -1
	s_cmp_eq_u32 s55, 12
	s_cselect_b32 s5, s13, s3
	s_cselect_b32 s4, s25, s2
	s_cselect_b32 s3, s23, s39
	s_cselect_b32 s2, s33, s38
	s_add_i32 m0, s6, 0xc000
	ds_read_b128 v[214:217], v178
	ds_read_b128 v[218:221], v178 offset:1024
	ds_read_b128 v[222:225], v178 offset:2048
	ds_read_b128 v[226:229], v178 offset:3072
	ds_read_b128 v[230:233], v178 offset:4096
	ds_read_b128 v[234:237], v178 offset:5120
	ds_read_b128 v[238:241], v178 offset:6144
	ds_read_b128 v[242:245], v178 offset:7168
	global_load_lds_dwordx4 v136, s[0:1]
	s_add_i32 m0, s6, 0xe000
	s_nop 0
	global_load_lds_dwordx4 v138, s[0:1]
	s_waitcnt vmcnt(8)
	s_waitcnt lgkmcnt(0)
	s_barrier
	s_setprio 1
	v_mfma_f32_16x16x32_bf16 v[124:127], v[140:143], v[214:217], 0
	v_mfma_f32_16x16x32_bf16 v[120:123], v[166:169], v[214:217], 0
	v_mfma_f32_16x16x32_bf16 v[116:119], v[180:183], v[214:217], 0
	v_mfma_f32_16x16x32_bf16 v[112:115], v[188:191], v[214:217], 0
	v_mfma_f32_16x16x32_bf16 v[108:111], v[140:143], v[222:225], 0
	v_mfma_f32_16x16x32_bf16 v[104:107], v[166:169], v[222:225], 0
	v_mfma_f32_16x16x32_bf16 v[100:103], v[180:183], v[222:225], 0
	v_mfma_f32_16x16x32_bf16 v[96:99], v[188:191], v[222:225], 0
	v_mfma_f32_16x16x32_bf16 v[92:95], v[140:143], v[230:233], 0
	v_mfma_f32_16x16x32_bf16 v[88:91], v[166:169], v[230:233], 0
	v_mfma_f32_16x16x32_bf16 v[84:87], v[180:183], v[230:233], 0
	v_mfma_f32_16x16x32_bf16 v[80:83], v[188:191], v[230:233], 0
	v_mfma_f32_16x16x32_bf16 v[76:79], v[140:143], v[238:241], 0
	v_mfma_f32_16x16x32_bf16 v[72:75], v[166:169], v[238:241], 0
	v_mfma_f32_16x16x32_bf16 v[68:71], v[180:183], v[238:241], 0
	v_mfma_f32_16x16x32_bf16 v[64:67], v[188:191], v[238:241], 0
	v_mfma_f32_16x16x32_bf16 v[124:127], v[162:165], v[218:221], v[124:127]
	v_mfma_f32_16x16x32_bf16 v[120:123], v[170:173], v[218:221], v[120:123]
	v_mfma_f32_16x16x32_bf16 v[116:119], v[184:187], v[218:221], v[116:119]
	v_mfma_f32_16x16x32_bf16 v[112:115], v[210:213], v[218:221], v[112:115]
	v_mfma_f32_16x16x32_bf16 v[108:111], v[162:165], v[226:229], v[108:111]
	v_mfma_f32_16x16x32_bf16 v[104:107], v[170:173], v[226:229], v[104:107]
	v_mfma_f32_16x16x32_bf16 v[100:103], v[184:187], v[226:229], v[100:103]
	v_mfma_f32_16x16x32_bf16 v[96:99], v[210:213], v[226:229], v[96:99]
	v_mfma_f32_16x16x32_bf16 v[92:95], v[162:165], v[234:237], v[92:95]
	v_mfma_f32_16x16x32_bf16 v[88:91], v[170:173], v[234:237], v[88:91]
	v_mfma_f32_16x16x32_bf16 v[84:87], v[184:187], v[234:237], v[84:87]
	v_mfma_f32_16x16x32_bf16 v[80:83], v[210:213], v[234:237], v[80:83]
	v_mfma_f32_16x16x32_bf16 v[76:79], v[162:165], v[242:245], v[76:79]
	v_mfma_f32_16x16x32_bf16 v[72:75], v[170:173], v[242:245], v[72:75]
	v_mfma_f32_16x16x32_bf16 v[68:71], v[184:187], v[242:245], v[68:71]
	v_mfma_f32_16x16x32_bf16 v[64:67], v[210:213], v[242:245], v[64:67]
	s_setprio 0
	s_barrier
	s_mov_b32 m0, s31
	s_add_u32 s56, s2, 0x40000
	s_addc_u32 s57, s3, 0
	ds_read_b128 v[214:217], v178 offset:16384
	ds_read_b128 v[218:221], v178 offset:17408
	ds_read_b128 v[222:225], v178 offset:18432
	ds_read_b128 v[226:229], v178 offset:19456
	ds_read_b128 v[230:233], v178 offset:20480
	ds_read_b128 v[234:237], v178 offset:21504
	ds_read_b128 v[238:241], v178 offset:22528
	ds_read_b128 v[242:245], v178 offset:23552
	global_load_lds_dwordx4 v132, s[2:3]
	s_mov_b32 m0, s34
	s_nop 0
	global_load_lds_dwordx4 v128, s[2:3]
	s_mov_b32 m0, s35
	s_nop 0
	global_load_lds_dwordx4 v132, s[56:57]
	s_mov_b32 m0, s40
	s_nop 0
	global_load_lds_dwordx4 v128, s[56:57]
	s_mov_b32 m0, s6
	s_nop 0
	global_load_lds_dwordx4 v134, s[4:5]
	s_mov_b32 m0, s41
	s_nop 0
	global_load_lds_dwordx4 v130, s[4:5]
	s_waitcnt vmcnt(8)
	s_waitcnt lgkmcnt(0)
	s_barrier
	s_setprio 1
	v_mfma_f32_16x16x32_bf16 v[60:63], v[140:143], v[214:217], 0
	v_mfma_f32_16x16x32_bf16 v[56:59], v[166:169], v[214:217], 0
	v_mfma_f32_16x16x32_bf16 v[52:55], v[180:183], v[214:217], 0
	v_mfma_f32_16x16x32_bf16 v[48:51], v[188:191], v[214:217], 0
	v_mfma_f32_16x16x32_bf16 v[44:47], v[140:143], v[222:225], 0
	v_mfma_f32_16x16x32_bf16 v[40:43], v[166:169], v[222:225], 0
	v_mfma_f32_16x16x32_bf16 v[36:39], v[180:183], v[222:225], 0
	v_mfma_f32_16x16x32_bf16 v[32:35], v[188:191], v[222:225], 0
	v_mfma_f32_16x16x32_bf16 v[28:31], v[140:143], v[230:233], 0
	v_mfma_f32_16x16x32_bf16 v[24:27], v[166:169], v[230:233], 0
	v_mfma_f32_16x16x32_bf16 v[20:23], v[180:183], v[230:233], 0
	v_mfma_f32_16x16x32_bf16 v[16:19], v[188:191], v[230:233], 0
	v_mfma_f32_16x16x32_bf16 v[12:15], v[140:143], v[238:241], 0
	v_mfma_f32_16x16x32_bf16 v[8:11], v[166:169], v[238:241], 0
	v_mfma_f32_16x16x32_bf16 v[4:7], v[180:183], v[238:241], 0
	v_mfma_f32_16x16x32_bf16 v[0:3], v[188:191], v[238:241], 0
	v_mfma_f32_16x16x32_bf16 v[60:63], v[162:165], v[218:221], v[60:63]
	v_mfma_f32_16x16x32_bf16 v[56:59], v[170:173], v[218:221], v[56:59]
	v_mfma_f32_16x16x32_bf16 v[52:55], v[184:187], v[218:221], v[52:55]
	v_mfma_f32_16x16x32_bf16 v[48:51], v[210:213], v[218:221], v[48:51]
	v_mfma_f32_16x16x32_bf16 v[44:47], v[162:165], v[226:229], v[44:47]
	v_mfma_f32_16x16x32_bf16 v[40:43], v[170:173], v[226:229], v[40:43]
	v_mfma_f32_16x16x32_bf16 v[36:39], v[184:187], v[226:229], v[36:39]
	v_mfma_f32_16x16x32_bf16 v[32:35], v[210:213], v[226:229], v[32:35]
	v_mfma_f32_16x16x32_bf16 v[28:31], v[162:165], v[234:237], v[28:31]
	v_mfma_f32_16x16x32_bf16 v[24:27], v[170:173], v[234:237], v[24:27]
	v_mfma_f32_16x16x32_bf16 v[20:23], v[184:187], v[234:237], v[20:23]
	v_mfma_f32_16x16x32_bf16 v[16:19], v[210:213], v[234:237], v[16:19]
	v_mfma_f32_16x16x32_bf16 v[12:15], v[162:165], v[242:245], v[12:15]
	v_mfma_f32_16x16x32_bf16 v[8:11], v[170:173], v[242:245], v[8:11]
	v_mfma_f32_16x16x32_bf16 v[4:7], v[184:187], v[242:245], v[4:7]
	v_mfma_f32_16x16x32_bf16 v[0:3], v[210:213], v[242:245], v[0:3]
	s_setprio 0
	s_barrier
; #define PG8_STAGE(bufoff, gbase, voff) do { _Pragma("unroll") for (int _i = 0; _i < 2; ++_i) \
;         __builtin_amdgcn_global_load_lds((const unsigned*)((const char*)(gbase) + (voff)[_i]), (PG8_LAS unsigned*)(lds + (bufoff) + ldsw + _i * 8192), 16, 0, 0); } while (0)
; #define PG8_LDA(dst, b, h) do { _Pragma("unroll") for (int m = 0; m < 4; ++m) _Pragma("unroll") for (int k = 0; k < 2; ++k) dst[m][k] = *(const PG8_LAS bf16x8*)(lds + PG8_SA(b, h) + aoff + m * 2048 + k * 1024); } while (0)
; #define PG8_LDB(dst, b, h) do { _Pragma("unroll") for (int n = 0; n < 2; ++n) _Pragma("unroll") for (int k = 0; k < 2; ++k) dst[n][k] = *(const PG8_LAS bf16x8*)(lds + PG8_SB(b, h) + boff + n * 2048 + k * 1024); } while (0)
; #define PG8_MMA(ai, bj, At, Bt) do { __builtin_amdgcn_s_setprio(1); _Pragma("unroll") for (int m = 0; m < 4; ++m) _Pragma("unroll") for (int n = 0; n < 2; ++n) _Pragma("unroll") for (int k = 0; k < 2; ++k) \
;         acc[ai][bj][m][n] = __builtin_amdgcn_mfma_f32_16x16x32_bf16(Bt[n][k], At[m][k], acc[ai][bj][m][n], 0, 0, 0); __builtin_amdgcn_s_setprio(0); } while (0)
; #define PG8_WAIT_V(n) asm volatile("s_waitcnt vmcnt(" #n ")" ::: "memory")
; #define PG8_WAIT_L(n) asm volatile("s_waitcnt lgkmcnt(" #n ")" ::: "memory")
; #define PG8_BAR __builtin_amdgcn_s_barrier()
; template <class Epi, class Sched, bool ALIGN_EPI = false, bool SP2 = false>
; __device__ __forceinline__ void gemm_phase(PG8_LAS unsigned char* lds, const Gemm g, const Sched& S, const Epi& E) {
;     ...
;         for (int t = 0; t < nt; t += 2) {
;             const bool last = (t == nt - 2);
;             const char* a1 = cA + (size_t)(t + 1) * kstep;
;             const char* a2 = last ? nA : cA + (size_t)(t + 2) * kstep; const char* b2 = last ? nB : cB + (size_t)(t + 2) * kstep;
;             const char* a3 = a2 + kstep; const char* b3 = b2 + kstep;
;     ...
;             PG8_LDB(B0, 1, 0); PG8_LDB(B1, 1, 1); PG8_SCHED; PG8_LDA(At, 1, 0); PG8_STAGE(PG8_SA(0, 1), a2 + hstep, voffA);
;             PG8_WAIT_V(8); PG8_WAIT_L(0); PG8_BAR; PG8_MMA(0, 0, At, B0); PG8_MMA(0, 1, At, B1); PG8_BAR; PG8_SCHED;
;             PG8_LDA(At, 1, 1); PG8_STAGE(PG8_SB(1, 0), b3, voffB); PG8_STAGE(PG8_SB(1, 1), b3 + hstep, voffB); PG8_STAGE(PG8_SA(1, 0), a3, voffA);
;             PG8_WAIT_V(8); PG8_WAIT_L(0); PG8_BAR; PG8_MMA(1, 0, At, B0); PG8_MMA(1, 1, At, B1); PG8_BAR; PG8_SCHED;
	ds_read_b128 v[140:143], v254 offset:32768
	ds_read_b128 v[162:165], v254 offset:33792
	ds_read_b128 v[166:169], v254 offset:34816
	ds_read_b128 v[170:173], v254 offset:35840
	ds_read_b128 v[180:183], v254 offset:49152
	ds_read_b128 v[184:187], v254 offset:50176
	ds_read_b128 v[188:191], v254 offset:51200
	ds_read_b128 v[210:213], v254 offset:52224
	s_add_u32 s4, s4, 0x40000
	s_addc_u32 s5, s5, 0
	s_mov_b32 m0, s42
	ds_read_b128 v[214:217], v178 offset:32768
	ds_read_b128 v[218:221], v178 offset:33792
	ds_read_b128 v[222:225], v178 offset:34816
	ds_read_b128 v[226:229], v178 offset:35840
	ds_read_b128 v[230:233], v178 offset:36864
	ds_read_b128 v[234:237], v178 offset:37888
	ds_read_b128 v[238:241], v178 offset:38912
	ds_read_b128 v[242:245], v178 offset:39936
	global_load_lds_dwordx4 v134, s[4:5]
	s_mov_b32 m0, s43
	s_nop 0
	global_load_lds_dwordx4 v130, s[4:5]
	s_waitcnt vmcnt(8)
	s_waitcnt lgkmcnt(0)
	s_barrier
	s_setprio 1
	v_mfma_f32_16x16x32_bf16 v[124:127], v[140:143], v[214:217], v[124:127]
	v_mfma_f32_16x16x32_bf16 v[120:123], v[166:169], v[214:217], v[120:123]
	v_mfma_f32_16x16x32_bf16 v[116:119], v[180:183], v[214:217], v[116:119]
	v_mfma_f32_16x16x32_bf16 v[112:115], v[188:191], v[214:217], v[112:115]
	v_mfma_f32_16x16x32_bf16 v[108:111], v[140:143], v[222:225], v[108:111]
	v_mfma_f32_16x16x32_bf16 v[104:107], v[166:169], v[222:225], v[104:107]
	v_mfma_f32_16x16x32_bf16 v[100:103], v[180:183], v[222:225], v[100:103]
	v_mfma_f32_16x16x32_bf16 v[96:99], v[188:191], v[222:225], v[96:99]
	v_mfma_f32_16x16x32_bf16 v[92:95], v[140:143], v[230:233], v[92:95]
	v_mfma_f32_16x16x32_bf16 v[88:91], v[166:169], v[230:233], v[88:91]
	v_mfma_f32_16x16x32_bf16 v[84:87], v[180:183], v[230:233], v[84:87]
	v_mfma_f32_16x16x32_bf16 v[80:83], v[188:191], v[230:233], v[80:83]
	v_mfma_f32_16x16x32_bf16 v[76:79], v[140:143], v[238:241], v[76:79]
	v_mfma_f32_16x16x32_bf16 v[72:75], v[166:169], v[238:241], v[72:75]
	v_mfma_f32_16x16x32_bf16 v[68:71], v[180:183], v[238:241], v[68:71]
	v_mfma_f32_16x16x32_bf16 v[64:67], v[188:191], v[238:241], v[64:67]
	v_mfma_f32_16x16x32_bf16 v[124:127], v[162:165], v[218:221], v[124:127]
	v_mfma_f32_16x16x32_bf16 v[120:123], v[170:173], v[218:221], v[120:123]
	v_mfma_f32_16x16x32_bf16 v[116:119], v[184:187], v[218:221], v[116:119]
	v_mfma_f32_16x16x32_bf16 v[112:115], v[210:213], v[218:221], v[112:115]
	v_mfma_f32_16x16x32_bf16 v[108:111], v[162:165], v[226:229], v[108:111]
	v_mfma_f32_16x16x32_bf16 v[104:107], v[170:173], v[226:229], v[104:107]
	v_mfma_f32_16x16x32_bf16 v[100:103], v[184:187], v[226:229], v[100:103]
	v_mfma_f32_16x16x32_bf16 v[96:99], v[210:213], v[226:229], v[96:99]
	v_mfma_f32_16x16x32_bf16 v[92:95], v[162:165], v[234:237], v[92:95]
	v_mfma_f32_16x16x32_bf16 v[88:91], v[170:173], v[234:237], v[88:91]
	v_mfma_f32_16x16x32_bf16 v[84:87], v[184:187], v[234:237], v[84:87]
	v_mfma_f32_16x16x32_bf16 v[80:83], v[210:213], v[234:237], v[80:83]
	v_mfma_f32_16x16x32_bf16 v[76:79], v[162:165], v[242:245], v[76:79]
	v_mfma_f32_16x16x32_bf16 v[72:75], v[170:173], v[242:245], v[72:75]
	v_mfma_f32_16x16x32_bf16 v[68:71], v[184:187], v[242:245], v[68:71]
	v_mfma_f32_16x16x32_bf16 v[64:67], v[210:213], v[242:245], v[64:67]
	s_setprio 0
	s_barrier
	s_mov_b32 m0, s48
	s_add_u32 s2, s2, 0x40080
	s_addc_u32 s3, s3, 0
	ds_read_b128 v[214:217], v178 offset:49152
	ds_read_b128 v[218:221], v178 offset:50176
	ds_read_b128 v[222:225], v178 offset:51200
	ds_read_b128 v[226:229], v178 offset:52224
	ds_read_b128 v[230:233], v178 offset:53248
	ds_read_b128 v[234:237], v178 offset:54272
	ds_read_b128 v[238:241], v178 offset:55296
	ds_read_b128 v[242:245], v178 offset:56320
	s_add_u32 s98, s2, 0xfffc0000
	s_addc_u32 s99, s3, -1
	global_load_lds_dwordx4 v132, s[98:99]
	s_mov_b32 m0, s49
	s_nop 0
	global_load_lds_dwordx4 v128, s[98:99]
	s_mov_b32 m0, s52
	s_nop 0
	global_load_lds_dwordx4 v132, s[2:3]
	s_mov_b32 m0, s53
	s_nop 0
	global_load_lds_dwordx4 v128, s[2:3]
	s_mov_b32 m0, s50
	s_nop 0
	s_add_u32 s100, s4, 0xfffc0080
	s_addc_u32 s101, s5, -1
	global_load_lds_dwordx4 v134, s[100:101]
	s_mov_b32 m0, s51
	s_nop 0
	global_load_lds_dwordx4 v130, s[100:101]
	s_waitcnt vmcnt(8)
	s_waitcnt lgkmcnt(0)
	s_barrier
	s_setprio 1
	v_mfma_f32_16x16x32_bf16 v[60:63], v[140:143], v[214:217], v[60:63]
	v_mfma_f32_16x16x32_bf16 v[56:59], v[166:169], v[214:217], v[56:59]
	v_mfma_f32_16x16x32_bf16 v[52:55], v[180:183], v[214:217], v[52:55]
	v_mfma_f32_16x16x32_bf16 v[48:51], v[188:191], v[214:217], v[48:51]
	v_mfma_f32_16x16x32_bf16 v[44:47], v[140:143], v[222:225], v[44:47]
	v_mfma_f32_16x16x32_bf16 v[40:43], v[166:169], v[222:225], v[40:43]
	v_mfma_f32_16x16x32_bf16 v[36:39], v[180:183], v[222:225], v[36:39]
	v_mfma_f32_16x16x32_bf16 v[32:35], v[188:191], v[222:225], v[32:35]
	v_mfma_f32_16x16x32_bf16 v[28:31], v[140:143], v[230:233], v[28:31]
	v_mfma_f32_16x16x32_bf16 v[24:27], v[166:169], v[230:233], v[24:27]
	v_mfma_f32_16x16x32_bf16 v[20:23], v[180:183], v[230:233], v[20:23]
	v_mfma_f32_16x16x32_bf16 v[16:19], v[188:191], v[230:233], v[16:19]
	v_mfma_f32_16x16x32_bf16 v[12:15], v[140:143], v[238:241], v[12:15]
	v_mfma_f32_16x16x32_bf16 v[8:11], v[166:169], v[238:241], v[8:11]
	v_mfma_f32_16x16x32_bf16 v[4:7], v[180:183], v[238:241], v[4:7]
	v_mfma_f32_16x16x32_bf16 v[0:3], v[188:191], v[238:241], v[0:3]
	v_mfma_f32_16x16x32_bf16 v[60:63], v[162:165], v[218:221], v[60:63]
	v_mfma_f32_16x16x32_bf16 v[56:59], v[170:173], v[218:221], v[56:59]
	v_mfma_f32_16x16x32_bf16 v[52:55], v[184:187], v[218:221], v[52:55]
	v_mfma_f32_16x16x32_bf16 v[48:51], v[210:213], v[218:221], v[48:51]
	v_mfma_f32_16x16x32_bf16 v[44:47], v[162:165], v[226:229], v[44:47]
	v_mfma_f32_16x16x32_bf16 v[40:43], v[170:173], v[226:229], v[40:43]
	v_mfma_f32_16x16x32_bf16 v[36:39], v[184:187], v[226:229], v[36:39]
	v_mfma_f32_16x16x32_bf16 v[32:35], v[210:213], v[226:229], v[32:35]
	v_mfma_f32_16x16x32_bf16 v[28:31], v[162:165], v[234:237], v[28:31]
	v_mfma_f32_16x16x32_bf16 v[24:27], v[170:173], v[234:237], v[24:27]
	v_mfma_f32_16x16x32_bf16 v[20:23], v[184:187], v[234:237], v[20:23]
	v_mfma_f32_16x16x32_bf16 v[16:19], v[210:213], v[234:237], v[16:19]
	v_mfma_f32_16x16x32_bf16 v[12:15], v[162:165], v[242:245], v[12:15]
	v_mfma_f32_16x16x32_bf16 v[8:11], v[170:173], v[242:245], v[8:11]
	v_mfma_f32_16x16x32_bf16 v[4:7], v[184:187], v[242:245], v[4:7]
	v_mfma_f32_16x16x32_bf16 v[0:3], v[210:213], v[242:245], v[0:3]
	s_setprio 0
	s_barrier
	s_add_i32 s55, s55, 2
	s_add_u32 s0, s0, 0x100
	s_addc_u32 s1, s1, 0
	s_add_u32 s38, s38, 0x100
	s_addc_u32 s39, s39, 0
	s_cmp_gt_u32 s55, 13
; #define PG8_STAGE(bufoff, gbase, voff) do { _Pragma("unroll") for (int _i = 0; _i < 2; ++_i) \
;         __builtin_amdgcn_global_load_lds((const unsigned*)((const char*)(gbase) + (voff)[_i]), (PG8_LAS unsigned*)(lds + (bufoff) + ldsw + _i * 8192), 16, 0, 0); } while (0)
; #define PG8_LDA(dst, b, h) do { _Pragma("unroll") for (int m = 0; m < 4; ++m) _Pragma("unroll") for (int k = 0; k < 2; ++k) dst[m][k] = *(const PG8_LAS bf16x8*)(lds + PG8_SA(b, h) + aoff + m * 2048 + k * 1024); } while (0)
; #define PG8_LDB(dst, b, h) do { _Pragma("unroll") for (int n = 0; n < 2; ++n) _Pragma("unroll") for (int k = 0; k < 2; ++k) dst[n][k] = *(const PG8_LAS bf16x8*)(lds + PG8_SB(b, h) + boff + n * 2048 + k * 1024); } while (0)
; #define PG8_MMA(ai, bj, At, Bt) do { __builtin_amdgcn_s_setprio(1); _Pragma("unroll") for (int m = 0; m < 4; ++m) _Pragma("unroll") for (int n = 0; n < 2; ++n) _Pragma("unroll") for (int k = 0; k < 2; ++k) \
;         acc[ai][bj][m][n] = __builtin_amdgcn_mfma_f32_16x16x32_bf16(Bt[n][k], At[m][k], acc[ai][bj][m][n], 0, 0, 0); __builtin_amdgcn_s_setprio(0); } while (0)
; #define PG8_WAIT_V(n) asm volatile("s_waitcnt vmcnt(" #n ")" ::: "memory")
; #define PG8_BAR __builtin_amdgcn_s_barrier()
; template <class Epi, class Sched, bool ALIGN_EPI = false, bool SP2 = false>
; __device__ __forceinline__ void gemm_phase(PG8_LAS unsigned char* lds, const Gemm g, const Sched& S, const Epi& E) {
;     ...
;         for (int t = 0; t < nt; t += 2) {
;             const bool last = (t == nt - 2);
;             const char* a1 = cA + (size_t)(t + 1) * kstep;
;             const char* a2 = last ? nA : cA + (size_t)(t + 2) * kstep; const char* b2 = last ? nB : cB + (size_t)(t + 2) * kstep;
;             const char* a3 = a2 + kstep; const char* b3 = b2 + kstep;
;             if (last && has_next) S.a_ready(nxt);
;             if constexpr (SP2) {
;             PG8_LDB(B0, 0, 0); PG8_LDB(B1, 0, 1); PG8_SCHED; PG8_LDA(At, 0, 0); PG8_STAGE(PG8_SA(1, 1), a1 + hstep, voffA);
;             PG8_WAIT_V(8); PG8_WAIT_L(0); PG8_BAR; PG8_MMA(0, 0, At, B0); PG8_MMA(0, 1, At, B1); PG8_BAR; PG8_SCHED;
;             PG8_LDA(At, 0, 1); PG8_STAGE(PG8_SB(0, 0), b2, voffB); PG8_STAGE(PG8_SB(0, 1), b2 + hstep, voffB); PG8_STAGE(PG8_SA(0, 0), a2, voffA);
;             PG8_WAIT_V(8); PG8_WAIT_L(0); PG8_BAR; PG8_MMA(1, 0, At, B0); PG8_MMA(1, 1, At, B1); PG8_BAR; PG8_SCHED;
.LBB0_749:
	ds_read_b128 v[140:143], v254
	ds_read_b128 v[162:165], v254 offset:1024
	ds_read_b128 v[166:169], v254 offset:2048
	ds_read_b128 v[170:173], v254 offset:3072
	ds_read_b128 v[180:183], v254 offset:16384
	ds_read_b128 v[184:187], v254 offset:17408
	ds_read_b128 v[188:191], v254 offset:18432
	ds_read_b128 v[210:213], v254 offset:19456
	s_add_u32 s2, s0, 0xfffc0080
	s_addc_u32 s3, s1, -1
	s_cmp_eq_u32 s55, 12
	s_cselect_b32 s5, s13, s3
	s_cselect_b32 s4, s25, s2
	s_cselect_b32 s3, s23, s39
	s_cselect_b32 s2, s33, s38
	s_add_i32 m0, s6, 0xc000
	ds_read_b128 v[214:217], v178
	ds_read_b128 v[218:221], v178 offset:1024
	ds_read_b128 v[222:225], v178 offset:2048
	ds_read_b128 v[226:229], v178 offset:3072
	ds_read_b128 v[230:233], v178 offset:4096
	ds_read_b128 v[234:237], v178 offset:5120
	ds_read_b128 v[238:241], v178 offset:6144
	ds_read_b128 v[242:245], v178 offset:7168
	global_load_lds_dwordx4 v136, s[0:1]
	s_add_i32 m0, s6, 0xe000
	s_nop 0
	global_load_lds_dwordx4 v138, s[0:1]
	s_waitcnt vmcnt(8)
	s_waitcnt lgkmcnt(0)
	s_barrier
	s_setprio 1
	v_mfma_f32_16x16x32_bf16 v[124:127], v[140:143], v[214:217], v[124:127]
	v_mfma_f32_16x16x32_bf16 v[120:123], v[166:169], v[214:217], v[120:123]
	v_mfma_f32_16x16x32_bf16 v[116:119], v[180:183], v[214:217], v[116:119]
	v_mfma_f32_16x16x32_bf16 v[112:115], v[188:191], v[214:217], v[112:115]
	v_mfma_f32_16x16x32_bf16 v[108:111], v[140:143], v[222:225], v[108:111]
	v_mfma_f32_16x16x32_bf16 v[104:107], v[166:169], v[222:225], v[104:107]
	v_mfma_f32_16x16x32_bf16 v[100:103], v[180:183], v[222:225], v[100:103]
	v_mfma_f32_16x16x32_bf16 v[96:99], v[188:191], v[222:225], v[96:99]
	v_mfma_f32_16x16x32_bf16 v[92:95], v[140:143], v[230:233], v[92:95]
	v_mfma_f32_16x16x32_bf16 v[88:91], v[166:169], v[230:233], v[88:91]
	v_mfma_f32_16x16x32_bf16 v[84:87], v[180:183], v[230:233], v[84:87]
	v_mfma_f32_16x16x32_bf16 v[80:83], v[188:191], v[230:233], v[80:83]
	v_mfma_f32_16x16x32_bf16 v[76:79], v[140:143], v[238:241], v[76:79]
	v_mfma_f32_16x16x32_bf16 v[72:75], v[166:169], v[238:241], v[72:75]
	v_mfma_f32_16x16x32_bf16 v[68:71], v[180:183], v[238:241], v[68:71]
	v_mfma_f32_16x16x32_bf16 v[64:67], v[188:191], v[238:241], v[64:67]
	v_mfma_f32_16x16x32_bf16 v[124:127], v[162:165], v[218:221], v[124:127]
	v_mfma_f32_16x16x32_bf16 v[120:123], v[170:173], v[218:221], v[120:123]
	v_mfma_f32_16x16x32_bf16 v[116:119], v[184:187], v[218:221], v[116:119]
	v_mfma_f32_16x16x32_bf16 v[112:115], v[210:213], v[218:221], v[112:115]
	v_mfma_f32_16x16x32_bf16 v[108:111], v[162:165], v[226:229], v[108:111]
	v_mfma_f32_16x16x32_bf16 v[104:107], v[170:173], v[226:229], v[104:107]
	v_mfma_f32_16x16x32_bf16 v[100:103], v[184:187], v[226:229], v[100:103]
	v_mfma_f32_16x16x32_bf16 v[96:99], v[210:213], v[226:229], v[96:99]
	v_mfma_f32_16x16x32_bf16 v[92:95], v[162:165], v[234:237], v[92:95]
	v_mfma_f32_16x16x32_bf16 v[88:91], v[170:173], v[234:237], v[88:91]
	v_mfma_f32_16x16x32_bf16 v[84:87], v[184:187], v[234:237], v[84:87]
	v_mfma_f32_16x16x32_bf16 v[80:83], v[210:213], v[234:237], v[80:83]
	v_mfma_f32_16x16x32_bf16 v[76:79], v[162:165], v[242:245], v[76:79]
	v_mfma_f32_16x16x32_bf16 v[72:75], v[170:173], v[242:245], v[72:75]
	v_mfma_f32_16x16x32_bf16 v[68:71], v[184:187], v[242:245], v[68:71]
	v_mfma_f32_16x16x32_bf16 v[64:67], v[210:213], v[242:245], v[64:67]
	s_setprio 0
	s_barrier
	s_mov_b32 m0, s31
	s_add_u32 s56, s2, 0x40000
	s_addc_u32 s57, s3, 0
	ds_read_b128 v[214:217], v178 offset:16384
	ds_read_b128 v[218:221], v178 offset:17408
	ds_read_b128 v[222:225], v178 offset:18432
	ds_read_b128 v[226:229], v178 offset:19456
	ds_read_b128 v[230:233], v178 offset:20480
	ds_read_b128 v[234:237], v178 offset:21504
	ds_read_b128 v[238:241], v178 offset:22528
	ds_read_b128 v[242:245], v178 offset:23552
	global_load_lds_dwordx4 v132, s[2:3]
	s_mov_b32 m0, s34
	s_nop 0
	global_load_lds_dwordx4 v128, s[2:3]
	s_mov_b32 m0, s35
	s_nop 0
	global_load_lds_dwordx4 v132, s[56:57]
	s_mov_b32 m0, s40
	s_nop 0
	global_load_lds_dwordx4 v128, s[56:57]
	s_mov_b32 m0, s6
	s_nop 0
	global_load_lds_dwordx4 v134, s[4:5]
	s_mov_b32 m0, s41
	s_nop 0
	global_load_lds_dwordx4 v130, s[4:5]
	s_waitcnt vmcnt(8)
	s_waitcnt lgkmcnt(0)
	s_barrier
	s_setprio 1
	v_mfma_f32_16x16x32_bf16 v[60:63], v[140:143], v[214:217], v[60:63]
	v_mfma_f32_16x16x32_bf16 v[56:59], v[166:169], v[214:217], v[56:59]
	v_mfma_f32_16x16x32_bf16 v[52:55], v[180:183], v[214:217], v[52:55]
	v_mfma_f32_16x16x32_bf16 v[48:51], v[188:191], v[214:217], v[48:51]
	v_mfma_f32_16x16x32_bf16 v[44:47], v[140:143], v[222:225], v[44:47]
	v_mfma_f32_16x16x32_bf16 v[40:43], v[166:169], v[222:225], v[40:43]
	v_mfma_f32_16x16x32_bf16 v[36:39], v[180:183], v[222:225], v[36:39]
	v_mfma_f32_16x16x32_bf16 v[32:35], v[188:191], v[222:225], v[32:35]
	v_mfma_f32_16x16x32_bf16 v[28:31], v[140:143], v[230:233], v[28:31]
	v_mfma_f32_16x16x32_bf16 v[24:27], v[166:169], v[230:233], v[24:27]
	v_mfma_f32_16x16x32_bf16 v[20:23], v[180:183], v[230:233], v[20:23]
	v_mfma_f32_16x16x32_bf16 v[16:19], v[188:191], v[230:233], v[16:19]
	v_mfma_f32_16x16x32_bf16 v[12:15], v[140:143], v[238:241], v[12:15]
	v_mfma_f32_16x16x32_bf16 v[8:11], v[166:169], v[238:241], v[8:11]
	v_mfma_f32_16x16x32_bf16 v[4:7], v[180:183], v[238:241], v[4:7]
	v_mfma_f32_16x16x32_bf16 v[0:3], v[188:191], v[238:241], v[0:3]
	v_mfma_f32_16x16x32_bf16 v[60:63], v[162:165], v[218:221], v[60:63]
	v_mfma_f32_16x16x32_bf16 v[56:59], v[170:173], v[218:221], v[56:59]
	v_mfma_f32_16x16x32_bf16 v[52:55], v[184:187], v[218:221], v[52:55]
	v_mfma_f32_16x16x32_bf16 v[48:51], v[210:213], v[218:221], v[48:51]
	v_mfma_f32_16x16x32_bf16 v[44:47], v[162:165], v[226:229], v[44:47]
	v_mfma_f32_16x16x32_bf16 v[40:43], v[170:173], v[226:229], v[40:43]
	v_mfma_f32_16x16x32_bf16 v[36:39], v[184:187], v[226:229], v[36:39]
	v_mfma_f32_16x16x32_bf16 v[32:35], v[210:213], v[226:229], v[32:35]
	v_mfma_f32_16x16x32_bf16 v[28:31], v[162:165], v[234:237], v[28:31]
	v_mfma_f32_16x16x32_bf16 v[24:27], v[170:173], v[234:237], v[24:27]
	v_mfma_f32_16x16x32_bf16 v[20:23], v[184:187], v[234:237], v[20:23]
	v_mfma_f32_16x16x32_bf16 v[16:19], v[210:213], v[234:237], v[16:19]
	v_mfma_f32_16x16x32_bf16 v[12:15], v[162:165], v[242:245], v[12:15]
	v_mfma_f32_16x16x32_bf16 v[8:11], v[170:173], v[242:245], v[8:11]
	v_mfma_f32_16x16x32_bf16 v[4:7], v[184:187], v[242:245], v[4:7]
	v_mfma_f32_16x16x32_bf16 v[0:3], v[210:213], v[242:245], v[0:3]
	s_setprio 0
	s_barrier
; #define PG8_STAGE(bufoff, gbase, voff) do { _Pragma("unroll") for (int _i = 0; _i < 2; ++_i) \
;         __builtin_amdgcn_global_load_lds((const unsigned*)((const char*)(gbase) + (voff)[_i]), (PG8_LAS unsigned*)(lds + (bufoff) + ldsw + _i * 8192), 16, 0, 0); } while (0)
; #define PG8_LDA(dst, b, h) do { _Pragma("unroll") for (int m = 0; m < 4; ++m) _Pragma("unroll") for (int k = 0; k < 2; ++k) dst[m][k] = *(const PG8_LAS bf16x8*)(lds + PG8_SA(b, h) + aoff + m * 2048 + k * 1024); } while (0)
; #define PG8_LDB(dst, b, h) do { _Pragma("unroll") for (int n = 0; n < 2; ++n) _Pragma("unroll") for (int k = 0; k < 2; ++k) dst[n][k] = *(const PG8_LAS bf16x8*)(lds + PG8_SB(b, h) + boff + n * 2048 + k * 1024); } while (0)
; #define PG8_MMA(ai, bj, At, Bt) do { __builtin_amdgcn_s_setprio(1); _Pragma("unroll") for (int m = 0; m < 4; ++m) _Pragma("unroll") for (int n = 0; n < 2; ++n) _Pragma("unroll") for (int k = 0; k < 2; ++k) \
;         acc[ai][bj][m][n] = __builtin_amdgcn_mfma_f32_16x16x32_bf16(Bt[n][k], At[m][k], acc[ai][bj][m][n], 0, 0, 0); __builtin_amdgcn_s_setprio(0); } while (0)
; #define PG8_WAIT_V(n) asm volatile("s_waitcnt vmcnt(" #n ")" ::: "memory")
; #define PG8_WAIT_L(n) asm volatile("s_waitcnt lgkmcnt(" #n ")" ::: "memory")
; #define PG8_BAR __builtin_amdgcn_s_barrier()
; #define PG8_SCHED __builtin_amdgcn_sched_barrier(0)
; template <class Epi, class Sched, bool ALIGN_EPI = false, bool SP2 = false>
; __device__ __forceinline__ void gemm_phase(PG8_LAS unsigned char* lds, const Gemm g, const Sched& S, const Epi& E) {
;     ...
;             PG8_LDB(B0, 1, 0); PG8_LDB(B1, 1, 1); PG8_SCHED; PG8_LDA(At, 1, 0); PG8_STAGE(PG8_SA(0, 1), a2 + hstep, voffA);
;             PG8_WAIT_V(8); PG8_WAIT_L(0); PG8_BAR; PG8_MMA(0, 0, At, B0); PG8_MMA(0, 1, At, B1); PG8_BAR; PG8_SCHED;
;             PG8_LDA(At, 1, 1); PG8_STAGE(PG8_SB(1, 0), b3, voffB); PG8_STAGE(PG8_SB(1, 1), b3 + hstep, voffB); PG8_STAGE(PG8_SA(1, 0), a3, voffA);
;             PG8_WAIT_V(8); PG8_WAIT_L(0); PG8_BAR; PG8_MMA(1, 0, At, B0); PG8_MMA(1, 1, At, B1); PG8_BAR; PG8_SCHED;
;     ...
;         if constexpr (ALIGN_EPI) { if (wr == 0) PG8_BAR; }
	ds_read_b128 v[140:143], v254 offset:32768
	ds_read_b128 v[162:165], v254 offset:33792
	ds_read_b128 v[166:169], v254 offset:34816
	ds_read_b128 v[170:173], v254 offset:35840
	ds_read_b128 v[180:183], v254 offset:49152
	ds_read_b128 v[184:187], v254 offset:50176
	ds_read_b128 v[188:191], v254 offset:51200
	ds_read_b128 v[210:213], v254 offset:52224
	s_add_u32 s4, s4, 0x40000
	s_addc_u32 s5, s5, 0
	s_mov_b32 m0, s42
	ds_read_b128 v[214:217], v178 offset:32768
	ds_read_b128 v[218:221], v178 offset:33792
	ds_read_b128 v[222:225], v178 offset:34816
	ds_read_b128 v[226:229], v178 offset:35840
	ds_read_b128 v[230:233], v178 offset:36864
	ds_read_b128 v[234:237], v178 offset:37888
	ds_read_b128 v[238:241], v178 offset:38912
	ds_read_b128 v[242:245], v178 offset:39936
	global_load_lds_dwordx4 v134, s[4:5]
	s_mov_b32 m0, s43
	s_nop 0
	global_load_lds_dwordx4 v130, s[4:5]
	s_waitcnt vmcnt(8)
	s_waitcnt lgkmcnt(0)
	s_barrier
	s_setprio 1
	v_mfma_f32_16x16x32_bf16 v[124:127], v[140:143], v[214:217], v[124:127]
	v_mfma_f32_16x16x32_bf16 v[120:123], v[166:169], v[214:217], v[120:123]
	v_mfma_f32_16x16x32_bf16 v[116:119], v[180:183], v[214:217], v[116:119]
	v_mfma_f32_16x16x32_bf16 v[112:115], v[188:191], v[214:217], v[112:115]
	v_mfma_f32_16x16x32_bf16 v[108:111], v[140:143], v[222:225], v[108:111]
	v_mfma_f32_16x16x32_bf16 v[104:107], v[166:169], v[222:225], v[104:107]
	v_mfma_f32_16x16x32_bf16 v[100:103], v[180:183], v[222:225], v[100:103]
	v_mfma_f32_16x16x32_bf16 v[96:99], v[188:191], v[222:225], v[96:99]
	v_mfma_f32_16x16x32_bf16 v[92:95], v[140:143], v[230:233], v[92:95]
	v_mfma_f32_16x16x32_bf16 v[88:91], v[166:169], v[230:233], v[88:91]
	v_mfma_f32_16x16x32_bf16 v[84:87], v[180:183], v[230:233], v[84:87]
	v_mfma_f32_16x16x32_bf16 v[80:83], v[188:191], v[230:233], v[80:83]
	v_mfma_f32_16x16x32_bf16 v[76:79], v[140:143], v[238:241], v[76:79]
	v_mfma_f32_16x16x32_bf16 v[72:75], v[166:169], v[238:241], v[72:75]
	v_mfma_f32_16x16x32_bf16 v[68:71], v[180:183], v[238:241], v[68:71]
	v_mfma_f32_16x16x32_bf16 v[64:67], v[188:191], v[238:241], v[64:67]
	v_mfma_f32_16x16x32_bf16 v[124:127], v[162:165], v[218:221], v[124:127]
	v_mfma_f32_16x16x32_bf16 v[120:123], v[170:173], v[218:221], v[120:123]
	v_mfma_f32_16x16x32_bf16 v[116:119], v[184:187], v[218:221], v[116:119]
	v_mfma_f32_16x16x32_bf16 v[112:115], v[210:213], v[218:221], v[112:115]
	v_mfma_f32_16x16x32_bf16 v[108:111], v[162:165], v[226:229], v[108:111]
	v_mfma_f32_16x16x32_bf16 v[104:107], v[170:173], v[226:229], v[104:107]
	v_mfma_f32_16x16x32_bf16 v[100:103], v[184:187], v[226:229], v[100:103]
	v_mfma_f32_16x16x32_bf16 v[96:99], v[210:213], v[226:229], v[96:99]
	v_mfma_f32_16x16x32_bf16 v[92:95], v[162:165], v[234:237], v[92:95]
	v_mfma_f32_16x16x32_bf16 v[88:91], v[170:173], v[234:237], v[88:91]
	v_mfma_f32_16x16x32_bf16 v[84:87], v[184:187], v[234:237], v[84:87]
	v_mfma_f32_16x16x32_bf16 v[80:83], v[210:213], v[234:237], v[80:83]
	v_mfma_f32_16x16x32_bf16 v[76:79], v[162:165], v[242:245], v[76:79]
	v_mfma_f32_16x16x32_bf16 v[72:75], v[170:173], v[242:245], v[72:75]
	v_mfma_f32_16x16x32_bf16 v[68:71], v[184:187], v[242:245], v[68:71]
	v_mfma_f32_16x16x32_bf16 v[64:67], v[210:213], v[242:245], v[64:67]
	s_setprio 0
	s_barrier
	s_mov_b32 m0, s48
	s_add_u32 s2, s2, 0x40080
	s_addc_u32 s3, s3, 0
	ds_read_b128 v[214:217], v178 offset:49152
	ds_read_b128 v[218:221], v178 offset:50176
	ds_read_b128 v[222:225], v178 offset:51200
	ds_read_b128 v[226:229], v178 offset:52224
	ds_read_b128 v[230:233], v178 offset:53248
	ds_read_b128 v[234:237], v178 offset:54272
	ds_read_b128 v[238:241], v178 offset:55296
	ds_read_b128 v[242:245], v178 offset:56320
	s_add_u32 s98, s2, 0xfffc0000
	s_addc_u32 s99, s3, -1
	global_load_lds_dwordx4 v132, s[98:99]
	s_mov_b32 m0, s49
	s_nop 0
	global_load_lds_dwordx4 v128, s[98:99]
	s_mov_b32 m0, s52
	s_nop 0
	global_load_lds_dwordx4 v132, s[2:3]
	s_mov_b32 m0, s53
	s_nop 0
	global_load_lds_dwordx4 v128, s[2:3]
	s_mov_b32 m0, s50
	s_nop 0
	s_add_u32 s100, s4, 0xfffc0080
	s_addc_u32 s101, s5, -1
	global_load_lds_dwordx4 v134, s[100:101]
	s_mov_b32 m0, s51
	s_nop 0
	global_load_lds_dwordx4 v130, s[100:101]
	s_waitcnt vmcnt(8)
	s_waitcnt lgkmcnt(0)
	s_barrier
	s_setprio 1
	v_mfma_f32_16x16x32_bf16 v[60:63], v[140:143], v[214:217], v[60:63]
	v_mfma_f32_16x16x32_bf16 v[56:59], v[166:169], v[214:217], v[56:59]
	v_mfma_f32_16x16x32_bf16 v[52:55], v[180:183], v[214:217], v[52:55]
	v_mfma_f32_16x16x32_bf16 v[48:51], v[188:191], v[214:217], v[48:51]
	v_mfma_f32_16x16x32_bf16 v[44:47], v[140:143], v[222:225], v[44:47]
	v_mfma_f32_16x16x32_bf16 v[40:43], v[166:169], v[222:225], v[40:43]
	v_mfma_f32_16x16x32_bf16 v[36:39], v[180:183], v[222:225], v[36:39]
	v_mfma_f32_16x16x32_bf16 v[32:35], v[188:191], v[222:225], v[32:35]
	v_mfma_f32_16x16x32_bf16 v[28:31], v[140:143], v[230:233], v[28:31]
	v_mfma_f32_16x16x32_bf16 v[24:27], v[166:169], v[230:233], v[24:27]
	v_mfma_f32_16x16x32_bf16 v[20:23], v[180:183], v[230:233], v[20:23]
	v_mfma_f32_16x16x32_bf16 v[16:19], v[188:191], v[230:233], v[16:19]
	v_mfma_f32_16x16x32_bf16 v[12:15], v[140:143], v[238:241], v[12:15]
	v_mfma_f32_16x16x32_bf16 v[8:11], v[166:169], v[238:241], v[8:11]
	v_mfma_f32_16x16x32_bf16 v[4:7], v[180:183], v[238:241], v[4:7]
	v_mfma_f32_16x16x32_bf16 v[0:3], v[188:191], v[238:241], v[0:3]
	v_mfma_f32_16x16x32_bf16 v[60:63], v[162:165], v[218:221], v[60:63]
	v_mfma_f32_16x16x32_bf16 v[56:59], v[170:173], v[218:221], v[56:59]
	v_mfma_f32_16x16x32_bf16 v[52:55], v[184:187], v[218:221], v[52:55]
	v_mfma_f32_16x16x32_bf16 v[48:51], v[210:213], v[218:221], v[48:51]
	v_mfma_f32_16x16x32_bf16 v[44:47], v[162:165], v[226:229], v[44:47]
	v_mfma_f32_16x16x32_bf16 v[40:43], v[170:173], v[226:229], v[40:43]
	v_mfma_f32_16x16x32_bf16 v[36:39], v[184:187], v[226:229], v[36:39]
	v_mfma_f32_16x16x32_bf16 v[32:35], v[210:213], v[226:229], v[32:35]
	v_mfma_f32_16x16x32_bf16 v[28:31], v[162:165], v[234:237], v[28:31]
	v_mfma_f32_16x16x32_bf16 v[24:27], v[170:173], v[234:237], v[24:27]
	v_mfma_f32_16x16x32_bf16 v[20:23], v[184:187], v[234:237], v[20:23]
	v_mfma_f32_16x16x32_bf16 v[16:19], v[210:213], v[234:237], v[16:19]
	v_mfma_f32_16x16x32_bf16 v[12:15], v[162:165], v[242:245], v[12:15]
	v_mfma_f32_16x16x32_bf16 v[8:11], v[170:173], v[242:245], v[8:11]
	v_mfma_f32_16x16x32_bf16 v[4:7], v[184:187], v[242:245], v[4:7]
	v_mfma_f32_16x16x32_bf16 v[0:3], v[210:213], v[242:245], v[0:3]
	s_setprio 0
	s_barrier
	s_add_i32 s55, s55, 2
	s_add_u32 s0, s0, 0x100
	s_addc_u32 s1, s1, 0
	s_add_u32 s38, s38, 0x100
	s_addc_u32 s39, s39, 0
	s_cmp_gt_u32 s55, 13
	s_cbranch_scc0 .LBB0_749
	s_and_b64 vcc, exec, s[18:19]
	s_cbranch_vccz .LBB0_752
	s_barrier

; #define PG8_STAGE(bufoff, gbase, voff) do { _Pragma("unroll") for (int _i = 0; _i < 2; ++_i) \
;         __builtin_amdgcn_global_load_lds((const unsigned*)((const char*)(gbase) + (voff)[_i]), (PG8_LAS unsigned*)(lds + (bufoff) + ldsw + _i * 8192), 16, 0, 0); } while (0)
; #define PG8_LDA(dst, b, h) do { _Pragma("unroll") for (int m = 0; m < 4; ++m) _Pragma("unroll") for (int k = 0; k < 2; ++k) dst[m][k] = *(const PG8_LAS bf16x8*)(lds + PG8_SA(b, h) + aoff + m * 2048 + k * 1024); } while (0)
; #define PG8_LDB(dst, b, h) do { _Pragma("unroll") for (int n = 0; n < 2; ++n) _Pragma("unroll") for (int k = 0; k < 2; ++k) dst[n][k] = *(const PG8_LAS bf16x8*)(lds + PG8_SB(b, h) + boff + n * 2048 + k * 1024); } while (0)
; #define PG8_MMA(ai, bj, At, Bt) do { __builtin_amdgcn_s_setprio(1); _Pragma("unroll") for (int m = 0; m < 4; ++m) _Pragma("unroll") for (int n = 0; n < 2; ++n) _Pragma("unroll") for (int k = 0; k < 2; ++k) \
;         acc[ai][bj][m][n] = __builtin_amdgcn_mfma_f32_16x16x32_bf16(Bt[n][k], At[m][k], acc[ai][bj][m][n], 0, 0, 0); __builtin_amdgcn_s_setprio(0); } while (0)
; #define PG8_WAIT_V(n) asm volatile("s_waitcnt vmcnt(" #n ")" ::: "memory")
; #define PG8_WAIT_L(n) asm volatile("s_waitcnt lgkmcnt(" #n ")" ::: "memory")
; template <class Epi, class Sched, bool ALIGN_EPI = false, bool SP2 = false>
; __device__ __forceinline__ void gemm_phase(PG8_LAS unsigned char* lds, const Gemm g, const Sched& S, const Epi& E) {
;     ...
;             const bool last = (t == nt - 2);
;             const char* a1 = cA + (size_t)(t + 1) * kstep;
;             const char* a2 = last ? nA : cA + (size_t)(t + 2) * kstep; const char* b2 = last ? nB : cB + (size_t)(t + 2) * kstep;
;             const char* a3 = a2 + kstep; const char* b3 = b2 + kstep;
;             if (last && has_next) S.a_ready(nxt);
;             if constexpr (SP2) {
;             PG8_LDB(B0, 0, 0); PG8_LDB(B1, 0, 1); PG8_SCHED; PG8_LDA(At, 0, 0); PG8_STAGE(PG8_SA(1, 1), a1 + hstep, voffA);
;             PG8_WAIT_V(8); PG8_WAIT_L(0); PG8_BAR; PG8_MMA(0, 0, At, B0); PG8_MMA(0, 1, At, B1); PG8_BAR; PG8_SCHED;
;             PG8_LDA(At, 0, 1); PG8_STAGE(PG8_SB(0, 0), b2, voffB); PG8_STAGE(PG8_SB(0, 1), b2 + hstep, voffB); PG8_STAGE(PG8_SA(0, 0), a2, voffA);
;             PG8_WAIT_V(8); PG8_WAIT_L(0); PG8_BAR; PG8_MMA(1, 0, At, B0); PG8_MMA(1, 1, At, B1); PG8_BAR; PG8_SCHED;
.Labi_peel:
	s_waitcnt lgkmcnt(0)
	ds_read_b128 v[140:143], v254
	ds_read_b128 v[162:165], v254 offset:1024
	ds_read_b128 v[166:169], v254 offset:2048
	ds_read_b128 v[176:179], v254 offset:3072
	ds_read_b128 v[180:183], v254 offset:16384
	ds_read_b128 v[184:187], v254 offset:17408
	ds_read_b128 v[188:191], v254 offset:18432
	ds_read_b128 v[210:213], v254 offset:19456
	s_add_u32 s2, s0, 0xfffc0080
	s_addc_u32 s3, s1, -1
	s_cmp_eq_u32 s52, 12
	s_cselect_b32 s5, s17, s3
	s_cselect_b32 s4, s48, s2
	s_cselect_b32 s3, s15, s51
	s_cselect_b32 s2, s49, s50
	s_add_i32 m0, s6, 0xc000
	ds_read_b128 v[214:217], v173
	ds_read_b128 v[218:221], v173 offset:1024
	ds_read_b128 v[222:225], v173 offset:2048
	ds_read_b128 v[226:229], v173 offset:3072
	ds_read_b128 v[230:233], v173 offset:4096
	ds_read_b128 v[234:237], v173 offset:5120
	ds_read_b128 v[238:241], v173 offset:6144
	ds_read_b128 v[242:245], v173 offset:7168
	global_load_lds_dwordx4 v136, s[0:1]
	s_add_i32 m0, s6, 0xe000
	s_nop 0
	global_load_lds_dwordx4 v138, s[0:1]
	s_waitcnt vmcnt(8)
	s_waitcnt lgkmcnt(0)
	s_barrier
	s_setprio 1
	v_mfma_f32_16x16x32_bf16 v[124:127], v[140:143], v[214:217], 0
	v_mfma_f32_16x16x32_bf16 v[120:123], v[166:169], v[214:217], 0
	v_mfma_f32_16x16x32_bf16 v[116:119], v[180:183], v[214:217], 0
	v_mfma_f32_16x16x32_bf16 v[108:111], v[188:191], v[214:217], 0
	v_mfma_f32_16x16x32_bf16 v[112:115], v[140:143], v[222:225], 0
	v_mfma_f32_16x16x32_bf16 v[104:107], v[166:169], v[222:225], 0
	v_mfma_f32_16x16x32_bf16 v[100:103], v[180:183], v[222:225], 0
	v_mfma_f32_16x16x32_bf16 v[92:95], v[188:191], v[222:225], 0
	v_mfma_f32_16x16x32_bf16 v[96:99], v[140:143], v[230:233], 0
	v_mfma_f32_16x16x32_bf16 v[88:91], v[166:169], v[230:233], 0
	v_mfma_f32_16x16x32_bf16 v[84:87], v[180:183], v[230:233], 0
	v_mfma_f32_16x16x32_bf16 v[76:79], v[188:191], v[230:233], 0
	v_mfma_f32_16x16x32_bf16 v[80:83], v[140:143], v[238:241], 0
	v_mfma_f32_16x16x32_bf16 v[72:75], v[166:169], v[238:241], 0
	v_mfma_f32_16x16x32_bf16 v[68:71], v[180:183], v[238:241], 0
	v_mfma_f32_16x16x32_bf16 v[64:67], v[188:191], v[238:241], 0
	v_mfma_f32_16x16x32_bf16 v[124:127], v[162:165], v[218:221], v[124:127]
	v_mfma_f32_16x16x32_bf16 v[120:123], v[176:179], v[218:221], v[120:123]
	v_mfma_f32_16x16x32_bf16 v[116:119], v[184:187], v[218:221], v[116:119]
	v_mfma_f32_16x16x32_bf16 v[108:111], v[210:213], v[218:221], v[108:111]
	v_mfma_f32_16x16x32_bf16 v[112:115], v[162:165], v[226:229], v[112:115]
	v_mfma_f32_16x16x32_bf16 v[104:107], v[176:179], v[226:229], v[104:107]
	v_mfma_f32_16x16x32_bf16 v[100:103], v[184:187], v[226:229], v[100:103]
	v_mfma_f32_16x16x32_bf16 v[92:95], v[210:213], v[226:229], v[92:95]
	v_mfma_f32_16x16x32_bf16 v[96:99], v[162:165], v[234:237], v[96:99]
	v_mfma_f32_16x16x32_bf16 v[88:91], v[176:179], v[234:237], v[88:91]
	v_mfma_f32_16x16x32_bf16 v[84:87], v[184:187], v[234:237], v[84:87]
	v_mfma_f32_16x16x32_bf16 v[76:79], v[210:213], v[234:237], v[76:79]
	v_mfma_f32_16x16x32_bf16 v[80:83], v[162:165], v[242:245], v[80:83]
	v_mfma_f32_16x16x32_bf16 v[72:75], v[176:179], v[242:245], v[72:75]
	v_mfma_f32_16x16x32_bf16 v[68:71], v[184:187], v[242:245], v[68:71]
	v_mfma_f32_16x16x32_bf16 v[64:67], v[210:213], v[242:245], v[64:67]
	s_setprio 0
	s_barrier
	s_mov_b32 m0, s27
	s_add_u32 s54, s2, 0x40000
	s_addc_u32 s55, s3, 0
	ds_read_b128 v[214:217], v173 offset:16384
	ds_read_b128 v[218:221], v173 offset:17408
	ds_read_b128 v[222:225], v173 offset:18432
	ds_read_b128 v[226:229], v173 offset:19456
	ds_read_b128 v[230:233], v173 offset:20480
	ds_read_b128 v[234:237], v173 offset:21504
	ds_read_b128 v[238:241], v173 offset:22528
	ds_read_b128 v[242:245], v173 offset:23552
	global_load_lds_dwordx4 v132, s[2:3]
	s_mov_b32 m0, s28
	s_nop 0
	global_load_lds_dwordx4 v128, s[2:3]
	s_mov_b32 m0, s29
	s_nop 0
	global_load_lds_dwordx4 v132, s[54:55]
	s_mov_b32 m0, s30
	s_nop 0
	global_load_lds_dwordx4 v128, s[54:55]
	s_mov_b32 m0, s6
	s_nop 0
	global_load_lds_dwordx4 v134, s[4:5]
	s_mov_b32 m0, s31
	s_nop 0
	global_load_lds_dwordx4 v130, s[4:5]
	s_waitcnt vmcnt(8)
	s_waitcnt lgkmcnt(0)
	s_barrier
	s_setprio 1
	v_mfma_f32_16x16x32_bf16 v[60:63], v[140:143], v[214:217], 0
	v_mfma_f32_16x16x32_bf16 v[56:59], v[166:169], v[214:217], 0
	v_mfma_f32_16x16x32_bf16 v[52:55], v[180:183], v[214:217], 0
	v_mfma_f32_16x16x32_bf16 v[44:47], v[188:191], v[214:217], 0
	v_mfma_f32_16x16x32_bf16 v[48:51], v[140:143], v[222:225], 0
	v_mfma_f32_16x16x32_bf16 v[40:43], v[166:169], v[222:225], 0
	v_mfma_f32_16x16x32_bf16 v[36:39], v[180:183], v[222:225], 0
	v_mfma_f32_16x16x32_bf16 v[28:31], v[188:191], v[222:225], 0
	v_mfma_f32_16x16x32_bf16 v[32:35], v[140:143], v[230:233], 0
	v_mfma_f32_16x16x32_bf16 v[24:27], v[166:169], v[230:233], 0
	v_mfma_f32_16x16x32_bf16 v[20:23], v[180:183], v[230:233], 0
	v_mfma_f32_16x16x32_bf16 v[12:15], v[188:191], v[230:233], 0
	v_mfma_f32_16x16x32_bf16 v[16:19], v[140:143], v[238:241], 0
	v_mfma_f32_16x16x32_bf16 v[8:11], v[166:169], v[238:241], 0
	v_mfma_f32_16x16x32_bf16 v[4:7], v[180:183], v[238:241], 0
	v_mfma_f32_16x16x32_bf16 v[0:3], v[188:191], v[238:241], 0
	v_mfma_f32_16x16x32_bf16 v[60:63], v[162:165], v[218:221], v[60:63]
	v_mfma_f32_16x16x32_bf16 v[56:59], v[176:179], v[218:221], v[56:59]
	v_mfma_f32_16x16x32_bf16 v[52:55], v[184:187], v[218:221], v[52:55]
	v_mfma_f32_16x16x32_bf16 v[44:47], v[210:213], v[218:221], v[44:47]
	v_mfma_f32_16x16x32_bf16 v[48:51], v[162:165], v[226:229], v[48:51]
	v_mfma_f32_16x16x32_bf16 v[40:43], v[176:179], v[226:229], v[40:43]
	v_mfma_f32_16x16x32_bf16 v[36:39], v[184:187], v[226:229], v[36:39]
	v_mfma_f32_16x16x32_bf16 v[28:31], v[210:213], v[226:229], v[28:31]
	v_mfma_f32_16x16x32_bf16 v[32:35], v[162:165], v[234:237], v[32:35]
	v_mfma_f32_16x16x32_bf16 v[24:27], v[176:179], v[234:237], v[24:27]
	v_mfma_f32_16x16x32_bf16 v[20:23], v[184:187], v[234:237], v[20:23]
	v_mfma_f32_16x16x32_bf16 v[12:15], v[210:213], v[234:237], v[12:15]
	v_mfma_f32_16x16x32_bf16 v[16:19], v[162:165], v[242:245], v[16:19]
	v_mfma_f32_16x16x32_bf16 v[8:11], v[176:179], v[242:245], v[8:11]
	v_mfma_f32_16x16x32_bf16 v[4:7], v[184:187], v[242:245], v[4:7]
	v_mfma_f32_16x16x32_bf16 v[0:3], v[210:213], v[242:245], v[0:3]
	s_setprio 0
	s_barrier
; #define PG8_STAGE(bufoff, gbase, voff) do { _Pragma("unroll") for (int _i = 0; _i < 2; ++_i) \
;         __builtin_amdgcn_global_load_lds((const unsigned*)((const char*)(gbase) + (voff)[_i]), (PG8_LAS unsigned*)(lds + (bufoff) + ldsw + _i * 8192), 16, 0, 0); } while (0)
; #define PG8_LDA(dst, b, h) do { _Pragma("unroll") for (int m = 0; m < 4; ++m) _Pragma("unroll") for (int k = 0; k < 2; ++k) dst[m][k] = *(const PG8_LAS bf16x8*)(lds + PG8_SA(b, h) + aoff + m * 2048 + k * 1024); } while (0)
; #define PG8_LDB(dst, b, h) do { _Pragma("unroll") for (int n = 0; n < 2; ++n) _Pragma("unroll") for (int k = 0; k < 2; ++k) dst[n][k] = *(const PG8_LAS bf16x8*)(lds + PG8_SB(b, h) + boff + n * 2048 + k * 1024); } while (0)
; #define PG8_MMA(ai, bj, At, Bt) do { __builtin_amdgcn_s_setprio(1); _Pragma("unroll") for (int m = 0; m < 4; ++m) _Pragma("unroll") for (int n = 0; n < 2; ++n) _Pragma("unroll") for (int k = 0; k < 2; ++k) \
;         acc[ai][bj][m][n] = __builtin_amdgcn_mfma_f32_16x16x32_bf16(Bt[n][k], At[m][k], acc[ai][bj][m][n], 0, 0, 0); __builtin_amdgcn_s_setprio(0); } while (0)
; #define PG8_WAIT_V(n) asm volatile("s_waitcnt vmcnt(" #n ")" ::: "memory")
; #define PG8_WAIT_L(n) asm volatile("s_waitcnt lgkmcnt(" #n ")" ::: "memory")
; #define PG8_BAR __builtin_amdgcn_s_barrier()
; #define PG8_SCHED __builtin_amdgcn_sched_barrier(0)
; template <class Epi, class Sched, bool ALIGN_EPI = false, bool SP2 = false>
; __device__ __forceinline__ void gemm_phase(PG8_LAS unsigned char* lds, const Gemm g, const Sched& S, const Epi& E) {
;     ...
;             PG8_LDB(B0, 1, 0); PG8_LDB(B1, 1, 1); PG8_SCHED; PG8_LDA(At, 1, 0); PG8_STAGE(PG8_SA(0, 1), a2 + hstep, voffA);
;             PG8_WAIT_V(8); PG8_WAIT_L(0); PG8_BAR; PG8_MMA(0, 0, At, B0); PG8_MMA(0, 1, At, B1); PG8_BAR; PG8_SCHED;
;             PG8_LDA(At, 1, 1); PG8_STAGE(PG8_SB(1, 0), b3, voffB); PG8_STAGE(PG8_SB(1, 1), b3 + hstep, voffB); PG8_STAGE(PG8_SA(1, 0), a3, voffA);
;             PG8_WAIT_V(8); PG8_WAIT_L(0); PG8_BAR; PG8_MMA(1, 0, At, B0); PG8_MMA(1, 1, At, B1); PG8_BAR; PG8_SCHED;
	ds_read_b128 v[140:143], v254 offset:32768
	ds_read_b128 v[162:165], v254 offset:33792
	ds_read_b128 v[166:169], v254 offset:34816
	ds_read_b128 v[176:179], v254 offset:35840
	ds_read_b128 v[180:183], v254 offset:49152
	ds_read_b128 v[184:187], v254 offset:50176
	ds_read_b128 v[188:191], v254 offset:51200
	ds_read_b128 v[210:213], v254 offset:52224
	s_add_u32 s4, s4, 0x40000
	s_addc_u32 s5, s5, 0
	s_mov_b32 m0, s33
	ds_read_b128 v[214:217], v173 offset:32768
	ds_read_b128 v[218:221], v173 offset:33792
	ds_read_b128 v[222:225], v173 offset:34816
	ds_read_b128 v[226:229], v173 offset:35840
	ds_read_b128 v[230:233], v173 offset:36864
	ds_read_b128 v[234:237], v173 offset:37888
	ds_read_b128 v[238:241], v173 offset:38912
	ds_read_b128 v[242:245], v173 offset:39936
	global_load_lds_dwordx4 v134, s[4:5]
	s_mov_b32 m0, s34
	s_nop 0
	global_load_lds_dwordx4 v130, s[4:5]
	s_waitcnt vmcnt(8)
	s_waitcnt lgkmcnt(0)
	s_barrier
	s_setprio 1
	v_mfma_f32_16x16x32_bf16 v[124:127], v[140:143], v[214:217], v[124:127]
	v_mfma_f32_16x16x32_bf16 v[120:123], v[166:169], v[214:217], v[120:123]
	v_mfma_f32_16x16x32_bf16 v[116:119], v[180:183], v[214:217], v[116:119]
	v_mfma_f32_16x16x32_bf16 v[108:111], v[188:191], v[214:217], v[108:111]
	v_mfma_f32_16x16x32_bf16 v[112:115], v[140:143], v[222:225], v[112:115]
	v_mfma_f32_16x16x32_bf16 v[104:107], v[166:169], v[222:225], v[104:107]
	v_mfma_f32_16x16x32_bf16 v[100:103], v[180:183], v[222:225], v[100:103]
	v_mfma_f32_16x16x32_bf16 v[92:95], v[188:191], v[222:225], v[92:95]
	v_mfma_f32_16x16x32_bf16 v[96:99], v[140:143], v[230:233], v[96:99]
	v_mfma_f32_16x16x32_bf16 v[88:91], v[166:169], v[230:233], v[88:91]
	v_mfma_f32_16x16x32_bf16 v[84:87], v[180:183], v[230:233], v[84:87]
	v_mfma_f32_16x16x32_bf16 v[76:79], v[188:191], v[230:233], v[76:79]
	v_mfma_f32_16x16x32_bf16 v[80:83], v[140:143], v[238:241], v[80:83]
	v_mfma_f32_16x16x32_bf16 v[72:75], v[166:169], v[238:241], v[72:75]
	v_mfma_f32_16x16x32_bf16 v[68:71], v[180:183], v[238:241], v[68:71]
	v_mfma_f32_16x16x32_bf16 v[64:67], v[188:191], v[238:241], v[64:67]
	v_mfma_f32_16x16x32_bf16 v[124:127], v[162:165], v[218:221], v[124:127]
	v_mfma_f32_16x16x32_bf16 v[120:123], v[176:179], v[218:221], v[120:123]
	v_mfma_f32_16x16x32_bf16 v[116:119], v[184:187], v[218:221], v[116:119]
	v_mfma_f32_16x16x32_bf16 v[108:111], v[210:213], v[218:221], v[108:111]
	v_mfma_f32_16x16x32_bf16 v[112:115], v[162:165], v[226:229], v[112:115]
	v_mfma_f32_16x16x32_bf16 v[104:107], v[176:179], v[226:229], v[104:107]
	v_mfma_f32_16x16x32_bf16 v[100:103], v[184:187], v[226:229], v[100:103]
	v_mfma_f32_16x16x32_bf16 v[92:95], v[210:213], v[226:229], v[92:95]
	v_mfma_f32_16x16x32_bf16 v[96:99], v[162:165], v[234:237], v[96:99]
	v_mfma_f32_16x16x32_bf16 v[88:91], v[176:179], v[234:237], v[88:91]
	v_mfma_f32_16x16x32_bf16 v[84:87], v[184:187], v[234:237], v[84:87]
	v_mfma_f32_16x16x32_bf16 v[76:79], v[210:213], v[234:237], v[76:79]
	v_mfma_f32_16x16x32_bf16 v[80:83], v[162:165], v[242:245], v[80:83]
	v_mfma_f32_16x16x32_bf16 v[72:75], v[176:179], v[242:245], v[72:75]
	v_mfma_f32_16x16x32_bf16 v[68:71], v[184:187], v[242:245], v[68:71]
	v_mfma_f32_16x16x32_bf16 v[64:67], v[210:213], v[242:245], v[64:67]
	s_setprio 0
	s_barrier
	s_mov_b32 m0, s37
	s_add_u32 s2, s2, 0x40080
	s_addc_u32 s3, s3, 0
	ds_read_b128 v[214:217], v173 offset:49152
	ds_read_b128 v[218:221], v173 offset:50176
	ds_read_b128 v[222:225], v173 offset:51200
	ds_read_b128 v[226:229], v173 offset:52224
	ds_read_b128 v[230:233], v173 offset:53248
	ds_read_b128 v[234:237], v173 offset:54272
	ds_read_b128 v[238:241], v173 offset:55296
	ds_read_b128 v[242:245], v173 offset:56320
	s_add_u32 s98, s2, 0xfffc0000
	s_addc_u32 s99, s3, -1
	global_load_lds_dwordx4 v132, s[98:99]
	s_mov_b32 m0, s38
	s_nop 0
	global_load_lds_dwordx4 v128, s[98:99]
	s_mov_b32 m0, s41
	s_nop 0
	global_load_lds_dwordx4 v132, s[2:3]
	s_mov_b32 m0, s42
	s_nop 0
	global_load_lds_dwordx4 v128, s[2:3]
	s_mov_b32 m0, s39
	s_nop 0
	s_add_u32 s100, s4, 0xfffc0080
	s_addc_u32 s101, s5, -1
	global_load_lds_dwordx4 v134, s[100:101]
	s_mov_b32 m0, s40
	s_nop 0
	global_load_lds_dwordx4 v130, s[100:101]
	s_waitcnt vmcnt(8)
	s_waitcnt lgkmcnt(0)
	s_barrier
	s_setprio 1
	v_mfma_f32_16x16x32_bf16 v[60:63], v[140:143], v[214:217], v[60:63]
	v_mfma_f32_16x16x32_bf16 v[56:59], v[166:169], v[214:217], v[56:59]
	v_mfma_f32_16x16x32_bf16 v[52:55], v[180:183], v[214:217], v[52:55]
	v_mfma_f32_16x16x32_bf16 v[44:47], v[188:191], v[214:217], v[44:47]
	v_mfma_f32_16x16x32_bf16 v[48:51], v[140:143], v[222:225], v[48:51]
	v_mfma_f32_16x16x32_bf16 v[40:43], v[166:169], v[222:225], v[40:43]
	v_mfma_f32_16x16x32_bf16 v[36:39], v[180:183], v[222:225], v[36:39]
	v_mfma_f32_16x16x32_bf16 v[28:31], v[188:191], v[222:225], v[28:31]
	v_mfma_f32_16x16x32_bf16 v[32:35], v[140:143], v[230:233], v[32:35]
	v_mfma_f32_16x16x32_bf16 v[24:27], v[166:169], v[230:233], v[24:27]
	v_mfma_f32_16x16x32_bf16 v[20:23], v[180:183], v[230:233], v[20:23]
	v_mfma_f32_16x16x32_bf16 v[12:15], v[188:191], v[230:233], v[12:15]
	v_mfma_f32_16x16x32_bf16 v[16:19], v[140:143], v[238:241], v[16:19]
	v_mfma_f32_16x16x32_bf16 v[8:11], v[166:169], v[238:241], v[8:11]
	v_mfma_f32_16x16x32_bf16 v[4:7], v[180:183], v[238:241], v[4:7]
	v_mfma_f32_16x16x32_bf16 v[0:3], v[188:191], v[238:241], v[0:3]
	v_mfma_f32_16x16x32_bf16 v[60:63], v[162:165], v[218:221], v[60:63]
	v_mfma_f32_16x16x32_bf16 v[56:59], v[176:179], v[218:221], v[56:59]
	v_mfma_f32_16x16x32_bf16 v[52:55], v[184:187], v[218:221], v[52:55]
	v_mfma_f32_16x16x32_bf16 v[44:47], v[210:213], v[218:221], v[44:47]
	v_mfma_f32_16x16x32_bf16 v[48:51], v[162:165], v[226:229], v[48:51]
	v_mfma_f32_16x16x32_bf16 v[40:43], v[176:179], v[226:229], v[40:43]
	v_mfma_f32_16x16x32_bf16 v[36:39], v[184:187], v[226:229], v[36:39]
	v_mfma_f32_16x16x32_bf16 v[28:31], v[210:213], v[226:229], v[28:31]
	v_mfma_f32_16x16x32_bf16 v[32:35], v[162:165], v[234:237], v[32:35]
	v_mfma_f32_16x16x32_bf16 v[24:27], v[176:179], v[234:237], v[24:27]
	v_mfma_f32_16x16x32_bf16 v[20:23], v[184:187], v[234:237], v[20:23]
	v_mfma_f32_16x16x32_bf16 v[12:15], v[210:213], v[234:237], v[12:15]
	v_mfma_f32_16x16x32_bf16 v[16:19], v[162:165], v[242:245], v[16:19]
	v_mfma_f32_16x16x32_bf16 v[8:11], v[176:179], v[242:245], v[8:11]
	v_mfma_f32_16x16x32_bf16 v[4:7], v[184:187], v[242:245], v[4:7]
	v_mfma_f32_16x16x32_bf16 v[0:3], v[210:213], v[242:245], v[0:3]
	s_setprio 0
	s_barrier
	s_add_i32 s52, s52, 2
	s_add_u32 s0, s0, 0x100
	s_addc_u32 s1, s1, 0
	s_add_u32 s50, s50, 0x100
	s_addc_u32 s51, s51, 0
	s_cmp_gt_u32 s52, 13
; #define PG8_STAGE(bufoff, gbase, voff) do { _Pragma("unroll") for (int _i = 0; _i < 2; ++_i) \
;         __builtin_amdgcn_global_load_lds((const unsigned*)((const char*)(gbase) + (voff)[_i]), (PG8_LAS unsigned*)(lds + (bufoff) + ldsw + _i * 8192), 16, 0, 0); } while (0)
; #define PG8_LDA(dst, b, h) do { _Pragma("unroll") for (int m = 0; m < 4; ++m) _Pragma("unroll") for (int k = 0; k < 2; ++k) dst[m][k] = *(const PG8_LAS bf16x8*)(lds + PG8_SA(b, h) + aoff + m * 2048 + k * 1024); } while (0)
; #define PG8_LDB(dst, b, h) do { _Pragma("unroll") for (int n = 0; n < 2; ++n) _Pragma("unroll") for (int k = 0; k < 2; ++k) dst[n][k] = *(const PG8_LAS bf16x8*)(lds + PG8_SB(b, h) + boff + n * 2048 + k * 1024); } while (0)
; #define PG8_MMA(ai, bj, At, Bt) do { __builtin_amdgcn_s_setprio(1); _Pragma("unroll") for (int m = 0; m < 4; ++m) _Pragma("unroll") for (int n = 0; n < 2; ++n) _Pragma("unroll") for (int k = 0; k < 2; ++k) \
;         acc[ai][bj][m][n] = __builtin_amdgcn_mfma_f32_16x16x32_bf16(Bt[n][k], At[m][k], acc[ai][bj][m][n], 0, 0, 0); __builtin_amdgcn_s_setprio(0); } while (0)
; #define PG8_WAIT_V(n) asm volatile("s_waitcnt vmcnt(" #n ")" ::: "memory")
; #define PG8_WAIT_L(n) asm volatile("s_waitcnt lgkmcnt(" #n ")" ::: "memory")
; template <class Epi, class Sched, bool ALIGN_EPI = false, bool SP2 = false>
; __device__ __forceinline__ void gemm_phase(PG8_LAS unsigned char* lds, const Gemm g, const Sched& S, const Epi& E) {
;     ...
;             const bool last = (t == nt - 2);
;             const char* a1 = cA + (size_t)(t + 1) * kstep;
;             const char* a2 = last ? nA : cA + (size_t)(t + 2) * kstep; const char* b2 = last ? nB : cB + (size_t)(t + 2) * kstep;
;             const char* a3 = a2 + kstep; const char* b3 = b2 + kstep;
;             if (last && has_next) S.a_ready(nxt);
;             if constexpr (SP2) {
;             PG8_LDB(B0, 0, 0); PG8_LDB(B1, 0, 1); PG8_SCHED; PG8_LDA(At, 0, 0); PG8_STAGE(PG8_SA(1, 1), a1 + hstep, voffA);
;             PG8_WAIT_V(8); PG8_WAIT_L(0); PG8_BAR; PG8_MMA(0, 0, At, B0); PG8_MMA(0, 1, At, B1); PG8_BAR; PG8_SCHED;
;             PG8_LDA(At, 0, 1); PG8_STAGE(PG8_SB(0, 0), b2, voffB); PG8_STAGE(PG8_SB(0, 1), b2 + hstep, voffB); PG8_STAGE(PG8_SA(0, 0), a2, voffA);
;             PG8_WAIT_V(8); PG8_WAIT_L(0); PG8_BAR; PG8_MMA(1, 0, At, B0); PG8_MMA(1, 1, At, B1); PG8_BAR; PG8_SCHED;
.LBB0_792:
	s_waitcnt lgkmcnt(0)
	ds_read_b128 v[140:143], v254
	ds_read_b128 v[162:165], v254 offset:1024
	ds_read_b128 v[166:169], v254 offset:2048
	ds_read_b128 v[176:179], v254 offset:3072
	ds_read_b128 v[180:183], v254 offset:16384
	ds_read_b128 v[184:187], v254 offset:17408
	ds_read_b128 v[188:191], v254 offset:18432
	ds_read_b128 v[210:213], v254 offset:19456
	s_add_u32 s2, s0, 0xfffc0080
	s_addc_u32 s3, s1, -1
	s_cmp_eq_u32 s52, 12
	s_cselect_b32 s5, s17, s3
	s_cselect_b32 s4, s48, s2
	s_cselect_b32 s3, s15, s51
	s_cselect_b32 s2, s49, s50
	s_add_i32 m0, s6, 0xc000
	ds_read_b128 v[214:217], v173
	ds_read_b128 v[218:221], v173 offset:1024
	ds_read_b128 v[222:225], v173 offset:2048
	ds_read_b128 v[226:229], v173 offset:3072
	ds_read_b128 v[230:233], v173 offset:4096
	ds_read_b128 v[234:237], v173 offset:5120
	ds_read_b128 v[238:241], v173 offset:6144
	ds_read_b128 v[242:245], v173 offset:7168
	global_load_lds_dwordx4 v136, s[0:1]
	s_add_i32 m0, s6, 0xe000
	s_nop 0
	global_load_lds_dwordx4 v138, s[0:1]
	s_waitcnt vmcnt(8)
	s_waitcnt lgkmcnt(0)
	s_barrier
	s_setprio 1
	v_mfma_f32_16x16x32_bf16 v[124:127], v[140:143], v[214:217], v[124:127]
	v_mfma_f32_16x16x32_bf16 v[120:123], v[166:169], v[214:217], v[120:123]
	v_mfma_f32_16x16x32_bf16 v[116:119], v[180:183], v[214:217], v[116:119]
	v_mfma_f32_16x16x32_bf16 v[108:111], v[188:191], v[214:217], v[108:111]
	v_mfma_f32_16x16x32_bf16 v[112:115], v[140:143], v[222:225], v[112:115]
	v_mfma_f32_16x16x32_bf16 v[104:107], v[166:169], v[222:225], v[104:107]
	v_mfma_f32_16x16x32_bf16 v[100:103], v[180:183], v[222:225], v[100:103]
	v_mfma_f32_16x16x32_bf16 v[92:95], v[188:191], v[222:225], v[92:95]
	v_mfma_f32_16x16x32_bf16 v[96:99], v[140:143], v[230:233], v[96:99]
	v_mfma_f32_16x16x32_bf16 v[88:91], v[166:169], v[230:233], v[88:91]
	v_mfma_f32_16x16x32_bf16 v[84:87], v[180:183], v[230:233], v[84:87]
	v_mfma_f32_16x16x32_bf16 v[76:79], v[188:191], v[230:233], v[76:79]
	v_mfma_f32_16x16x32_bf16 v[80:83], v[140:143], v[238:241], v[80:83]
	v_mfma_f32_16x16x32_bf16 v[72:75], v[166:169], v[238:241], v[72:75]
	v_mfma_f32_16x16x32_bf16 v[68:71], v[180:183], v[238:241], v[68:71]
	v_mfma_f32_16x16x32_bf16 v[64:67], v[188:191], v[238:241], v[64:67]
	v_mfma_f32_16x16x32_bf16 v[124:127], v[162:165], v[218:221], v[124:127]
	v_mfma_f32_16x16x32_bf16 v[120:123], v[176:179], v[218:221], v[120:123]
	v_mfma_f32_16x16x32_bf16 v[116:119], v[184:187], v[218:221], v[116:119]
	v_mfma_f32_16x16x32_bf16 v[108:111], v[210:213], v[218:221], v[108:111]
	v_mfma_f32_16x16x32_bf16 v[112:115], v[162:165], v[226:229], v[112:115]
	v_mfma_f32_16x16x32_bf16 v[104:107], v[176:179], v[226:229], v[104:107]
	v_mfma_f32_16x16x32_bf16 v[100:103], v[184:187], v[226:229], v[100:103]
	v_mfma_f32_16x16x32_bf16 v[92:95], v[210:213], v[226:229], v[92:95]
	v_mfma_f32_16x16x32_bf16 v[96:99], v[162:165], v[234:237], v[96:99]
	v_mfma_f32_16x16x32_bf16 v[88:91], v[176:179], v[234:237], v[88:91]
	v_mfma_f32_16x16x32_bf16 v[84:87], v[184:187], v[234:237], v[84:87]
	v_mfma_f32_16x16x32_bf16 v[76:79], v[210:213], v[234:237], v[76:79]
	v_mfma_f32_16x16x32_bf16 v[80:83], v[162:165], v[242:245], v[80:83]
	v_mfma_f32_16x16x32_bf16 v[72:75], v[176:179], v[242:245], v[72:75]
	v_mfma_f32_16x16x32_bf16 v[68:71], v[184:187], v[242:245], v[68:71]
	v_mfma_f32_16x16x32_bf16 v[64:67], v[210:213], v[242:245], v[64:67]
	s_setprio 0
	s_barrier
	s_mov_b32 m0, s27
	s_add_u32 s54, s2, 0x40000
	s_addc_u32 s55, s3, 0
	ds_read_b128 v[214:217], v173 offset:16384
	ds_read_b128 v[218:221], v173 offset:17408
	ds_read_b128 v[222:225], v173 offset:18432
	ds_read_b128 v[226:229], v173 offset:19456
	ds_read_b128 v[230:233], v173 offset:20480
	ds_read_b128 v[234:237], v173 offset:21504
	ds_read_b128 v[238:241], v173 offset:22528
	ds_read_b128 v[242:245], v173 offset:23552
	global_load_lds_dwordx4 v132, s[2:3]
	s_mov_b32 m0, s28
	s_nop 0
	global_load_lds_dwordx4 v128, s[2:3]
	s_mov_b32 m0, s29
	s_nop 0
	global_load_lds_dwordx4 v132, s[54:55]
	s_mov_b32 m0, s30
	s_nop 0
	global_load_lds_dwordx4 v128, s[54:55]
	s_mov_b32 m0, s6
	s_nop 0
	global_load_lds_dwordx4 v134, s[4:5]
	s_mov_b32 m0, s31
	s_nop 0
	global_load_lds_dwordx4 v130, s[4:5]
	s_waitcnt vmcnt(8)
	s_waitcnt lgkmcnt(0)
	s_barrier
	s_setprio 1
	v_mfma_f32_16x16x32_bf16 v[60:63], v[140:143], v[214:217], v[60:63]
	v_mfma_f32_16x16x32_bf16 v[56:59], v[166:169], v[214:217], v[56:59]
	v_mfma_f32_16x16x32_bf16 v[52:55], v[180:183], v[214:217], v[52:55]
	v_mfma_f32_16x16x32_bf16 v[44:47], v[188:191], v[214:217], v[44:47]
	v_mfma_f32_16x16x32_bf16 v[48:51], v[140:143], v[222:225], v[48:51]
	v_mfma_f32_16x16x32_bf16 v[40:43], v[166:169], v[222:225], v[40:43]
	v_mfma_f32_16x16x32_bf16 v[36:39], v[180:183], v[222:225], v[36:39]
	v_mfma_f32_16x16x32_bf16 v[28:31], v[188:191], v[222:225], v[28:31]
	v_mfma_f32_16x16x32_bf16 v[32:35], v[140:143], v[230:233], v[32:35]
	v_mfma_f32_16x16x32_bf16 v[24:27], v[166:169], v[230:233], v[24:27]
	v_mfma_f32_16x16x32_bf16 v[20:23], v[180:183], v[230:233], v[20:23]
	v_mfma_f32_16x16x32_bf16 v[12:15], v[188:191], v[230:233], v[12:15]
	v_mfma_f32_16x16x32_bf16 v[16:19], v[140:143], v[238:241], v[16:19]
	v_mfma_f32_16x16x32_bf16 v[8:11], v[166:169], v[238:241], v[8:11]
	v_mfma_f32_16x16x32_bf16 v[4:7], v[180:183], v[238:241], v[4:7]
	v_mfma_f32_16x16x32_bf16 v[0:3], v[188:191], v[238:241], v[0:3]
	v_mfma_f32_16x16x32_bf16 v[60:63], v[162:165], v[218:221], v[60:63]
	v_mfma_f32_16x16x32_bf16 v[56:59], v[176:179], v[218:221], v[56:59]
	v_mfma_f32_16x16x32_bf16 v[52:55], v[184:187], v[218:221], v[52:55]
	v_mfma_f32_16x16x32_bf16 v[44:47], v[210:213], v[218:221], v[44:47]
	v_mfma_f32_16x16x32_bf16 v[48:51], v[162:165], v[226:229], v[48:51]
	v_mfma_f32_16x16x32_bf16 v[40:43], v[176:179], v[226:229], v[40:43]
	v_mfma_f32_16x16x32_bf16 v[36:39], v[184:187], v[226:229], v[36:39]
	v_mfma_f32_16x16x32_bf16 v[28:31], v[210:213], v[226:229], v[28:31]
	v_mfma_f32_16x16x32_bf16 v[32:35], v[162:165], v[234:237], v[32:35]
	v_mfma_f32_16x16x32_bf16 v[24:27], v[176:179], v[234:237], v[24:27]
	v_mfma_f32_16x16x32_bf16 v[20:23], v[184:187], v[234:237], v[20:23]
	v_mfma_f32_16x16x32_bf16 v[12:15], v[210:213], v[234:237], v[12:15]
	v_mfma_f32_16x16x32_bf16 v[16:19], v[162:165], v[242:245], v[16:19]
	v_mfma_f32_16x16x32_bf16 v[8:11], v[176:179], v[242:245], v[8:11]
	v_mfma_f32_16x16x32_bf16 v[4:7], v[184:187], v[242:245], v[4:7]
	v_mfma_f32_16x16x32_bf16 v[0:3], v[210:213], v[242:245], v[0:3]
	s_setprio 0
	s_barrier
; #define PG8_STAGE(bufoff, gbase, voff) do { _Pragma("unroll") for (int _i = 0; _i < 2; ++_i) \
;         __builtin_amdgcn_global_load_lds((const unsigned*)((const char*)(gbase) + (voff)[_i]), (PG8_LAS unsigned*)(lds + (bufoff) + ldsw + _i * 8192), 16, 0, 0); } while (0)
; #define PG8_LDA(dst, b, h) do { _Pragma("unroll") for (int m = 0; m < 4; ++m) _Pragma("unroll") for (int k = 0; k < 2; ++k) dst[m][k] = *(const PG8_LAS bf16x8*)(lds + PG8_SA(b, h) + aoff + m * 2048 + k * 1024); } while (0)
; #define PG8_LDB(dst, b, h) do { _Pragma("unroll") for (int n = 0; n < 2; ++n) _Pragma("unroll") for (int k = 0; k < 2; ++k) dst[n][k] = *(const PG8_LAS bf16x8*)(lds + PG8_SB(b, h) + boff + n * 2048 + k * 1024); } while (0)
; #define PG8_MMA(ai, bj, At, Bt) do { __builtin_amdgcn_s_setprio(1); _Pragma("unroll") for (int m = 0; m < 4; ++m) _Pragma("unroll") for (int n = 0; n < 2; ++n) _Pragma("unroll") for (int k = 0; k < 2; ++k) \
;         acc[ai][bj][m][n] = __builtin_amdgcn_mfma_f32_16x16x32_bf16(Bt[n][k], At[m][k], acc[ai][bj][m][n], 0, 0, 0); __builtin_amdgcn_s_setprio(0); } while (0)
; #define PG8_WAIT_V(n) asm volatile("s_waitcnt vmcnt(" #n ")" ::: "memory")
; #define PG8_WAIT_L(n) asm volatile("s_waitcnt lgkmcnt(" #n ")" ::: "memory")
; #define PG8_BAR __builtin_amdgcn_s_barrier()
; #define PG8_SCHED __builtin_amdgcn_sched_barrier(0)
; template <class Epi, class Sched, bool ALIGN_EPI = false, bool SP2 = false>
; __device__ __forceinline__ void gemm_phase(PG8_LAS unsigned char* lds, const Gemm g, const Sched& S, const Epi& E) {
;     ...
;             PG8_LDB(B0, 1, 0); PG8_LDB(B1, 1, 1); PG8_SCHED; PG8_LDA(At, 1, 0); PG8_STAGE(PG8_SA(0, 1), a2 + hstep, voffA);
;             PG8_WAIT_V(8); PG8_WAIT_L(0); PG8_BAR; PG8_MMA(0, 0, At, B0); PG8_MMA(0, 1, At, B1); PG8_BAR; PG8_SCHED;
;             PG8_LDA(At, 1, 1); PG8_STAGE(PG8_SB(1, 0), b3, voffB); PG8_STAGE(PG8_SB(1, 1), b3 + hstep, voffB); PG8_STAGE(PG8_SA(1, 0), a3, voffA);
;             PG8_WAIT_V(8); PG8_WAIT_L(0); PG8_BAR; PG8_MMA(1, 0, At, B0); PG8_MMA(1, 1, At, B1); PG8_BAR; PG8_SCHED;
;     ...
;         if constexpr (ALIGN_EPI) { if (wr == 0) PG8_BAR; }
	ds_read_b128 v[140:143], v254 offset:32768
	ds_read_b128 v[162:165], v254 offset:33792
	ds_read_b128 v[166:169], v254 offset:34816
	ds_read_b128 v[176:179], v254 offset:35840
	ds_read_b128 v[180:183], v254 offset:49152
	ds_read_b128 v[184:187], v254 offset:50176
	ds_read_b128 v[188:191], v254 offset:51200
	ds_read_b128 v[210:213], v254 offset:52224
	s_add_u32 s4, s4, 0x40000
	s_addc_u32 s5, s5, 0
	s_mov_b32 m0, s33
	ds_read_b128 v[214:217], v173 offset:32768
	ds_read_b128 v[218:221], v173 offset:33792
	ds_read_b128 v[222:225], v173 offset:34816
	ds_read_b128 v[226:229], v173 offset:35840
	ds_read_b128 v[230:233], v173 offset:36864
	ds_read_b128 v[234:237], v173 offset:37888
	ds_read_b128 v[238:241], v173 offset:38912
	ds_read_b128 v[242:245], v173 offset:39936
	global_load_lds_dwordx4 v134, s[4:5]
	s_mov_b32 m0, s34
	s_nop 0
	global_load_lds_dwordx4 v130, s[4:5]
	s_waitcnt vmcnt(8)
	s_waitcnt lgkmcnt(0)
	s_barrier
	s_setprio 1
	v_mfma_f32_16x16x32_bf16 v[124:127], v[140:143], v[214:217], v[124:127]
	v_mfma_f32_16x16x32_bf16 v[120:123], v[166:169], v[214:217], v[120:123]
	v_mfma_f32_16x16x32_bf16 v[116:119], v[180:183], v[214:217], v[116:119]
	v_mfma_f32_16x16x32_bf16 v[108:111], v[188:191], v[214:217], v[108:111]
	v_mfma_f32_16x16x32_bf16 v[112:115], v[140:143], v[222:225], v[112:115]
	v_mfma_f32_16x16x32_bf16 v[104:107], v[166:169], v[222:225], v[104:107]
	v_mfma_f32_16x16x32_bf16 v[100:103], v[180:183], v[222:225], v[100:103]
	v_mfma_f32_16x16x32_bf16 v[92:95], v[188:191], v[222:225], v[92:95]
	v_mfma_f32_16x16x32_bf16 v[96:99], v[140:143], v[230:233], v[96:99]
	v_mfma_f32_16x16x32_bf16 v[88:91], v[166:169], v[230:233], v[88:91]
	v_mfma_f32_16x16x32_bf16 v[84:87], v[180:183], v[230:233], v[84:87]
	v_mfma_f32_16x16x32_bf16 v[76:79], v[188:191], v[230:233], v[76:79]
	v_mfma_f32_16x16x32_bf16 v[80:83], v[140:143], v[238:241], v[80:83]
	v_mfma_f32_16x16x32_bf16 v[72:75], v[166:169], v[238:241], v[72:75]
	v_mfma_f32_16x16x32_bf16 v[68:71], v[180:183], v[238:241], v[68:71]
	v_mfma_f32_16x16x32_bf16 v[64:67], v[188:191], v[238:241], v[64:67]
	v_mfma_f32_16x16x32_bf16 v[124:127], v[162:165], v[218:221], v[124:127]
	v_mfma_f32_16x16x32_bf16 v[120:123], v[176:179], v[218:221], v[120:123]
	v_mfma_f32_16x16x32_bf16 v[116:119], v[184:187], v[218:221], v[116:119]
	v_mfma_f32_16x16x32_bf16 v[108:111], v[210:213], v[218:221], v[108:111]
	v_mfma_f32_16x16x32_bf16 v[112:115], v[162:165], v[226:229], v[112:115]
	v_mfma_f32_16x16x32_bf16 v[104:107], v[176:179], v[226:229], v[104:107]
	v_mfma_f32_16x16x32_bf16 v[100:103], v[184:187], v[226:229], v[100:103]
	v_mfma_f32_16x16x32_bf16 v[92:95], v[210:213], v[226:229], v[92:95]
	v_mfma_f32_16x16x32_bf16 v[96:99], v[162:165], v[234:237], v[96:99]
	v_mfma_f32_16x16x32_bf16 v[88:91], v[176:179], v[234:237], v[88:91]
	v_mfma_f32_16x16x32_bf16 v[84:87], v[184:187], v[234:237], v[84:87]
	v_mfma_f32_16x16x32_bf16 v[76:79], v[210:213], v[234:237], v[76:79]
	v_mfma_f32_16x16x32_bf16 v[80:83], v[162:165], v[242:245], v[80:83]
	v_mfma_f32_16x16x32_bf16 v[72:75], v[176:179], v[242:245], v[72:75]
	v_mfma_f32_16x16x32_bf16 v[68:71], v[184:187], v[242:245], v[68:71]
	v_mfma_f32_16x16x32_bf16 v[64:67], v[210:213], v[242:245], v[64:67]
	s_setprio 0
	s_barrier
	s_mov_b32 m0, s37
	s_add_u32 s2, s2, 0x40080
	s_addc_u32 s3, s3, 0
	ds_read_b128 v[214:217], v173 offset:49152
	ds_read_b128 v[218:221], v173 offset:50176
	ds_read_b128 v[222:225], v173 offset:51200
	ds_read_b128 v[226:229], v173 offset:52224
	ds_read_b128 v[230:233], v173 offset:53248
	ds_read_b128 v[234:237], v173 offset:54272
	ds_read_b128 v[238:241], v173 offset:55296
	ds_read_b128 v[242:245], v173 offset:56320
	s_add_u32 s98, s2, 0xfffc0000
	s_addc_u32 s99, s3, -1
	global_load_lds_dwordx4 v132, s[98:99]
	s_mov_b32 m0, s38
	s_nop 0
	global_load_lds_dwordx4 v128, s[98:99]
	s_mov_b32 m0, s41
	s_nop 0
	global_load_lds_dwordx4 v132, s[2:3]
	s_mov_b32 m0, s42
	s_nop 0
	global_load_lds_dwordx4 v128, s[2:3]
	s_mov_b32 m0, s39
	s_nop 0
	s_add_u32 s100, s4, 0xfffc0080
	s_addc_u32 s101, s5, -1
	global_load_lds_dwordx4 v134, s[100:101]
	s_mov_b32 m0, s40
	s_nop 0
	global_load_lds_dwordx4 v130, s[100:101]
	s_waitcnt vmcnt(8)
	s_waitcnt lgkmcnt(0)
	s_barrier
	s_setprio 1
	v_mfma_f32_16x16x32_bf16 v[60:63], v[140:143], v[214:217], v[60:63]
	v_mfma_f32_16x16x32_bf16 v[56:59], v[166:169], v[214:217], v[56:59]
	v_mfma_f32_16x16x32_bf16 v[52:55], v[180:183], v[214:217], v[52:55]
	v_mfma_f32_16x16x32_bf16 v[44:47], v[188:191], v[214:217], v[44:47]
	v_mfma_f32_16x16x32_bf16 v[48:51], v[140:143], v[222:225], v[48:51]
	v_mfma_f32_16x16x32_bf16 v[40:43], v[166:169], v[222:225], v[40:43]
	v_mfma_f32_16x16x32_bf16 v[36:39], v[180:183], v[222:225], v[36:39]
	v_mfma_f32_16x16x32_bf16 v[28:31], v[188:191], v[222:225], v[28:31]
	v_mfma_f32_16x16x32_bf16 v[32:35], v[140:143], v[230:233], v[32:35]
	v_mfma_f32_16x16x32_bf16 v[24:27], v[166:169], v[230:233], v[24:27]
	v_mfma_f32_16x16x32_bf16 v[20:23], v[180:183], v[230:233], v[20:23]
	v_mfma_f32_16x16x32_bf16 v[12:15], v[188:191], v[230:233], v[12:15]
	v_mfma_f32_16x16x32_bf16 v[16:19], v[140:143], v[238:241], v[16:19]
	v_mfma_f32_16x16x32_bf16 v[8:11], v[166:169], v[238:241], v[8:11]
	v_mfma_f32_16x16x32_bf16 v[4:7], v[180:183], v[238:241], v[4:7]
	v_mfma_f32_16x16x32_bf16 v[0:3], v[188:191], v[238:241], v[0:3]
	v_mfma_f32_16x16x32_bf16 v[60:63], v[162:165], v[218:221], v[60:63]
	v_mfma_f32_16x16x32_bf16 v[56:59], v[176:179], v[218:221], v[56:59]
	v_mfma_f32_16x16x32_bf16 v[52:55], v[184:187], v[218:221], v[52:55]
	v_mfma_f32_16x16x32_bf16 v[44:47], v[210:213], v[218:221], v[44:47]
	v_mfma_f32_16x16x32_bf16 v[48:51], v[162:165], v[226:229], v[48:51]
	v_mfma_f32_16x16x32_bf16 v[40:43], v[176:179], v[226:229], v[40:43]
	v_mfma_f32_16x16x32_bf16 v[36:39], v[184:187], v[226:229], v[36:39]
	v_mfma_f32_16x16x32_bf16 v[28:31], v[210:213], v[226:229], v[28:31]
	v_mfma_f32_16x16x32_bf16 v[32:35], v[162:165], v[234:237], v[32:35]
	v_mfma_f32_16x16x32_bf16 v[24:27], v[176:179], v[234:237], v[24:27]
	v_mfma_f32_16x16x32_bf16 v[20:23], v[184:187], v[234:237], v[20:23]
	v_mfma_f32_16x16x32_bf16 v[12:15], v[210:213], v[234:237], v[12:15]
	v_mfma_f32_16x16x32_bf16 v[16:19], v[162:165], v[242:245], v[16:19]
	v_mfma_f32_16x16x32_bf16 v[8:11], v[176:179], v[242:245], v[8:11]
	v_mfma_f32_16x16x32_bf16 v[4:7], v[184:187], v[242:245], v[4:7]
	v_mfma_f32_16x16x32_bf16 v[0:3], v[210:213], v[242:245], v[0:3]
	s_setprio 0
	s_barrier
	s_add_i32 s52, s52, 2
	s_add_u32 s0, s0, 0x100
	s_addc_u32 s1, s1, 0
	s_add_u32 s50, s50, 0x100
	s_addc_u32 s51, s51, 0
	s_cmp_gt_u32 s52, 13
	s_cbranch_scc0 .LBB0_792
	s_and_b64 vcc, exec, s[12:13]
	s_cbranch_vccz .LBB0_795
	s_barrier

; #define PG8_STAGE(bufoff, gbase, voff) do { _Pragma("unroll") for (int _i = 0; _i < 2; ++_i) \
;         __builtin_amdgcn_global_load_lds((const unsigned*)((const char*)(gbase) + (voff)[_i]), (PG8_LAS unsigned*)(lds + (bufoff) + ldsw + _i * 8192), 16, 0, 0); } while (0)
; #define PG8_LDA(dst, b, h) do { _Pragma("unroll") for (int m = 0; m < 4; ++m) _Pragma("unroll") for (int k = 0; k < 2; ++k) dst[m][k] = *(const PG8_LAS bf16x8*)(lds + PG8_SA(b, h) + aoff + m * 2048 + k * 1024); } while (0)
; #define PG8_LDB(dst, b, h) do { _Pragma("unroll") for (int n = 0; n < 2; ++n) _Pragma("unroll") for (int k = 0; k < 2; ++k) dst[n][k] = *(const PG8_LAS bf16x8*)(lds + PG8_SB(b, h) + boff + n * 2048 + k * 1024); } while (0)
; #define PG8_MMA(ai, bj, At, Bt) do { __builtin_amdgcn_s_setprio(1); _Pragma("unroll") for (int m = 0; m < 4; ++m) _Pragma("unroll") for (int n = 0; n < 2; ++n) _Pragma("unroll") for (int k = 0; k < 2; ++k) \
;         acc[ai][bj][m][n] = __builtin_amdgcn_mfma_f32_16x16x32_bf16(Bt[n][k], At[m][k], acc[ai][bj][m][n], 0, 0, 0); __builtin_amdgcn_s_setprio(0); } while (0)
; #define PG8_WAIT_V(n) asm volatile("s_waitcnt vmcnt(" #n ")" ::: "memory")
; #define PG8_WAIT_L(n) asm volatile("s_waitcnt lgkmcnt(" #n ")" ::: "memory")
; template <class Epi, class Sched, bool ALIGN_EPI = false, bool SP2 = false>
; __device__ __forceinline__ void gemm_phase(PG8_LAS unsigned char* lds, const Gemm g, const Sched& S, const Epi& E) {
;     ...
;             const bool last = (t == nt - 2);
;             const char* a1 = cA + (size_t)(t + 1) * kstep;
;             const char* a2 = last ? nA : cA + (size_t)(t + 2) * kstep; const char* b2 = last ? nB : cB + (size_t)(t + 2) * kstep;
;             const char* a3 = a2 + kstep; const char* b3 = b2 + kstep;
;             if (last && has_next) S.a_ready(nxt);
;             if constexpr (SP2) {
;             PG8_LDB(B0, 0, 0); PG8_LDB(B1, 0, 1); PG8_SCHED; PG8_LDA(At, 0, 0); PG8_STAGE(PG8_SA(1, 1), a1 + hstep, voffA);
;             PG8_WAIT_V(8); PG8_WAIT_L(0); PG8_BAR; PG8_MMA(0, 0, At, B0); PG8_MMA(0, 1, At, B1); PG8_BAR; PG8_SCHED;
;             PG8_LDA(At, 0, 1); PG8_STAGE(PG8_SB(0, 0), b2, voffB); PG8_STAGE(PG8_SB(0, 1), b2 + hstep, voffB); PG8_STAGE(PG8_SA(0, 0), a2, voffA);
;             PG8_WAIT_V(8); PG8_WAIT_L(0); PG8_BAR; PG8_MMA(1, 0, At, B0); PG8_MMA(1, 1, At, B1); PG8_BAR; PG8_SCHED;
.Lsgo_peel:
	ds_read_b128 v[140:143], v254
	ds_read_b128 v[166:169], v254 offset:1024
	ds_read_b128 v[170:173], v254 offset:2048
	ds_read_b128 v[174:177], v254 offset:3072
	ds_read_b128 v[178:181], v254 offset:16384
	ds_read_b128 v[182:185], v254 offset:17408
	ds_read_b128 v[186:189], v254 offset:18432
	ds_read_b128 v[210:213], v254 offset:19456
	s_add_u32 s2, s0, 0xfffc0080
	s_addc_u32 s3, s1, -1
	s_cmp_eq_u32 s55, 12
	s_cselect_b32 s5, s23, s3
	s_cselect_b32 s4, s51, s2
	s_cselect_b32 s3, s21, s54
	s_cselect_b32 s2, s52, s53
	s_add_i32 m0, s31, 0xc000
	ds_read_b128 v[214:217], v163
	ds_read_b128 v[218:221], v163 offset:1024
	ds_read_b128 v[222:225], v163 offset:2048
	ds_read_b128 v[226:229], v163 offset:3072
	ds_read_b128 v[230:233], v163 offset:4096
	ds_read_b128 v[234:237], v163 offset:5120
	ds_read_b128 v[238:241], v163 offset:6144
	ds_read_b128 v[242:245], v163 offset:7168
	global_load_lds_dwordx4 v136, s[0:1]
	s_add_i32 m0, s31, 0xe000
	s_nop 0
	global_load_lds_dwordx4 v138, s[0:1]
	s_waitcnt vmcnt(8)
	s_waitcnt lgkmcnt(0)
	s_barrier
	s_setprio 1
	v_mfma_f32_16x16x32_bf16 v[124:127], v[140:143], v[214:217], 0
	v_mfma_f32_16x16x32_bf16 v[120:123], v[170:173], v[214:217], 0
	v_mfma_f32_16x16x32_bf16 v[116:119], v[178:181], v[214:217], 0
	v_mfma_f32_16x16x32_bf16 v[112:115], v[186:189], v[214:217], 0
	v_mfma_f32_16x16x32_bf16 v[108:111], v[140:143], v[222:225], 0
	v_mfma_f32_16x16x32_bf16 v[104:107], v[170:173], v[222:225], 0
	v_mfma_f32_16x16x32_bf16 v[100:103], v[178:181], v[222:225], 0
	v_mfma_f32_16x16x32_bf16 v[96:99], v[186:189], v[222:225], 0
	v_mfma_f32_16x16x32_bf16 v[92:95], v[140:143], v[230:233], 0
	v_mfma_f32_16x16x32_bf16 v[88:91], v[170:173], v[230:233], 0
	v_mfma_f32_16x16x32_bf16 v[84:87], v[178:181], v[230:233], 0
	v_mfma_f32_16x16x32_bf16 v[80:83], v[186:189], v[230:233], 0
	v_mfma_f32_16x16x32_bf16 v[76:79], v[140:143], v[238:241], 0
	v_mfma_f32_16x16x32_bf16 v[72:75], v[170:173], v[238:241], 0
	v_mfma_f32_16x16x32_bf16 v[68:71], v[178:181], v[238:241], 0
	v_mfma_f32_16x16x32_bf16 v[64:67], v[186:189], v[238:241], 0
	v_mfma_f32_16x16x32_bf16 v[124:127], v[166:169], v[218:221], v[124:127]
	v_mfma_f32_16x16x32_bf16 v[120:123], v[174:177], v[218:221], v[120:123]
	v_mfma_f32_16x16x32_bf16 v[116:119], v[182:185], v[218:221], v[116:119]
	v_mfma_f32_16x16x32_bf16 v[112:115], v[210:213], v[218:221], v[112:115]
	v_mfma_f32_16x16x32_bf16 v[108:111], v[166:169], v[226:229], v[108:111]
	v_mfma_f32_16x16x32_bf16 v[104:107], v[174:177], v[226:229], v[104:107]
	v_mfma_f32_16x16x32_bf16 v[100:103], v[182:185], v[226:229], v[100:103]
	v_mfma_f32_16x16x32_bf16 v[96:99], v[210:213], v[226:229], v[96:99]
	v_mfma_f32_16x16x32_bf16 v[92:95], v[166:169], v[234:237], v[92:95]
	v_mfma_f32_16x16x32_bf16 v[88:91], v[174:177], v[234:237], v[88:91]
	v_mfma_f32_16x16x32_bf16 v[84:87], v[182:185], v[234:237], v[84:87]
	v_mfma_f32_16x16x32_bf16 v[80:83], v[210:213], v[234:237], v[80:83]
	v_mfma_f32_16x16x32_bf16 v[76:79], v[166:169], v[242:245], v[76:79]
	v_mfma_f32_16x16x32_bf16 v[72:75], v[174:177], v[242:245], v[72:75]
	v_mfma_f32_16x16x32_bf16 v[68:71], v[182:185], v[242:245], v[68:71]
	v_mfma_f32_16x16x32_bf16 v[64:67], v[210:213], v[242:245], v[64:67]
	s_setprio 0
	s_barrier
	s_mov_b32 m0, s33
	s_add_u32 s56, s2, 0x40000
	s_addc_u32 s57, s3, 0
	ds_read_b128 v[214:217], v163 offset:16384
	ds_read_b128 v[218:221], v163 offset:17408
	ds_read_b128 v[222:225], v163 offset:18432
	ds_read_b128 v[226:229], v163 offset:19456
	ds_read_b128 v[230:233], v163 offset:20480
	ds_read_b128 v[234:237], v163 offset:21504
	ds_read_b128 v[238:241], v163 offset:22528
	ds_read_b128 v[242:245], v163 offset:23552
	global_load_lds_dwordx4 v132, s[2:3]
	s_mov_b32 m0, s34
	s_nop 0
	global_load_lds_dwordx4 v128, s[2:3]
	s_mov_b32 m0, s35
	s_nop 0
	global_load_lds_dwordx4 v132, s[56:57]
	s_mov_b32 m0, s36
	s_nop 0
	global_load_lds_dwordx4 v128, s[56:57]
	s_mov_b32 m0, s31
	s_nop 0
	global_load_lds_dwordx4 v134, s[4:5]
	s_mov_b32 m0, s37
	s_nop 0
	global_load_lds_dwordx4 v130, s[4:5]
	s_waitcnt vmcnt(8)
	s_waitcnt lgkmcnt(0)
	s_barrier
	s_setprio 1
	v_mfma_f32_16x16x32_bf16 v[60:63], v[140:143], v[214:217], 0
	v_mfma_f32_16x16x32_bf16 v[56:59], v[170:173], v[214:217], 0
	v_mfma_f32_16x16x32_bf16 v[52:55], v[178:181], v[214:217], 0
	v_mfma_f32_16x16x32_bf16 v[48:51], v[186:189], v[214:217], 0
	v_mfma_f32_16x16x32_bf16 v[44:47], v[140:143], v[222:225], 0
	v_mfma_f32_16x16x32_bf16 v[40:43], v[170:173], v[222:225], 0
	v_mfma_f32_16x16x32_bf16 v[36:39], v[178:181], v[222:225], 0
	v_mfma_f32_16x16x32_bf16 v[32:35], v[186:189], v[222:225], 0
	v_mfma_f32_16x16x32_bf16 v[28:31], v[140:143], v[230:233], 0
	v_mfma_f32_16x16x32_bf16 v[24:27], v[170:173], v[230:233], 0
	v_mfma_f32_16x16x32_bf16 v[20:23], v[178:181], v[230:233], 0
	v_mfma_f32_16x16x32_bf16 v[16:19], v[186:189], v[230:233], 0
	v_mfma_f32_16x16x32_bf16 v[12:15], v[140:143], v[238:241], 0
	v_mfma_f32_16x16x32_bf16 v[8:11], v[170:173], v[238:241], 0
	v_mfma_f32_16x16x32_bf16 v[4:7], v[178:181], v[238:241], 0
	v_mfma_f32_16x16x32_bf16 v[0:3], v[186:189], v[238:241], 0
	v_mfma_f32_16x16x32_bf16 v[60:63], v[166:169], v[218:221], v[60:63]
	v_mfma_f32_16x16x32_bf16 v[56:59], v[174:177], v[218:221], v[56:59]
	v_mfma_f32_16x16x32_bf16 v[52:55], v[182:185], v[218:221], v[52:55]
	v_mfma_f32_16x16x32_bf16 v[48:51], v[210:213], v[218:221], v[48:51]
	v_mfma_f32_16x16x32_bf16 v[44:47], v[166:169], v[226:229], v[44:47]
	v_mfma_f32_16x16x32_bf16 v[40:43], v[174:177], v[226:229], v[40:43]
	v_mfma_f32_16x16x32_bf16 v[36:39], v[182:185], v[226:229], v[36:39]
	v_mfma_f32_16x16x32_bf16 v[32:35], v[210:213], v[226:229], v[32:35]
	v_mfma_f32_16x16x32_bf16 v[28:31], v[166:169], v[234:237], v[28:31]
	v_mfma_f32_16x16x32_bf16 v[24:27], v[174:177], v[234:237], v[24:27]
	v_mfma_f32_16x16x32_bf16 v[20:23], v[182:185], v[234:237], v[20:23]
	v_mfma_f32_16x16x32_bf16 v[16:19], v[210:213], v[234:237], v[16:19]
	v_mfma_f32_16x16x32_bf16 v[12:15], v[166:169], v[242:245], v[12:15]
	v_mfma_f32_16x16x32_bf16 v[8:11], v[174:177], v[242:245], v[8:11]
	v_mfma_f32_16x16x32_bf16 v[4:7], v[182:185], v[242:245], v[4:7]
	v_mfma_f32_16x16x32_bf16 v[0:3], v[210:213], v[242:245], v[0:3]
	s_setprio 0
	s_barrier
; #define PG8_STAGE(bufoff, gbase, voff) do { _Pragma("unroll") for (int _i = 0; _i < 2; ++_i) \
;         __builtin_amdgcn_global_load_lds((const unsigned*)((const char*)(gbase) + (voff)[_i]), (PG8_LAS unsigned*)(lds + (bufoff) + ldsw + _i * 8192), 16, 0, 0); } while (0)
; #define PG8_LDA(dst, b, h) do { _Pragma("unroll") for (int m = 0; m < 4; ++m) _Pragma("unroll") for (int k = 0; k < 2; ++k) dst[m][k] = *(const PG8_LAS bf16x8*)(lds + PG8_SA(b, h) + aoff + m * 2048 + k * 1024); } while (0)
; #define PG8_LDB(dst, b, h) do { _Pragma("unroll") for (int n = 0; n < 2; ++n) _Pragma("unroll") for (int k = 0; k < 2; ++k) dst[n][k] = *(const PG8_LAS bf16x8*)(lds + PG8_SB(b, h) + boff + n * 2048 + k * 1024); } while (0)
; #define PG8_MMA(ai, bj, At, Bt) do { __builtin_amdgcn_s_setprio(1); _Pragma("unroll") for (int m = 0; m < 4; ++m) _Pragma("unroll") for (int n = 0; n < 2; ++n) _Pragma("unroll") for (int k = 0; k < 2; ++k) \
;         acc[ai][bj][m][n] = __builtin_amdgcn_mfma_f32_16x16x32_bf16(Bt[n][k], At[m][k], acc[ai][bj][m][n], 0, 0, 0); __builtin_amdgcn_s_setprio(0); } while (0)
; #define PG8_WAIT_V(n) asm volatile("s_waitcnt vmcnt(" #n ")" ::: "memory")
; #define PG8_WAIT_L(n) asm volatile("s_waitcnt lgkmcnt(" #n ")" ::: "memory")
; #define PG8_BAR __builtin_amdgcn_s_barrier()
; #define PG8_SCHED __builtin_amdgcn_sched_barrier(0)
; template <class Epi, class Sched, bool ALIGN_EPI = false, bool SP2 = false>
; __device__ __forceinline__ void gemm_phase(PG8_LAS unsigned char* lds, const Gemm g, const Sched& S, const Epi& E) {
;     ...
;             PG8_LDB(B0, 1, 0); PG8_LDB(B1, 1, 1); PG8_SCHED; PG8_LDA(At, 1, 0); PG8_STAGE(PG8_SA(0, 1), a2 + hstep, voffA);
;             PG8_WAIT_V(8); PG8_WAIT_L(0); PG8_BAR; PG8_MMA(0, 0, At, B0); PG8_MMA(0, 1, At, B1); PG8_BAR; PG8_SCHED;
;             PG8_LDA(At, 1, 1); PG8_STAGE(PG8_SB(1, 0), b3, voffB); PG8_STAGE(PG8_SB(1, 1), b3 + hstep, voffB); PG8_STAGE(PG8_SA(1, 0), a3, voffA);
;             PG8_WAIT_V(8); PG8_WAIT_L(0); PG8_BAR; PG8_MMA(1, 0, At, B0); PG8_MMA(1, 1, At, B1); PG8_BAR; PG8_SCHED;
	ds_read_b128 v[140:143], v254 offset:32768
	ds_read_b128 v[166:169], v254 offset:33792
	ds_read_b128 v[170:173], v254 offset:34816
	ds_read_b128 v[174:177], v254 offset:35840
	ds_read_b128 v[178:181], v254 offset:49152
	ds_read_b128 v[182:185], v254 offset:50176
	ds_read_b128 v[186:189], v254 offset:51200
	ds_read_b128 v[210:213], v254 offset:52224
	s_add_u32 s4, s4, 0x40000
	s_addc_u32 s5, s5, 0
	s_mov_b32 m0, s38
	ds_read_b128 v[214:217], v163 offset:32768
	ds_read_b128 v[218:221], v163 offset:33792
	ds_read_b128 v[222:225], v163 offset:34816
	ds_read_b128 v[226:229], v163 offset:35840
	ds_read_b128 v[230:233], v163 offset:36864
	ds_read_b128 v[234:237], v163 offset:37888
	ds_read_b128 v[238:241], v163 offset:38912
	ds_read_b128 v[242:245], v163 offset:39936
	global_load_lds_dwordx4 v134, s[4:5]
	s_mov_b32 m0, s39
	s_nop 0
	global_load_lds_dwordx4 v130, s[4:5]
	s_waitcnt vmcnt(8)
	s_waitcnt lgkmcnt(0)
	s_barrier
	s_setprio 1
	v_mfma_f32_16x16x32_bf16 v[124:127], v[140:143], v[214:217], v[124:127]
	v_mfma_f32_16x16x32_bf16 v[120:123], v[170:173], v[214:217], v[120:123]
	v_mfma_f32_16x16x32_bf16 v[116:119], v[178:181], v[214:217], v[116:119]
	v_mfma_f32_16x16x32_bf16 v[112:115], v[186:189], v[214:217], v[112:115]
	v_mfma_f32_16x16x32_bf16 v[108:111], v[140:143], v[222:225], v[108:111]
	v_mfma_f32_16x16x32_bf16 v[104:107], v[170:173], v[222:225], v[104:107]
	v_mfma_f32_16x16x32_bf16 v[100:103], v[178:181], v[222:225], v[100:103]
	v_mfma_f32_16x16x32_bf16 v[96:99], v[186:189], v[222:225], v[96:99]
	v_mfma_f32_16x16x32_bf16 v[92:95], v[140:143], v[230:233], v[92:95]
	v_mfma_f32_16x16x32_bf16 v[88:91], v[170:173], v[230:233], v[88:91]
	v_mfma_f32_16x16x32_bf16 v[84:87], v[178:181], v[230:233], v[84:87]
	v_mfma_f32_16x16x32_bf16 v[80:83], v[186:189], v[230:233], v[80:83]
	v_mfma_f32_16x16x32_bf16 v[76:79], v[140:143], v[238:241], v[76:79]
	v_mfma_f32_16x16x32_bf16 v[72:75], v[170:173], v[238:241], v[72:75]
	v_mfma_f32_16x16x32_bf16 v[68:71], v[178:181], v[238:241], v[68:71]
	v_mfma_f32_16x16x32_bf16 v[64:67], v[186:189], v[238:241], v[64:67]
	v_mfma_f32_16x16x32_bf16 v[124:127], v[166:169], v[218:221], v[124:127]
	v_mfma_f32_16x16x32_bf16 v[120:123], v[174:177], v[218:221], v[120:123]
	v_mfma_f32_16x16x32_bf16 v[116:119], v[182:185], v[218:221], v[116:119]
	v_mfma_f32_16x16x32_bf16 v[112:115], v[210:213], v[218:221], v[112:115]
	v_mfma_f32_16x16x32_bf16 v[108:111], v[166:169], v[226:229], v[108:111]
	v_mfma_f32_16x16x32_bf16 v[104:107], v[174:177], v[226:229], v[104:107]
	v_mfma_f32_16x16x32_bf16 v[100:103], v[182:185], v[226:229], v[100:103]
	v_mfma_f32_16x16x32_bf16 v[96:99], v[210:213], v[226:229], v[96:99]
	v_mfma_f32_16x16x32_bf16 v[92:95], v[166:169], v[234:237], v[92:95]
	v_mfma_f32_16x16x32_bf16 v[88:91], v[174:177], v[234:237], v[88:91]
	v_mfma_f32_16x16x32_bf16 v[84:87], v[182:185], v[234:237], v[84:87]
	v_mfma_f32_16x16x32_bf16 v[80:83], v[210:213], v[234:237], v[80:83]
	v_mfma_f32_16x16x32_bf16 v[76:79], v[166:169], v[242:245], v[76:79]
	v_mfma_f32_16x16x32_bf16 v[72:75], v[174:177], v[242:245], v[72:75]
	v_mfma_f32_16x16x32_bf16 v[68:71], v[182:185], v[242:245], v[68:71]
	v_mfma_f32_16x16x32_bf16 v[64:67], v[210:213], v[242:245], v[64:67]
	s_setprio 0
	s_barrier
	s_mov_b32 m0, s43
	s_add_u32 s2, s2, 0x40080
	s_addc_u32 s3, s3, 0
	ds_read_b128 v[214:217], v163 offset:49152
	ds_read_b128 v[218:221], v163 offset:50176
	ds_read_b128 v[222:225], v163 offset:51200
	ds_read_b128 v[226:229], v163 offset:52224
	ds_read_b128 v[230:233], v163 offset:53248
	ds_read_b128 v[234:237], v163 offset:54272
	ds_read_b128 v[238:241], v163 offset:55296
	ds_read_b128 v[242:245], v163 offset:56320
	s_add_u32 s98, s2, 0xfffc0000
	s_addc_u32 s99, s3, -1
	global_load_lds_dwordx4 v132, s[98:99]
	s_mov_b32 m0, s44
	s_nop 0
	global_load_lds_dwordx4 v128, s[98:99]
	s_mov_b32 m0, s48
	s_nop 0
	global_load_lds_dwordx4 v132, s[2:3]
	s_mov_b32 m0, s49
	s_nop 0
	global_load_lds_dwordx4 v128, s[2:3]
	s_mov_b32 m0, s45
	s_nop 0
	s_add_u32 s100, s4, 0xfffc0080
	s_addc_u32 s101, s5, -1
	global_load_lds_dwordx4 v134, s[100:101]
	s_mov_b32 m0, s47
	s_nop 0
	global_load_lds_dwordx4 v130, s[100:101]
	s_waitcnt vmcnt(8)
	s_waitcnt lgkmcnt(0)
	s_barrier
	s_setprio 1
	v_mfma_f32_16x16x32_bf16 v[60:63], v[140:143], v[214:217], v[60:63]
	v_mfma_f32_16x16x32_bf16 v[56:59], v[170:173], v[214:217], v[56:59]
	v_mfma_f32_16x16x32_bf16 v[52:55], v[178:181], v[214:217], v[52:55]
	v_mfma_f32_16x16x32_bf16 v[48:51], v[186:189], v[214:217], v[48:51]
	v_mfma_f32_16x16x32_bf16 v[44:47], v[140:143], v[222:225], v[44:47]
	v_mfma_f32_16x16x32_bf16 v[40:43], v[170:173], v[222:225], v[40:43]
	v_mfma_f32_16x16x32_bf16 v[36:39], v[178:181], v[222:225], v[36:39]
	v_mfma_f32_16x16x32_bf16 v[32:35], v[186:189], v[222:225], v[32:35]
	v_mfma_f32_16x16x32_bf16 v[28:31], v[140:143], v[230:233], v[28:31]
	v_mfma_f32_16x16x32_bf16 v[24:27], v[170:173], v[230:233], v[24:27]
	v_mfma_f32_16x16x32_bf16 v[20:23], v[178:181], v[230:233], v[20:23]
	v_mfma_f32_16x16x32_bf16 v[16:19], v[186:189], v[230:233], v[16:19]
	v_mfma_f32_16x16x32_bf16 v[12:15], v[140:143], v[238:241], v[12:15]
	v_mfma_f32_16x16x32_bf16 v[8:11], v[170:173], v[238:241], v[8:11]
	v_mfma_f32_16x16x32_bf16 v[4:7], v[178:181], v[238:241], v[4:7]
	v_mfma_f32_16x16x32_bf16 v[0:3], v[186:189], v[238:241], v[0:3]
	v_mfma_f32_16x16x32_bf16 v[60:63], v[166:169], v[218:221], v[60:63]
	v_mfma_f32_16x16x32_bf16 v[56:59], v[174:177], v[218:221], v[56:59]
	v_mfma_f32_16x16x32_bf16 v[52:55], v[182:185], v[218:221], v[52:55]
	v_mfma_f32_16x16x32_bf16 v[48:51], v[210:213], v[218:221], v[48:51]
	v_mfma_f32_16x16x32_bf16 v[44:47], v[166:169], v[226:229], v[44:47]
	v_mfma_f32_16x16x32_bf16 v[40:43], v[174:177], v[226:229], v[40:43]
	v_mfma_f32_16x16x32_bf16 v[36:39], v[182:185], v[226:229], v[36:39]
	v_mfma_f32_16x16x32_bf16 v[32:35], v[210:213], v[226:229], v[32:35]
	v_mfma_f32_16x16x32_bf16 v[28:31], v[166:169], v[234:237], v[28:31]
	v_mfma_f32_16x16x32_bf16 v[24:27], v[174:177], v[234:237], v[24:27]
	v_mfma_f32_16x16x32_bf16 v[20:23], v[182:185], v[234:237], v[20:23]
	v_mfma_f32_16x16x32_bf16 v[16:19], v[210:213], v[234:237], v[16:19]
	v_mfma_f32_16x16x32_bf16 v[12:15], v[166:169], v[242:245], v[12:15]
	v_mfma_f32_16x16x32_bf16 v[8:11], v[174:177], v[242:245], v[8:11]
	v_mfma_f32_16x16x32_bf16 v[4:7], v[182:185], v[242:245], v[4:7]
	v_mfma_f32_16x16x32_bf16 v[0:3], v[210:213], v[242:245], v[0:3]
	s_setprio 0
	s_barrier
	s_add_i32 s55, s55, 2
	s_add_u32 s0, s0, 0x100
	s_addc_u32 s1, s1, 0
	s_add_u32 s53, s53, 0x100
	s_addc_u32 s54, s54, 0
	s_cmp_gt_u32 s55, 13
; #define PG8_STAGE(bufoff, gbase, voff) do { _Pragma("unroll") for (int _i = 0; _i < 2; ++_i) \
;         __builtin_amdgcn_global_load_lds((const unsigned*)((const char*)(gbase) + (voff)[_i]), (PG8_LAS unsigned*)(lds + (bufoff) + ldsw + _i * 8192), 16, 0, 0); } while (0)
; #define PG8_LDA(dst, b, h) do { _Pragma("unroll") for (int m = 0; m < 4; ++m) _Pragma("unroll") for (int k = 0; k < 2; ++k) dst[m][k] = *(const PG8_LAS bf16x8*)(lds + PG8_SA(b, h) + aoff + m * 2048 + k * 1024); } while (0)
; #define PG8_LDB(dst, b, h) do { _Pragma("unroll") for (int n = 0; n < 2; ++n) _Pragma("unroll") for (int k = 0; k < 2; ++k) dst[n][k] = *(const PG8_LAS bf16x8*)(lds + PG8_SB(b, h) + boff + n * 2048 + k * 1024); } while (0)
; #define PG8_MMA(ai, bj, At, Bt) do { __builtin_amdgcn_s_setprio(1); _Pragma("unroll") for (int m = 0; m < 4; ++m) _Pragma("unroll") for (int n = 0; n < 2; ++n) _Pragma("unroll") for (int k = 0; k < 2; ++k) \
;         acc[ai][bj][m][n] = __builtin_amdgcn_mfma_f32_16x16x32_bf16(Bt[n][k], At[m][k], acc[ai][bj][m][n], 0, 0, 0); __builtin_amdgcn_s_setprio(0); } while (0)
; #define PG8_WAIT_V(n) asm volatile("s_waitcnt vmcnt(" #n ")" ::: "memory")
; #define PG8_WAIT_L(n) asm volatile("s_waitcnt lgkmcnt(" #n ")" ::: "memory")
; template <class Epi, class Sched, bool ALIGN_EPI = false, bool SP2 = false>
; __device__ __forceinline__ void gemm_phase(PG8_LAS unsigned char* lds, const Gemm g, const Sched& S, const Epi& E) {
;     ...
;             const bool last = (t == nt - 2);
;             const char* a1 = cA + (size_t)(t + 1) * kstep;
;             const char* a2 = last ? nA : cA + (size_t)(t + 2) * kstep; const char* b2 = last ? nB : cB + (size_t)(t + 2) * kstep;
;             const char* a3 = a2 + kstep; const char* b3 = b2 + kstep;
;             if (last && has_next) S.a_ready(nxt);
;             if constexpr (SP2) {
;             PG8_LDB(B0, 0, 0); PG8_LDB(B1, 0, 1); PG8_SCHED; PG8_LDA(At, 0, 0); PG8_STAGE(PG8_SA(1, 1), a1 + hstep, voffA);
;             PG8_WAIT_V(8); PG8_WAIT_L(0); PG8_BAR; PG8_MMA(0, 0, At, B0); PG8_MMA(0, 1, At, B1); PG8_BAR; PG8_SCHED;
;             PG8_LDA(At, 0, 1); PG8_STAGE(PG8_SB(0, 0), b2, voffB); PG8_STAGE(PG8_SB(0, 1), b2 + hstep, voffB); PG8_STAGE(PG8_SA(0, 0), a2, voffA);
;             PG8_WAIT_V(8); PG8_WAIT_L(0); PG8_BAR; PG8_MMA(1, 0, At, B0); PG8_MMA(1, 1, At, B1); PG8_BAR; PG8_SCHED;
.LBB0_1042:
	ds_read_b128 v[140:143], v254
	ds_read_b128 v[166:169], v254 offset:1024
	ds_read_b128 v[170:173], v254 offset:2048
	ds_read_b128 v[174:177], v254 offset:3072
	ds_read_b128 v[178:181], v254 offset:16384
	ds_read_b128 v[182:185], v254 offset:17408
	ds_read_b128 v[186:189], v254 offset:18432
	ds_read_b128 v[210:213], v254 offset:19456
	s_add_u32 s2, s0, 0xfffc0080
	s_addc_u32 s3, s1, -1
	s_cmp_eq_u32 s55, 12
	s_cselect_b32 s5, s23, s3
	s_cselect_b32 s4, s51, s2
	s_cselect_b32 s3, s21, s54
	s_cselect_b32 s2, s52, s53
	s_add_i32 m0, s31, 0xc000
	ds_read_b128 v[214:217], v163
	ds_read_b128 v[218:221], v163 offset:1024
	ds_read_b128 v[222:225], v163 offset:2048
	ds_read_b128 v[226:229], v163 offset:3072
	ds_read_b128 v[230:233], v163 offset:4096
	ds_read_b128 v[234:237], v163 offset:5120
	ds_read_b128 v[238:241], v163 offset:6144
	ds_read_b128 v[242:245], v163 offset:7168
	global_load_lds_dwordx4 v136, s[0:1]
	s_add_i32 m0, s31, 0xe000
	s_nop 0
	global_load_lds_dwordx4 v138, s[0:1]
	s_waitcnt vmcnt(8)
	s_waitcnt lgkmcnt(0)
	s_barrier
	s_setprio 1
	v_mfma_f32_16x16x32_bf16 v[124:127], v[140:143], v[214:217], v[124:127]
	v_mfma_f32_16x16x32_bf16 v[120:123], v[170:173], v[214:217], v[120:123]
	v_mfma_f32_16x16x32_bf16 v[116:119], v[178:181], v[214:217], v[116:119]
	v_mfma_f32_16x16x32_bf16 v[112:115], v[186:189], v[214:217], v[112:115]
	v_mfma_f32_16x16x32_bf16 v[108:111], v[140:143], v[222:225], v[108:111]
	v_mfma_f32_16x16x32_bf16 v[104:107], v[170:173], v[222:225], v[104:107]
	v_mfma_f32_16x16x32_bf16 v[100:103], v[178:181], v[222:225], v[100:103]
	v_mfma_f32_16x16x32_bf16 v[96:99], v[186:189], v[222:225], v[96:99]
	v_mfma_f32_16x16x32_bf16 v[92:95], v[140:143], v[230:233], v[92:95]
	v_mfma_f32_16x16x32_bf16 v[88:91], v[170:173], v[230:233], v[88:91]
	v_mfma_f32_16x16x32_bf16 v[84:87], v[178:181], v[230:233], v[84:87]
	v_mfma_f32_16x16x32_bf16 v[80:83], v[186:189], v[230:233], v[80:83]
	v_mfma_f32_16x16x32_bf16 v[76:79], v[140:143], v[238:241], v[76:79]
	v_mfma_f32_16x16x32_bf16 v[72:75], v[170:173], v[238:241], v[72:75]
	v_mfma_f32_16x16x32_bf16 v[68:71], v[178:181], v[238:241], v[68:71]
	v_mfma_f32_16x16x32_bf16 v[64:67], v[186:189], v[238:241], v[64:67]
	v_mfma_f32_16x16x32_bf16 v[124:127], v[166:169], v[218:221], v[124:127]
	v_mfma_f32_16x16x32_bf16 v[120:123], v[174:177], v[218:221], v[120:123]
	v_mfma_f32_16x16x32_bf16 v[116:119], v[182:185], v[218:221], v[116:119]
	v_mfma_f32_16x16x32_bf16 v[112:115], v[210:213], v[218:221], v[112:115]
	v_mfma_f32_16x16x32_bf16 v[108:111], v[166:169], v[226:229], v[108:111]
	v_mfma_f32_16x16x32_bf16 v[104:107], v[174:177], v[226:229], v[104:107]
	v_mfma_f32_16x16x32_bf16 v[100:103], v[182:185], v[226:229], v[100:103]
	v_mfma_f32_16x16x32_bf16 v[96:99], v[210:213], v[226:229], v[96:99]
	v_mfma_f32_16x16x32_bf16 v[92:95], v[166:169], v[234:237], v[92:95]
	v_mfma_f32_16x16x32_bf16 v[88:91], v[174:177], v[234:237], v[88:91]
	v_mfma_f32_16x16x32_bf16 v[84:87], v[182:185], v[234:237], v[84:87]
	v_mfma_f32_16x16x32_bf16 v[80:83], v[210:213], v[234:237], v[80:83]
	v_mfma_f32_16x16x32_bf16 v[76:79], v[166:169], v[242:245], v[76:79]
	v_mfma_f32_16x16x32_bf16 v[72:75], v[174:177], v[242:245], v[72:75]
	v_mfma_f32_16x16x32_bf16 v[68:71], v[182:185], v[242:245], v[68:71]
	v_mfma_f32_16x16x32_bf16 v[64:67], v[210:213], v[242:245], v[64:67]
	s_setprio 0
	s_barrier
	s_mov_b32 m0, s33
	s_add_u32 s56, s2, 0x40000
	s_addc_u32 s57, s3, 0
	ds_read_b128 v[214:217], v163 offset:16384
	ds_read_b128 v[218:221], v163 offset:17408
	ds_read_b128 v[222:225], v163 offset:18432
	ds_read_b128 v[226:229], v163 offset:19456
	ds_read_b128 v[230:233], v163 offset:20480
	ds_read_b128 v[234:237], v163 offset:21504
	ds_read_b128 v[238:241], v163 offset:22528
	ds_read_b128 v[242:245], v163 offset:23552
	global_load_lds_dwordx4 v132, s[2:3]
	s_mov_b32 m0, s34
	s_nop 0
	global_load_lds_dwordx4 v128, s[2:3]
	s_mov_b32 m0, s35
	s_nop 0
	global_load_lds_dwordx4 v132, s[56:57]
	s_mov_b32 m0, s36
	s_nop 0
	global_load_lds_dwordx4 v128, s[56:57]
	s_mov_b32 m0, s31
	s_nop 0
	global_load_lds_dwordx4 v134, s[4:5]
	s_mov_b32 m0, s37
	s_nop 0
	global_load_lds_dwordx4 v130, s[4:5]
	s_waitcnt vmcnt(8)
	s_waitcnt lgkmcnt(0)
	s_barrier
	s_setprio 1
	v_mfma_f32_16x16x32_bf16 v[60:63], v[140:143], v[214:217], v[60:63]
	v_mfma_f32_16x16x32_bf16 v[56:59], v[170:173], v[214:217], v[56:59]
	v_mfma_f32_16x16x32_bf16 v[52:55], v[178:181], v[214:217], v[52:55]
	v_mfma_f32_16x16x32_bf16 v[48:51], v[186:189], v[214:217], v[48:51]
	v_mfma_f32_16x16x32_bf16 v[44:47], v[140:143], v[222:225], v[44:47]
	v_mfma_f32_16x16x32_bf16 v[40:43], v[170:173], v[222:225], v[40:43]
	v_mfma_f32_16x16x32_bf16 v[36:39], v[178:181], v[222:225], v[36:39]
	v_mfma_f32_16x16x32_bf16 v[32:35], v[186:189], v[222:225], v[32:35]
	v_mfma_f32_16x16x32_bf16 v[28:31], v[140:143], v[230:233], v[28:31]
	v_mfma_f32_16x16x32_bf16 v[24:27], v[170:173], v[230:233], v[24:27]
	v_mfma_f32_16x16x32_bf16 v[20:23], v[178:181], v[230:233], v[20:23]
	v_mfma_f32_16x16x32_bf16 v[16:19], v[186:189], v[230:233], v[16:19]
	v_mfma_f32_16x16x32_bf16 v[12:15], v[140:143], v[238:241], v[12:15]
	v_mfma_f32_16x16x32_bf16 v[8:11], v[170:173], v[238:241], v[8:11]
	v_mfma_f32_16x16x32_bf16 v[4:7], v[178:181], v[238:241], v[4:7]
	v_mfma_f32_16x16x32_bf16 v[0:3], v[186:189], v[238:241], v[0:3]
	v_mfma_f32_16x16x32_bf16 v[60:63], v[166:169], v[218:221], v[60:63]
	v_mfma_f32_16x16x32_bf16 v[56:59], v[174:177], v[218:221], v[56:59]
	v_mfma_f32_16x16x32_bf16 v[52:55], v[182:185], v[218:221], v[52:55]
	v_mfma_f32_16x16x32_bf16 v[48:51], v[210:213], v[218:221], v[48:51]
	v_mfma_f32_16x16x32_bf16 v[44:47], v[166:169], v[226:229], v[44:47]
	v_mfma_f32_16x16x32_bf16 v[40:43], v[174:177], v[226:229], v[40:43]
	v_mfma_f32_16x16x32_bf16 v[36:39], v[182:185], v[226:229], v[36:39]
	v_mfma_f32_16x16x32_bf16 v[32:35], v[210:213], v[226:229], v[32:35]
	v_mfma_f32_16x16x32_bf16 v[28:31], v[166:169], v[234:237], v[28:31]
	v_mfma_f32_16x16x32_bf16 v[24:27], v[174:177], v[234:237], v[24:27]
	v_mfma_f32_16x16x32_bf16 v[20:23], v[182:185], v[234:237], v[20:23]
	v_mfma_f32_16x16x32_bf16 v[16:19], v[210:213], v[234:237], v[16:19]
	v_mfma_f32_16x16x32_bf16 v[12:15], v[166:169], v[242:245], v[12:15]
	v_mfma_f32_16x16x32_bf16 v[8:11], v[174:177], v[242:245], v[8:11]
	v_mfma_f32_16x16x32_bf16 v[4:7], v[182:185], v[242:245], v[4:7]
	v_mfma_f32_16x16x32_bf16 v[0:3], v[210:213], v[242:245], v[0:3]
	s_setprio 0
	s_barrier
; #define PG8_STAGE(bufoff, gbase, voff) do { _Pragma("unroll") for (int _i = 0; _i < 2; ++_i) \
;         __builtin_amdgcn_global_load_lds((const unsigned*)((const char*)(gbase) + (voff)[_i]), (PG8_LAS unsigned*)(lds + (bufoff) + ldsw + _i * 8192), 16, 0, 0); } while (0)
; #define PG8_LDA(dst, b, h) do { _Pragma("unroll") for (int m = 0; m < 4; ++m) _Pragma("unroll") for (int k = 0; k < 2; ++k) dst[m][k] = *(const PG8_LAS bf16x8*)(lds + PG8_SA(b, h) + aoff + m * 2048 + k * 1024); } while (0)
; #define PG8_LDB(dst, b, h) do { _Pragma("unroll") for (int n = 0; n < 2; ++n) _Pragma("unroll") for (int k = 0; k < 2; ++k) dst[n][k] = *(const PG8_LAS bf16x8*)(lds + PG8_SB(b, h) + boff + n * 2048 + k * 1024); } while (0)
; #define PG8_MMA(ai, bj, At, Bt) do { __builtin_amdgcn_s_setprio(1); _Pragma("unroll") for (int m = 0; m < 4; ++m) _Pragma("unroll") for (int n = 0; n < 2; ++n) _Pragma("unroll") for (int k = 0; k < 2; ++k) \
;         acc[ai][bj][m][n] = __builtin_amdgcn_mfma_f32_16x16x32_bf16(Bt[n][k], At[m][k], acc[ai][bj][m][n], 0, 0, 0); __builtin_amdgcn_s_setprio(0); } while (0)
; #define PG8_WAIT_V(n) asm volatile("s_waitcnt vmcnt(" #n ")" ::: "memory")
; #define PG8_WAIT_L(n) asm volatile("s_waitcnt lgkmcnt(" #n ")" ::: "memory")
; #define PG8_BAR __builtin_amdgcn_s_barrier()
; #define PG8_SCHED __builtin_amdgcn_sched_barrier(0)
; template <class Epi, class Sched, bool ALIGN_EPI = false, bool SP2 = false>
; __device__ __forceinline__ void gemm_phase(PG8_LAS unsigned char* lds, const Gemm g, const Sched& S, const Epi& E) {
;     ...
;             PG8_LDB(B0, 1, 0); PG8_LDB(B1, 1, 1); PG8_SCHED; PG8_LDA(At, 1, 0); PG8_STAGE(PG8_SA(0, 1), a2 + hstep, voffA);
;             PG8_WAIT_V(8); PG8_WAIT_L(0); PG8_BAR; PG8_MMA(0, 0, At, B0); PG8_MMA(0, 1, At, B1); PG8_BAR; PG8_SCHED;
;             PG8_LDA(At, 1, 1); PG8_STAGE(PG8_SB(1, 0), b3, voffB); PG8_STAGE(PG8_SB(1, 1), b3 + hstep, voffB); PG8_STAGE(PG8_SA(1, 0), a3, voffA);
;             PG8_WAIT_V(8); PG8_WAIT_L(0); PG8_BAR; PG8_MMA(1, 0, At, B0); PG8_MMA(1, 1, At, B1); PG8_BAR; PG8_SCHED;
;     ...
;         if constexpr (ALIGN_EPI) { if (wr == 0) PG8_BAR; }
	ds_read_b128 v[140:143], v254 offset:32768
	ds_read_b128 v[166:169], v254 offset:33792
	ds_read_b128 v[170:173], v254 offset:34816
	ds_read_b128 v[174:177], v254 offset:35840
	ds_read_b128 v[178:181], v254 offset:49152
	ds_read_b128 v[182:185], v254 offset:50176
	ds_read_b128 v[186:189], v254 offset:51200
	ds_read_b128 v[210:213], v254 offset:52224
	s_add_u32 s4, s4, 0x40000
	s_addc_u32 s5, s5, 0
	s_mov_b32 m0, s38
	ds_read_b128 v[214:217], v163 offset:32768
	ds_read_b128 v[218:221], v163 offset:33792
	ds_read_b128 v[222:225], v163 offset:34816
	ds_read_b128 v[226:229], v163 offset:35840
	ds_read_b128 v[230:233], v163 offset:36864
	ds_read_b128 v[234:237], v163 offset:37888
	ds_read_b128 v[238:241], v163 offset:38912
	ds_read_b128 v[242:245], v163 offset:39936
	global_load_lds_dwordx4 v134, s[4:5]
	s_mov_b32 m0, s39
	s_nop 0
	global_load_lds_dwordx4 v130, s[4:5]
	s_waitcnt vmcnt(8)
	s_waitcnt lgkmcnt(0)
	s_barrier
	s_setprio 1
	v_mfma_f32_16x16x32_bf16 v[124:127], v[140:143], v[214:217], v[124:127]
	v_mfma_f32_16x16x32_bf16 v[120:123], v[170:173], v[214:217], v[120:123]
	v_mfma_f32_16x16x32_bf16 v[116:119], v[178:181], v[214:217], v[116:119]
	v_mfma_f32_16x16x32_bf16 v[112:115], v[186:189], v[214:217], v[112:115]
	v_mfma_f32_16x16x32_bf16 v[108:111], v[140:143], v[222:225], v[108:111]
	v_mfma_f32_16x16x32_bf16 v[104:107], v[170:173], v[222:225], v[104:107]
	v_mfma_f32_16x16x32_bf16 v[100:103], v[178:181], v[222:225], v[100:103]
	v_mfma_f32_16x16x32_bf16 v[96:99], v[186:189], v[222:225], v[96:99]
	v_mfma_f32_16x16x32_bf16 v[92:95], v[140:143], v[230:233], v[92:95]
	v_mfma_f32_16x16x32_bf16 v[88:91], v[170:173], v[230:233], v[88:91]
	v_mfma_f32_16x16x32_bf16 v[84:87], v[178:181], v[230:233], v[84:87]
	v_mfma_f32_16x16x32_bf16 v[80:83], v[186:189], v[230:233], v[80:83]
	v_mfma_f32_16x16x32_bf16 v[76:79], v[140:143], v[238:241], v[76:79]
	v_mfma_f32_16x16x32_bf16 v[72:75], v[170:173], v[238:241], v[72:75]
	v_mfma_f32_16x16x32_bf16 v[68:71], v[178:181], v[238:241], v[68:71]
	v_mfma_f32_16x16x32_bf16 v[64:67], v[186:189], v[238:241], v[64:67]
	v_mfma_f32_16x16x32_bf16 v[124:127], v[166:169], v[218:221], v[124:127]
	v_mfma_f32_16x16x32_bf16 v[120:123], v[174:177], v[218:221], v[120:123]
	v_mfma_f32_16x16x32_bf16 v[116:119], v[182:185], v[218:221], v[116:119]
	v_mfma_f32_16x16x32_bf16 v[112:115], v[210:213], v[218:221], v[112:115]
	v_mfma_f32_16x16x32_bf16 v[108:111], v[166:169], v[226:229], v[108:111]
	v_mfma_f32_16x16x32_bf16 v[104:107], v[174:177], v[226:229], v[104:107]
	v_mfma_f32_16x16x32_bf16 v[100:103], v[182:185], v[226:229], v[100:103]
	v_mfma_f32_16x16x32_bf16 v[96:99], v[210:213], v[226:229], v[96:99]
	v_mfma_f32_16x16x32_bf16 v[92:95], v[166:169], v[234:237], v[92:95]
	v_mfma_f32_16x16x32_bf16 v[88:91], v[174:177], v[234:237], v[88:91]
	v_mfma_f32_16x16x32_bf16 v[84:87], v[182:185], v[234:237], v[84:87]
	v_mfma_f32_16x16x32_bf16 v[80:83], v[210:213], v[234:237], v[80:83]
	v_mfma_f32_16x16x32_bf16 v[76:79], v[166:169], v[242:245], v[76:79]
	v_mfma_f32_16x16x32_bf16 v[72:75], v[174:177], v[242:245], v[72:75]
	v_mfma_f32_16x16x32_bf16 v[68:71], v[182:185], v[242:245], v[68:71]
	v_mfma_f32_16x16x32_bf16 v[64:67], v[210:213], v[242:245], v[64:67]
	s_setprio 0
	s_barrier
	s_mov_b32 m0, s43
	s_add_u32 s2, s2, 0x40080
	s_addc_u32 s3, s3, 0
	ds_read_b128 v[214:217], v163 offset:49152
	ds_read_b128 v[218:221], v163 offset:50176
	ds_read_b128 v[222:225], v163 offset:51200
	ds_read_b128 v[226:229], v163 offset:52224
	ds_read_b128 v[230:233], v163 offset:53248
	ds_read_b128 v[234:237], v163 offset:54272
	ds_read_b128 v[238:241], v163 offset:55296
	ds_read_b128 v[242:245], v163 offset:56320
	s_add_u32 s98, s2, 0xfffc0000
	s_addc_u32 s99, s3, -1
	global_load_lds_dwordx4 v132, s[98:99]
	s_mov_b32 m0, s44
	s_nop 0
	global_load_lds_dwordx4 v128, s[98:99]
	s_mov_b32 m0, s48
	s_nop 0
	global_load_lds_dwordx4 v132, s[2:3]
	s_mov_b32 m0, s49
	s_nop 0
	global_load_lds_dwordx4 v128, s[2:3]
	s_mov_b32 m0, s45
	s_nop 0
	s_add_u32 s100, s4, 0xfffc0080
	s_addc_u32 s101, s5, -1
	global_load_lds_dwordx4 v134, s[100:101]
	s_mov_b32 m0, s47
	s_nop 0
	global_load_lds_dwordx4 v130, s[100:101]
	s_waitcnt vmcnt(8)
	s_waitcnt lgkmcnt(0)
	s_barrier
	s_setprio 1
	v_mfma_f32_16x16x32_bf16 v[60:63], v[140:143], v[214:217], v[60:63]
	v_mfma_f32_16x16x32_bf16 v[56:59], v[170:173], v[214:217], v[56:59]
	v_mfma_f32_16x16x32_bf16 v[52:55], v[178:181], v[214:217], v[52:55]
	v_mfma_f32_16x16x32_bf16 v[48:51], v[186:189], v[214:217], v[48:51]
	v_mfma_f32_16x16x32_bf16 v[44:47], v[140:143], v[222:225], v[44:47]
	v_mfma_f32_16x16x32_bf16 v[40:43], v[170:173], v[222:225], v[40:43]
	v_mfma_f32_16x16x32_bf16 v[36:39], v[178:181], v[222:225], v[36:39]
	v_mfma_f32_16x16x32_bf16 v[32:35], v[186:189], v[222:225], v[32:35]
	v_mfma_f32_16x16x32_bf16 v[28:31], v[140:143], v[230:233], v[28:31]
	v_mfma_f32_16x16x32_bf16 v[24:27], v[170:173], v[230:233], v[24:27]
	v_mfma_f32_16x16x32_bf16 v[20:23], v[178:181], v[230:233], v[20:23]
	v_mfma_f32_16x16x32_bf16 v[16:19], v[186:189], v[230:233], v[16:19]
	v_mfma_f32_16x16x32_bf16 v[12:15], v[140:143], v[238:241], v[12:15]
	v_mfma_f32_16x16x32_bf16 v[8:11], v[170:173], v[238:241], v[8:11]
	v_mfma_f32_16x16x32_bf16 v[4:7], v[178:181], v[238:241], v[4:7]
	v_mfma_f32_16x16x32_bf16 v[0:3], v[186:189], v[238:241], v[0:3]
	v_mfma_f32_16x16x32_bf16 v[60:63], v[166:169], v[218:221], v[60:63]
	v_mfma_f32_16x16x32_bf16 v[56:59], v[174:177], v[218:221], v[56:59]
	v_mfma_f32_16x16x32_bf16 v[52:55], v[182:185], v[218:221], v[52:55]
	v_mfma_f32_16x16x32_bf16 v[48:51], v[210:213], v[218:221], v[48:51]
	v_mfma_f32_16x16x32_bf16 v[44:47], v[166:169], v[226:229], v[44:47]
	v_mfma_f32_16x16x32_bf16 v[40:43], v[174:177], v[226:229], v[40:43]
	v_mfma_f32_16x16x32_bf16 v[36:39], v[182:185], v[226:229], v[36:39]
	v_mfma_f32_16x16x32_bf16 v[32:35], v[210:213], v[226:229], v[32:35]
	v_mfma_f32_16x16x32_bf16 v[28:31], v[166:169], v[234:237], v[28:31]
	v_mfma_f32_16x16x32_bf16 v[24:27], v[174:177], v[234:237], v[24:27]
	v_mfma_f32_16x16x32_bf16 v[20:23], v[182:185], v[234:237], v[20:23]
	v_mfma_f32_16x16x32_bf16 v[16:19], v[210:213], v[234:237], v[16:19]
	v_mfma_f32_16x16x32_bf16 v[12:15], v[166:169], v[242:245], v[12:15]
	v_mfma_f32_16x16x32_bf16 v[8:11], v[174:177], v[242:245], v[8:11]
	v_mfma_f32_16x16x32_bf16 v[4:7], v[182:185], v[242:245], v[4:7]
	v_mfma_f32_16x16x32_bf16 v[0:3], v[210:213], v[242:245], v[0:3]
	s_setprio 0
	s_barrier
	s_add_i32 s55, s55, 2
	s_add_u32 s0, s0, 0x100
	s_addc_u32 s1, s1, 0
	s_add_u32 s53, s53, 0x100
	s_addc_u32 s54, s54, 0
	s_cmp_gt_u32 s55, 13
	s_cbranch_scc0 .LBB0_1042
	s_and_b64 vcc, exec, s[18:19]
	s_cbranch_vccz .LBB0_1045
	s_barrier
